# v59 + K-loop DMA address arithmetic: +kstep addresses via offset:128 with M0-128, single-use addresses via SGPR-base DMA form (8-10 fewer 64-bit VALU adds per body)
# speedup vs baseline: 1.0130x; 1.0086x over previous
; #define PG8_STAGE(bufoff, gbase, voff) do { _Pragma("unroll") for (int _i = 0; _i < 2; ++_i) \
;         __builtin_amdgcn_global_load_lds((const unsigned*)((const char*)(gbase) + (voff)[_i]), (PG8_LAS unsigned*)(lds + (bufoff) + ldsw + _i * 8192), 16, 0, 0); } while (0)
; #define PG8_LDA(dst, b, h) do { _Pragma("unroll") for (int m = 0; m < 4; ++m) _Pragma("unroll") for (int k = 0; k < 2; ++k) dst[m][k] = *(const PG8_LAS bf16x8*)(lds + PG8_SA(b, h) + aoff + m * 2048 + k * 1024); } while (0)
; #define PG8_LDB(dst, b, h) do { _Pragma("unroll") for (int n = 0; n < 2; ++n) _Pragma("unroll") for (int k = 0; k < 2; ++k) dst[n][k] = *(const PG8_LAS bf16x8*)(lds + PG8_SB(b, h) + boff + n * 2048 + k * 1024); } while (0)
; #define PG8_MMA(ai, bj, At, Bt) do { __builtin_amdgcn_s_setprio(1); _Pragma("unroll") for (int m = 0; m < 4; ++m) _Pragma("unroll") for (int n = 0; n < 2; ++n) _Pragma("unroll") for (int k = 0; k < 2; ++k) \
;         acc[ai][bj][m][n] = __builtin_amdgcn_mfma_f32_16x16x32_bf16(Bt[n][k], At[m][k], acc[ai][bj][m][n], 0, 0, 0); __builtin_amdgcn_s_setprio(0); } while (0)
; #define PG8_WAIT_V(n) asm volatile("s_waitcnt vmcnt(" #n ")" ::: "memory")
; #define PG8_WAIT_L(n) asm volatile("s_waitcnt lgkmcnt(" #n ")" ::: "memory")
; #define PG8_BAR __builtin_amdgcn_s_barrier()
; template <class Epi, class Sched, bool ALIGN_EPI = false, bool SP2 = false>
; __device__ __forceinline__ void gemm_phase(PG8_LAS unsigned char* lds, const Gemm g, const Sched& S, const Epi& E, const int wv) {
;     ...
;         for (int t = 0; t < nt; t += 2) {
;             const bool last = (t == nt - 2);
;             const char* a1 = cA + (size_t)(t + 1) * kstep;
;             const char* a2 = last ? nA : cA + (size_t)(t + 2) * kstep; const char* b2 = last ? nB : cB + (size_t)(t + 2) * kstep;
;             const char* a3 = a2 + kstep; const char* b3 = b2 + kstep;
;             if (last && has_next) S.a_ready(nxt);
;             if constexpr (SP2) {
;             PG8_LDB(B0, 0, 0); PG8_LDB(B1, 0, 1); PG8_SCHED; PG8_LDA(At, 0, 0); PG8_STAGE(PG8_SA(1, 1), a1 + hstepA, voffA);
;             PG8_WAIT_V(8); PG8_WAIT_L(0); PG8_BAR; PG8_MMA(0, 0, At, B0); PG8_MMA(0, 1, At, B1); PG8_BAR; PG8_SCHED;
;             PG8_LDA(At, 0, 1); PG8_STAGE(PG8_SB(0, 0), b2, voffB); PG8_STAGE(PG8_SB(0, 1), b2 + hstepB, voffB); PG8_STAGE(PG8_SA(0, 0), a2, voffA);
.LBB0_176:
	s_add_i32 s67, s14, 2
	s_add_u32 s68, s12, 0xfff80080
	s_addc_u32 s15, s13, -1
	s_add_i32 s70, 0, 0x10000
	s_cmp_eq_u32 s61, s14
	s_cselect_b32 s15, s11, s15
	s_cselect_b32 s14, s35, s68
	v_add_u32_e32 v59, s70, v185
	s_cselect_b32 s69, s45, s43
	s_cselect_b32 s68, s44, s42
	s_add_i32 s71, 0, 0x14000
	ds_read_b128 v[66:69], v59
	ds_read_b128 v[74:77], v59 offset:1024
	ds_read_b128 v[82:85], v59 offset:2048
	ds_read_b128 v[86:89], v59 offset:3072
	v_add_u32_e32 v59, s71, v185
	ds_read_b128 v[154:157], v59
	ds_read_b128 v[158:161], v59 offset:1024
	ds_read_b128 v[174:177], v59 offset:2048
	ds_read_b128 v[178:181], v59 offset:3072
	s_add_i32 m0, s54, 0xc000
	ds_read_b128 v[202:205], v200
	ds_read_b128 v[206:209], v200 offset:1024
	ds_read_b128 v[210:213], v200 offset:2048
	ds_read_b128 v[214:217], v200 offset:3072
	ds_read_b128 v[228:231], v200 offset:4096
	ds_read_b128 v[232:235], v200 offset:5120
	ds_read_b128 v[236:239], v200 offset:6144
	ds_read_b128 v[240:243], v200 offset:7168
	global_load_lds_dwordx4 v170, s[12:13]
	s_add_i32 m0, s54, 0xe000
	s_nop 0
	global_load_lds_dwordx4 v172, s[12:13]
	s_waitcnt vmcnt(8)
	s_waitcnt lgkmcnt(0)
	s_barrier
	s_waitcnt lgkmcnt(0)
	v_mfma_f32_16x16x32_bf16 v[150:153], v[66:69], v[202:205], v[150:153]
	v_mfma_f32_16x16x32_bf16 v[146:149], v[82:85], v[202:205], v[146:149]
	v_mfma_f32_16x16x32_bf16 v[134:137], v[66:69], v[210:213], v[134:137]
	v_mfma_f32_16x16x32_bf16 v[130:133], v[82:85], v[210:213], v[130:133]
	v_mfma_f32_16x16x32_bf16 v[118:121], v[66:69], v[228:231], v[118:121]
	v_mfma_f32_16x16x32_bf16 v[114:117], v[82:85], v[228:231], v[114:117]
	v_mfma_f32_16x16x32_bf16 v[102:105], v[66:69], v[236:239], v[102:105]
	v_mfma_f32_16x16x32_bf16 v[98:101], v[82:85], v[236:239], v[98:101]
	v_mfma_f32_16x16x32_bf16 v[150:153], v[74:77], v[206:209], v[150:153]
	v_mfma_f32_16x16x32_bf16 v[146:149], v[86:89], v[206:209], v[146:149]
	v_mfma_f32_16x16x32_bf16 v[134:137], v[74:77], v[214:217], v[134:137]
	v_mfma_f32_16x16x32_bf16 v[130:133], v[86:89], v[214:217], v[130:133]
	v_mfma_f32_16x16x32_bf16 v[118:121], v[74:77], v[232:235], v[118:121]
	v_mfma_f32_16x16x32_bf16 v[114:117], v[86:89], v[232:235], v[114:117]
	v_mfma_f32_16x16x32_bf16 v[102:105], v[74:77], v[240:243], v[102:105]
	v_mfma_f32_16x16x32_bf16 v[98:101], v[86:89], v[240:243], v[98:101]
	v_mfma_f32_16x16x32_bf16 v[142:145], v[154:157], v[202:205], v[142:145]
	v_mfma_f32_16x16x32_bf16 v[138:141], v[174:177], v[202:205], v[138:141]
	v_mfma_f32_16x16x32_bf16 v[126:129], v[154:157], v[210:213], v[126:129]
	v_mfma_f32_16x16x32_bf16 v[122:125], v[174:177], v[210:213], v[122:125]
	v_mfma_f32_16x16x32_bf16 v[110:113], v[154:157], v[228:231], v[110:113]
	v_mfma_f32_16x16x32_bf16 v[106:109], v[174:177], v[228:231], v[106:109]
	v_mfma_f32_16x16x32_bf16 v[94:97], v[154:157], v[236:239], v[94:97]
	v_mfma_f32_16x16x32_bf16 v[90:93], v[174:177], v[236:239], v[90:93]
	v_mfma_f32_16x16x32_bf16 v[142:145], v[158:161], v[206:209], v[142:145]
	v_mfma_f32_16x16x32_bf16 v[138:141], v[178:181], v[206:209], v[138:141]
	v_mfma_f32_16x16x32_bf16 v[126:129], v[158:161], v[214:217], v[126:129]
	v_mfma_f32_16x16x32_bf16 v[122:125], v[178:181], v[214:217], v[122:125]
	v_mfma_f32_16x16x32_bf16 v[110:113], v[158:161], v[232:235], v[110:113]
	v_mfma_f32_16x16x32_bf16 v[106:109], v[178:181], v[232:235], v[106:109]
	v_mfma_f32_16x16x32_bf16 v[94:97], v[158:161], v[240:243], v[94:97]
	v_mfma_f32_16x16x32_bf16 v[90:93], v[178:181], v[240:243], v[90:93]
	s_barrier
	s_add_i32 s70, s70, s53
	v_lshl_add_u64 v[218:219], s[68:69], 0, v[0:1]
	s_mov_b32 m0, s70
	ds_read_b128 v[202:205], v200 offset:16384
	ds_read_b128 v[206:209], v200 offset:17408
	ds_read_b128 v[210:213], v200 offset:18432
	ds_read_b128 v[214:217], v200 offset:19456
	ds_read_b128 v[228:231], v200 offset:20480
	ds_read_b128 v[232:235], v200 offset:21504
	ds_read_b128 v[236:239], v200 offset:22528
	ds_read_b128 v[240:243], v200 offset:23552
	global_load_lds_dwordx4 v[218:219], off
	s_add_i32 m0, s70, 0x2000
	v_lshl_add_u64 v[244:245], s[68:69], 0, v[166:167]
	s_add_u32 s68, s68, s24
	s_addc_u32 s69, s69, s25
	s_add_i32 s70, s71, s53
	global_load_lds_dwordx4 v[244:245], off
	v_lshl_add_u64 v[246:247], s[68:69], 0, v[0:1]
	s_mov_b32 m0, s70
	v_lshl_add_u64 v[248:249], s[68:69], 0, v[166:167]
	global_load_lds_dwordx4 v[246:247], off
	s_add_i32 m0, s70, 0x2000
	v_lshl_add_u64 v[250:251], s[14:15], 0, v[162:163]
	global_load_lds_dwordx4 v[248:249], off
	s_mov_b32 m0, s54
	v_lshl_add_u64 v[252:253], s[14:15], 0, v[164:165]
	global_load_lds_dwordx4 v[250:251], off
	s_mov_b32 m0, s55
	s_nop 0
	global_load_lds_dwordx4 v[252:253], off
	s_waitcnt vmcnt(8)
	s_waitcnt lgkmcnt(0)
	s_barrier
; #define PG8_STAGE(bufoff, gbase, voff) do { _Pragma("unroll") for (int _i = 0; _i < 2; ++_i) \
;         __builtin_amdgcn_global_load_lds((const unsigned*)((const char*)(gbase) + (voff)[_i]), (PG8_LAS unsigned*)(lds + (bufoff) + ldsw + _i * 8192), 16, 0, 0); } while (0)
; #define PG8_LDA(dst, b, h) do { _Pragma("unroll") for (int m = 0; m < 4; ++m) _Pragma("unroll") for (int k = 0; k < 2; ++k) dst[m][k] = *(const PG8_LAS bf16x8*)(lds + PG8_SA(b, h) + aoff + m * 2048 + k * 1024); } while (0)
; #define PG8_LDB(dst, b, h) do { _Pragma("unroll") for (int n = 0; n < 2; ++n) _Pragma("unroll") for (int k = 0; k < 2; ++k) dst[n][k] = *(const PG8_LAS bf16x8*)(lds + PG8_SB(b, h) + boff + n * 2048 + k * 1024); } while (0)
; #define PG8_MMA(ai, bj, At, Bt) do { __builtin_amdgcn_s_setprio(1); _Pragma("unroll") for (int m = 0; m < 4; ++m) _Pragma("unroll") for (int n = 0; n < 2; ++n) _Pragma("unroll") for (int k = 0; k < 2; ++k) \
;         acc[ai][bj][m][n] = __builtin_amdgcn_mfma_f32_16x16x32_bf16(Bt[n][k], At[m][k], acc[ai][bj][m][n], 0, 0, 0); __builtin_amdgcn_s_setprio(0); } while (0)
; #define PG8_WAIT_V(n) asm volatile("s_waitcnt vmcnt(" #n ")" ::: "memory")
; #define PG8_WAIT_L(n) asm volatile("s_waitcnt lgkmcnt(" #n ")" ::: "memory")
; #define PG8_BAR __builtin_amdgcn_s_barrier()
; #define PG8_SCHED __builtin_amdgcn_sched_barrier(0)
; template <class Epi, class Sched, bool ALIGN_EPI = false, bool SP2 = false>
; __device__ __forceinline__ void gemm_phase(PG8_LAS unsigned char* lds, const Gemm g, const Sched& S, const Epi& E, const int wv) {
;     ...
;             PG8_WAIT_V(8); PG8_WAIT_L(0); PG8_BAR; PG8_MMA(1, 0, At, B0); PG8_MMA(1, 1, At, B1); PG8_BAR; PG8_SCHED;
;             PG8_LDB(B0, 1, 0); PG8_LDB(B1, 1, 1); PG8_SCHED; PG8_LDA(At, 1, 0); PG8_STAGE(PG8_SA(0, 1), a2 + hstepA, voffA);
;             PG8_WAIT_V(8); PG8_WAIT_L(0); PG8_BAR; PG8_MMA(0, 0, At, B0); PG8_MMA(0, 1, At, B1); PG8_BAR; PG8_SCHED;
	s_waitcnt lgkmcnt(0)
	v_mfma_f32_16x16x32_bf16 v[78:81], v[66:69], v[202:205], v[78:81]
	v_mfma_f32_16x16x32_bf16 v[70:73], v[82:85], v[202:205], v[70:73]
	v_mfma_f32_16x16x32_bf16 v[46:49], v[66:69], v[210:213], v[46:49]
	v_mfma_f32_16x16x32_bf16 v[42:45], v[82:85], v[210:213], v[42:45]
	v_mfma_f32_16x16x32_bf16 v[30:33], v[66:69], v[228:231], v[30:33]
	v_mfma_f32_16x16x32_bf16 v[26:29], v[82:85], v[228:231], v[26:29]
	v_mfma_f32_16x16x32_bf16 v[14:17], v[66:69], v[236:239], v[14:17]
	v_mfma_f32_16x16x32_bf16 v[10:13], v[82:85], v[236:239], v[10:13]
	v_mfma_f32_16x16x32_bf16 v[78:81], v[74:77], v[206:209], v[78:81]
	v_mfma_f32_16x16x32_bf16 v[70:73], v[86:89], v[206:209], v[70:73]
	v_mfma_f32_16x16x32_bf16 v[46:49], v[74:77], v[214:217], v[46:49]
	v_mfma_f32_16x16x32_bf16 v[42:45], v[86:89], v[214:217], v[42:45]
	v_mfma_f32_16x16x32_bf16 v[30:33], v[74:77], v[232:235], v[30:33]
	v_mfma_f32_16x16x32_bf16 v[26:29], v[86:89], v[232:235], v[26:29]
	v_mfma_f32_16x16x32_bf16 v[14:17], v[74:77], v[240:243], v[14:17]
	v_mfma_f32_16x16x32_bf16 v[10:13], v[86:89], v[240:243], v[10:13]
	v_mfma_f32_16x16x32_bf16 v[60:63], v[154:157], v[202:205], v[62:65]
	v_mfma_f32_16x16x32_bf16 v[54:57], v[174:177], v[202:205], v[54:57]
	v_mfma_f32_16x16x32_bf16 v[38:41], v[154:157], v[210:213], v[38:41]
	v_mfma_f32_16x16x32_bf16 v[34:37], v[174:177], v[210:213], v[34:37]
	v_mfma_f32_16x16x32_bf16 v[22:25], v[154:157], v[228:231], v[22:25]
	v_mfma_f32_16x16x32_bf16 v[18:21], v[174:177], v[228:231], v[18:21]
	v_mfma_f32_16x16x32_bf16 v[6:9], v[154:157], v[236:239], v[6:9]
	v_mfma_f32_16x16x32_bf16 v[2:5], v[174:177], v[236:239], v[2:5]
	v_mfma_f32_16x16x32_bf16 v[60:63], v[158:161], v[206:209], v[60:63]
	v_mfma_f32_16x16x32_bf16 v[54:57], v[178:181], v[206:209], v[54:57]
	v_mfma_f32_16x16x32_bf16 v[38:41], v[158:161], v[214:217], v[38:41]
	v_mfma_f32_16x16x32_bf16 v[34:37], v[178:181], v[214:217], v[34:37]
	v_mfma_f32_16x16x32_bf16 v[22:25], v[158:161], v[232:235], v[22:25]
	v_mfma_f32_16x16x32_bf16 v[18:21], v[178:181], v[232:235], v[18:21]
	v_mfma_f32_16x16x32_bf16 v[6:9], v[158:161], v[240:243], v[6:9]
	v_mfma_f32_16x16x32_bf16 v[2:5], v[178:181], v[240:243], v[2:5]
	s_barrier
	s_add_i32 s68, 0, 0x18000
	v_add_u32_e32 v59, s68, v185
	s_add_i32 s69, 0, 0x1c000
	ds_read_b128 v[64:67], v59
	ds_read_b128 v[74:77], v59 offset:1024
	ds_read_b128 v[82:85], v59 offset:2048
	ds_read_b128 v[86:89], v59 offset:3072
	v_add_u32_e32 v59, s69, v185
	ds_read_b128 v[154:157], v59
	ds_read_b128 v[158:161], v59 offset:1024
	ds_read_b128 v[174:177], v59 offset:2048
	ds_read_b128 v[178:181], v59 offset:3072
	s_add_u32 s14, s14, 0x80000
	s_addc_u32 s15, s15, 0
	s_mov_b32 m0, s56
	ds_read_b128 v[202:205], v200 offset:32768
	ds_read_b128 v[206:209], v200 offset:33792
	ds_read_b128 v[210:213], v200 offset:34816
	ds_read_b128 v[214:217], v200 offset:35840
	ds_read_b128 v[228:231], v200 offset:36864
	ds_read_b128 v[232:235], v200 offset:37888
	ds_read_b128 v[236:239], v200 offset:38912
	ds_read_b128 v[240:243], v200 offset:39936
	global_load_lds_dwordx4 v162, s[14:15]
	s_mov_b32 m0, s57
	s_nop 0
	global_load_lds_dwordx4 v164, s[14:15]
	s_waitcnt vmcnt(8)
	s_waitcnt lgkmcnt(0)
	s_barrier
	s_waitcnt lgkmcnt(0)
	v_mfma_f32_16x16x32_bf16 v[150:153], v[64:67], v[202:205], v[150:153]
	v_mfma_f32_16x16x32_bf16 v[146:149], v[82:85], v[202:205], v[146:149]
	v_mfma_f32_16x16x32_bf16 v[134:137], v[64:67], v[210:213], v[134:137]
	v_mfma_f32_16x16x32_bf16 v[130:133], v[82:85], v[210:213], v[130:133]
	v_mfma_f32_16x16x32_bf16 v[118:121], v[64:67], v[228:231], v[118:121]
	v_mfma_f32_16x16x32_bf16 v[114:117], v[82:85], v[228:231], v[114:117]
	v_mfma_f32_16x16x32_bf16 v[102:105], v[64:67], v[236:239], v[102:105]
	v_mfma_f32_16x16x32_bf16 v[98:101], v[82:85], v[236:239], v[98:101]
	v_mfma_f32_16x16x32_bf16 v[150:153], v[74:77], v[206:209], v[150:153]
	v_mfma_f32_16x16x32_bf16 v[146:149], v[86:89], v[206:209], v[146:149]
	v_mfma_f32_16x16x32_bf16 v[134:137], v[74:77], v[214:217], v[134:137]
	v_mfma_f32_16x16x32_bf16 v[130:133], v[86:89], v[214:217], v[130:133]
	v_mfma_f32_16x16x32_bf16 v[118:121], v[74:77], v[232:235], v[118:121]
	v_mfma_f32_16x16x32_bf16 v[114:117], v[86:89], v[232:235], v[114:117]
	v_mfma_f32_16x16x32_bf16 v[102:105], v[74:77], v[240:243], v[102:105]
	v_mfma_f32_16x16x32_bf16 v[98:101], v[86:89], v[240:243], v[98:101]
	v_mfma_f32_16x16x32_bf16 v[142:145], v[154:157], v[202:205], v[142:145]
	v_mfma_f32_16x16x32_bf16 v[138:141], v[174:177], v[202:205], v[138:141]
	v_mfma_f32_16x16x32_bf16 v[126:129], v[154:157], v[210:213], v[126:129]
	v_mfma_f32_16x16x32_bf16 v[122:125], v[174:177], v[210:213], v[122:125]
	v_mfma_f32_16x16x32_bf16 v[110:113], v[154:157], v[228:231], v[110:113]
	v_mfma_f32_16x16x32_bf16 v[106:109], v[174:177], v[228:231], v[106:109]
	v_mfma_f32_16x16x32_bf16 v[94:97], v[154:157], v[236:239], v[94:97]
	v_mfma_f32_16x16x32_bf16 v[90:93], v[174:177], v[236:239], v[90:93]
	v_mfma_f32_16x16x32_bf16 v[142:145], v[158:161], v[206:209], v[142:145]
	v_mfma_f32_16x16x32_bf16 v[138:141], v[178:181], v[206:209], v[138:141]
	v_mfma_f32_16x16x32_bf16 v[126:129], v[158:161], v[214:217], v[126:129]
	v_mfma_f32_16x16x32_bf16 v[122:125], v[178:181], v[214:217], v[122:125]
	v_mfma_f32_16x16x32_bf16 v[110:113], v[158:161], v[232:235], v[110:113]
	v_mfma_f32_16x16x32_bf16 v[106:109], v[178:181], v[232:235], v[106:109]
	v_mfma_f32_16x16x32_bf16 v[94:97], v[158:161], v[240:243], v[94:97]
	v_mfma_f32_16x16x32_bf16 v[90:93], v[178:181], v[240:243], v[90:93]
	s_barrier
; #define PG8_STAGE(bufoff, gbase, voff) do { _Pragma("unroll") for (int _i = 0; _i < 2; ++_i) \
;         __builtin_amdgcn_global_load_lds((const unsigned*)((const char*)(gbase) + (voff)[_i]), (PG8_LAS unsigned*)(lds + (bufoff) + ldsw + _i * 8192), 16, 0, 0); } while (0)
; #define PG8_LDA(dst, b, h) do { _Pragma("unroll") for (int m = 0; m < 4; ++m) _Pragma("unroll") for (int k = 0; k < 2; ++k) dst[m][k] = *(const PG8_LAS bf16x8*)(lds + PG8_SA(b, h) + aoff + m * 2048 + k * 1024); } while (0)
; #define PG8_MMA(ai, bj, At, Bt) do { __builtin_amdgcn_s_setprio(1); _Pragma("unroll") for (int m = 0; m < 4; ++m) _Pragma("unroll") for (int n = 0; n < 2; ++n) _Pragma("unroll") for (int k = 0; k < 2; ++k) \
;         acc[ai][bj][m][n] = __builtin_amdgcn_mfma_f32_16x16x32_bf16(Bt[n][k], At[m][k], acc[ai][bj][m][n], 0, 0, 0); __builtin_amdgcn_s_setprio(0); } while (0)
; #define PG8_WAIT_V(n) asm volatile("s_waitcnt vmcnt(" #n ")" ::: "memory")
; #define PG8_WAIT_L(n) asm volatile("s_waitcnt lgkmcnt(" #n ")" ::: "memory")
; #define PG8_BAR __builtin_amdgcn_s_barrier()
; #define PG8_SCHED __builtin_amdgcn_sched_barrier(0)
; template <class Epi, class Sched, bool ALIGN_EPI = false, bool SP2 = false>
; __device__ __forceinline__ void gemm_phase(PG8_LAS unsigned char* lds, const Gemm g, const Sched& S, const Epi& E, const int wv) {
;     ...
;         for (int t = 0; t < nt; t += 2) {
;             const bool last = (t == nt - 2);
;             const char* a1 = cA + (size_t)(t + 1) * kstep;
;             const char* a2 = last ? nA : cA + (size_t)(t + 2) * kstep; const char* b2 = last ? nB : cB + (size_t)(t + 2) * kstep;
;     ...
;             PG8_LDA(At, 1, 1); PG8_STAGE(PG8_SB(1, 0), b3, voffB); PG8_STAGE(PG8_SB(1, 1), b3 + hstepB, voffB); PG8_STAGE(PG8_SA(1, 0), a3, voffA);
;             PG8_WAIT_V(8); PG8_WAIT_L(0); PG8_BAR; PG8_MMA(1, 0, At, B0); PG8_MMA(1, 1, At, B1); PG8_BAR; PG8_SCHED;
	s_add_i32 s14, s68, s53
	s_add_i32 m0, s14, 0xffffff80
	ds_read_b128 v[202:205], v200 offset:49152
	ds_read_b128 v[206:209], v200 offset:50176
	ds_read_b128 v[210:213], v200 offset:51200
	ds_read_b128 v[214:217], v200 offset:52224
	ds_read_b128 v[228:231], v200 offset:53248
	ds_read_b128 v[232:235], v200 offset:54272
	ds_read_b128 v[236:239], v200 offset:55296
	ds_read_b128 v[240:243], v200 offset:56320
	global_load_lds_dwordx4 v[218:219], off offset:128
	s_add_i32 m0, s14, 0x1f80
	s_add_i32 s14, s69, s53
	global_load_lds_dwordx4 v[244:245], off offset:128
	s_add_i32 m0, s14, 0xffffff80
	s_nop 0
	global_load_lds_dwordx4 v[246:247], off offset:128
	s_add_i32 m0, s14, 0x1f80
	s_nop 0
	global_load_lds_dwordx4 v[248:249], off offset:128
	s_add_i32 m0, s58, 0xffffff80
	s_nop 0
	global_load_lds_dwordx4 v[250:251], off offset:128
	s_add_i32 m0, s59, 0xffffff80
	s_nop 0
	global_load_lds_dwordx4 v[252:253], off offset:128
	s_waitcnt vmcnt(8)
	s_waitcnt lgkmcnt(0)
	s_barrier
	s_waitcnt lgkmcnt(0)
	v_mfma_f32_16x16x32_bf16 v[78:81], v[64:67], v[202:205], v[78:81]
	v_mfma_f32_16x16x32_bf16 v[68:71], v[82:85], v[202:205], v[70:73]
	v_mfma_f32_16x16x32_bf16 v[46:49], v[64:67], v[210:213], v[46:49]
	v_mfma_f32_16x16x32_bf16 v[42:45], v[82:85], v[210:213], v[42:45]
	v_mfma_f32_16x16x32_bf16 v[30:33], v[64:67], v[228:231], v[30:33]
	v_mfma_f32_16x16x32_bf16 v[26:29], v[82:85], v[228:231], v[26:29]
	v_mfma_f32_16x16x32_bf16 v[14:17], v[64:67], v[236:239], v[14:17]
	v_mfma_f32_16x16x32_bf16 v[10:13], v[82:85], v[236:239], v[10:13]
	v_mfma_f32_16x16x32_bf16 v[78:81], v[74:77], v[206:209], v[78:81]
	v_mfma_f32_16x16x32_bf16 v[70:73], v[86:89], v[206:209], v[68:71]
	v_mfma_f32_16x16x32_bf16 v[46:49], v[74:77], v[214:217], v[46:49]
	v_mfma_f32_16x16x32_bf16 v[42:45], v[86:89], v[214:217], v[42:45]
	v_mfma_f32_16x16x32_bf16 v[30:33], v[74:77], v[232:235], v[30:33]
	v_mfma_f32_16x16x32_bf16 v[26:29], v[86:89], v[232:235], v[26:29]
	v_mfma_f32_16x16x32_bf16 v[14:17], v[74:77], v[240:243], v[14:17]
	v_mfma_f32_16x16x32_bf16 v[10:13], v[86:89], v[240:243], v[10:13]
	v_mfma_f32_16x16x32_bf16 v[60:63], v[154:157], v[202:205], v[60:63]
	v_mfma_f32_16x16x32_bf16 v[54:57], v[174:177], v[202:205], v[54:57]
	v_mfma_f32_16x16x32_bf16 v[38:41], v[154:157], v[210:213], v[38:41]
	v_mfma_f32_16x16x32_bf16 v[34:37], v[174:177], v[210:213], v[34:37]
	v_mfma_f32_16x16x32_bf16 v[22:25], v[154:157], v[228:231], v[22:25]
	v_mfma_f32_16x16x32_bf16 v[18:21], v[174:177], v[228:231], v[18:21]
	v_mfma_f32_16x16x32_bf16 v[6:9], v[154:157], v[236:239], v[6:9]
	v_mfma_f32_16x16x32_bf16 v[2:5], v[174:177], v[236:239], v[2:5]
	v_mfma_f32_16x16x32_bf16 v[62:65], v[158:161], v[206:209], v[60:63]
	v_mfma_f32_16x16x32_bf16 v[54:57], v[178:181], v[206:209], v[54:57]
	v_mfma_f32_16x16x32_bf16 v[38:41], v[158:161], v[214:217], v[38:41]
	v_mfma_f32_16x16x32_bf16 v[34:37], v[178:181], v[214:217], v[34:37]
	v_mfma_f32_16x16x32_bf16 v[22:25], v[158:161], v[232:235], v[22:25]
	v_mfma_f32_16x16x32_bf16 v[18:21], v[178:181], v[232:235], v[18:21]
	v_mfma_f32_16x16x32_bf16 v[6:9], v[158:161], v[240:243], v[6:9]
	v_mfma_f32_16x16x32_bf16 v[2:5], v[178:181], v[240:243], v[2:5]
	s_barrier
	s_add_u32 s12, s12, 0x100
	s_addc_u32 s13, s13, 0
	s_add_u32 s42, s42, 0x100
	s_addc_u32 s43, s43, 0
	s_cmp_ge_i32 s67, s60
	s_mov_b32 s14, s67
	s_cbranch_scc0 .LBB0_176
	s_movk_i32 s68, 0x4000
	s_movk_i32 s69, 0x6000
	s_mov_b32 s70, 0x18000
	s_mov_b32 s71, 0x3f317217

; #define PG8_STAGE(bufoff, gbase, voff) do { _Pragma("unroll") for (int _i = 0; _i < 2; ++_i) \
;         __builtin_amdgcn_global_load_lds((const unsigned*)((const char*)(gbase) + (voff)[_i]), (PG8_LAS unsigned*)(lds + (bufoff) + ldsw + _i * 8192), 16, 0, 0); } while (0)
; #define PG8_LDA(dst, b, h) do { _Pragma("unroll") for (int m = 0; m < 4; ++m) _Pragma("unroll") for (int k = 0; k < 2; ++k) dst[m][k] = *(const PG8_LAS bf16x8*)(lds + PG8_SA(b, h) + aoff + m * 2048 + k * 1024); } while (0)
; #define PG8_LDB(dst, b, h) do { _Pragma("unroll") for (int n = 0; n < 2; ++n) _Pragma("unroll") for (int k = 0; k < 2; ++k) dst[n][k] = *(const PG8_LAS bf16x8*)(lds + PG8_SB(b, h) + boff + n * 2048 + k * 1024); } while (0)
; #define PG8_MMA(ai, bj, At, Bt) do { __builtin_amdgcn_s_setprio(1); _Pragma("unroll") for (int m = 0; m < 4; ++m) _Pragma("unroll") for (int n = 0; n < 2; ++n) _Pragma("unroll") for (int k = 0; k < 2; ++k) \
;         acc[ai][bj][m][n] = __builtin_amdgcn_mfma_f32_16x16x32_bf16(Bt[n][k], At[m][k], acc[ai][bj][m][n], 0, 0, 0); __builtin_amdgcn_s_setprio(0); } while (0)
; #define PG8_WAIT_V(n) asm volatile("s_waitcnt vmcnt(" #n ")" ::: "memory")
; #define PG8_WAIT_L(n) asm volatile("s_waitcnt lgkmcnt(" #n ")" ::: "memory")
; #define PG8_BAR __builtin_amdgcn_s_barrier()
; template <class Epi, class Sched, bool ALIGN_EPI = false, bool SP2 = false>
; __device__ __forceinline__ void gemm_phase(PG8_LAS unsigned char* lds, const Gemm g, const Sched& S, const Epi& E, const int wv) {
;     ...
;         for (int t = 0; t < nt; t += 2) {
;             const bool last = (t == nt - 2);
;             const char* a1 = cA + (size_t)(t + 1) * kstep;
;             const char* a2 = last ? nA : cA + (size_t)(t + 2) * kstep; const char* b2 = last ? nB : cB + (size_t)(t + 2) * kstep;
;             const char* a3 = a2 + kstep; const char* b3 = b2 + kstep;
;             if (last && has_next) S.a_ready(nxt);
;             if constexpr (SP2) {
;             PG8_LDB(B0, 0, 0); PG8_LDB(B1, 0, 1); PG8_SCHED; PG8_LDA(At, 0, 0); PG8_STAGE(PG8_SA(1, 1), a1 + hstepA, voffA);
;             PG8_WAIT_V(8); PG8_WAIT_L(0); PG8_BAR; PG8_MMA(0, 0, At, B0); PG8_MMA(0, 1, At, B1); PG8_BAR; PG8_SCHED;
;             PG8_LDA(At, 0, 1); PG8_STAGE(PG8_SB(0, 0), b2, voffB); PG8_STAGE(PG8_SB(0, 1), b2 + hstepB, voffB); PG8_STAGE(PG8_SA(0, 0), a2, voffA);
.LBB0_336:
	s_add_i32 s40, s14, 2
	s_add_u32 s41, s12, 0xfff80080
	s_addc_u32 s15, s13, -1
	s_add_i32 s65, 0, 0x10000
	s_cmp_eq_u32 s62, s14
	s_cselect_b32 s15, s93, s15
	s_cselect_b32 s14, s92, s41
	s_cselect_b32 s45, s25, s17
	s_cselect_b32 s44, s24, s11
	s_add_i32 s41, 0, 0x14000
	v_add_u32_e32 v46, s65, v197
	v_add_u32_e32 v158, s41, v197
	ds_read_b128 v[26:29], v46
	ds_read_b128 v[30:33], v46 offset:1024
	ds_read_b128 v[42:45], v46 offset:2048
	ds_read_b128 v[46:49], v46 offset:3072
	ds_read_b128 v[146:149], v158
	ds_read_b128 v[150:153], v158 offset:1024
	ds_read_b128 v[154:157], v158 offset:2048
	ds_read_b128 v[158:161], v158 offset:3072
	s_add_i32 m0, s55, 0xc000
	ds_read_b128 v[172:175], v199
	ds_read_b128 v[176:179], v199 offset:1024
	ds_read_b128 v[180:183], v199 offset:2048
	ds_read_b128 v[200:203], v199 offset:3072
	ds_read_b128 v[204:207], v199 offset:4096
	ds_read_b128 v[208:211], v199 offset:5120
	ds_read_b128 v[212:215], v199 offset:6144
	ds_read_b128 v[216:219], v199 offset:7168
	global_load_lds_dwordx4 v168, s[12:13]
	s_add_i32 m0, s55, 0xe000
	s_nop 0
	global_load_lds_dwordx4 v170, s[12:13]
	s_waitcnt vmcnt(8)
	s_waitcnt lgkmcnt(0)
	s_barrier
	s_waitcnt lgkmcnt(0)
	v_mfma_f32_16x16x32_bf16 v[138:141], v[26:29], v[172:175], v[138:141]
	v_mfma_f32_16x16x32_bf16 v[142:145], v[42:45], v[172:175], v[142:145]
	v_mfma_f32_16x16x32_bf16 v[126:129], v[26:29], v[180:183], v[126:129]
	v_mfma_f32_16x16x32_bf16 v[122:125], v[42:45], v[180:183], v[122:125]
	v_mfma_f32_16x16x32_bf16 v[110:113], v[26:29], v[204:207], v[110:113]
	v_mfma_f32_16x16x32_bf16 v[106:109], v[42:45], v[204:207], v[106:109]
	v_mfma_f32_16x16x32_bf16 v[94:97], v[26:29], v[212:215], v[94:97]
	v_mfma_f32_16x16x32_bf16 v[90:93], v[42:45], v[212:215], v[90:93]
	v_mfma_f32_16x16x32_bf16 v[138:141], v[30:33], v[176:179], v[138:141]
	v_mfma_f32_16x16x32_bf16 v[142:145], v[46:49], v[176:179], v[142:145]
	v_mfma_f32_16x16x32_bf16 v[126:129], v[30:33], v[200:203], v[126:129]
	v_mfma_f32_16x16x32_bf16 v[122:125], v[46:49], v[200:203], v[122:125]
	v_mfma_f32_16x16x32_bf16 v[110:113], v[30:33], v[208:211], v[110:113]
	v_mfma_f32_16x16x32_bf16 v[106:109], v[46:49], v[208:211], v[106:109]
	v_mfma_f32_16x16x32_bf16 v[94:97], v[30:33], v[216:219], v[94:97]
	v_mfma_f32_16x16x32_bf16 v[90:93], v[46:49], v[216:219], v[90:93]
	v_mfma_f32_16x16x32_bf16 v[134:137], v[146:149], v[172:175], v[134:137]
	v_mfma_f32_16x16x32_bf16 v[130:133], v[154:157], v[172:175], v[130:133]
	v_mfma_f32_16x16x32_bf16 v[118:121], v[146:149], v[180:183], v[118:121]
	v_mfma_f32_16x16x32_bf16 v[114:117], v[154:157], v[180:183], v[114:117]
	v_mfma_f32_16x16x32_bf16 v[102:105], v[146:149], v[204:207], v[102:105]
	v_mfma_f32_16x16x32_bf16 v[98:101], v[154:157], v[204:207], v[98:101]
	v_mfma_f32_16x16x32_bf16 v[86:89], v[146:149], v[212:215], v[86:89]
	v_mfma_f32_16x16x32_bf16 v[82:85], v[154:157], v[212:215], v[82:85]
	v_mfma_f32_16x16x32_bf16 v[134:137], v[150:153], v[176:179], v[134:137]
	v_mfma_f32_16x16x32_bf16 v[130:133], v[158:161], v[176:179], v[130:133]
	v_mfma_f32_16x16x32_bf16 v[118:121], v[150:153], v[200:203], v[118:121]
	v_mfma_f32_16x16x32_bf16 v[114:117], v[158:161], v[200:203], v[114:117]
	v_mfma_f32_16x16x32_bf16 v[102:105], v[150:153], v[208:211], v[102:105]
	v_mfma_f32_16x16x32_bf16 v[98:101], v[158:161], v[208:211], v[98:101]
	v_mfma_f32_16x16x32_bf16 v[86:89], v[150:153], v[216:219], v[86:89]
	v_mfma_f32_16x16x32_bf16 v[82:85], v[158:161], v[216:219], v[82:85]
	s_barrier
	s_add_i32 s65, s65, s54
	v_lshl_add_u64 v[184:185], s[44:45], 0, v[0:1]
	s_mov_b32 m0, s65
	ds_read_b128 v[172:175], v199 offset:16384
	ds_read_b128 v[176:179], v199 offset:17408
	ds_read_b128 v[180:183], v199 offset:18432
	ds_read_b128 v[200:203], v199 offset:19456
	ds_read_b128 v[204:207], v199 offset:20480
	ds_read_b128 v[208:211], v199 offset:21504
	ds_read_b128 v[212:215], v199 offset:22528
	ds_read_b128 v[216:219], v199 offset:23552
	global_load_lds_dwordx4 v[184:185], off
	s_add_i32 m0, s65, 0x2000
	v_lshl_add_u64 v[194:195], s[44:45], 0, v[162:163]
	s_add_u32 s44, s44, s28
	s_addc_u32 s45, s45, s29
	s_add_i32 s41, s41, s54
	global_load_lds_dwordx4 v[194:195], off
	v_lshl_add_u64 v[228:229], s[44:45], 0, v[0:1]
	s_mov_b32 m0, s41
	v_lshl_add_u64 v[230:231], s[44:45], 0, v[162:163]
	global_load_lds_dwordx4 v[228:229], off
	s_add_i32 m0, s41, 0x2000
	v_lshl_add_u64 v[232:233], s[14:15], 0, v[166:167]
	global_load_lds_dwordx4 v[230:231], off
	s_mov_b32 m0, s55
	v_lshl_add_u64 v[234:235], s[14:15], 0, v[164:165]
	global_load_lds_dwordx4 v[232:233], off
	s_mov_b32 m0, s56
	s_nop 0
	global_load_lds_dwordx4 v[234:235], off
	s_waitcnt vmcnt(8)
	s_waitcnt lgkmcnt(0)
	s_barrier
; #define PG8_STAGE(bufoff, gbase, voff) do { _Pragma("unroll") for (int _i = 0; _i < 2; ++_i) \
;         __builtin_amdgcn_global_load_lds((const unsigned*)((const char*)(gbase) + (voff)[_i]), (PG8_LAS unsigned*)(lds + (bufoff) + ldsw + _i * 8192), 16, 0, 0); } while (0)
; #define PG8_LDA(dst, b, h) do { _Pragma("unroll") for (int m = 0; m < 4; ++m) _Pragma("unroll") for (int k = 0; k < 2; ++k) dst[m][k] = *(const PG8_LAS bf16x8*)(lds + PG8_SA(b, h) + aoff + m * 2048 + k * 1024); } while (0)
; #define PG8_LDB(dst, b, h) do { _Pragma("unroll") for (int n = 0; n < 2; ++n) _Pragma("unroll") for (int k = 0; k < 2; ++k) dst[n][k] = *(const PG8_LAS bf16x8*)(lds + PG8_SB(b, h) + boff + n * 2048 + k * 1024); } while (0)
; #define PG8_MMA(ai, bj, At, Bt) do { __builtin_amdgcn_s_setprio(1); _Pragma("unroll") for (int m = 0; m < 4; ++m) _Pragma("unroll") for (int n = 0; n < 2; ++n) _Pragma("unroll") for (int k = 0; k < 2; ++k) \
;         acc[ai][bj][m][n] = __builtin_amdgcn_mfma_f32_16x16x32_bf16(Bt[n][k], At[m][k], acc[ai][bj][m][n], 0, 0, 0); __builtin_amdgcn_s_setprio(0); } while (0)
; #define PG8_WAIT_V(n) asm volatile("s_waitcnt vmcnt(" #n ")" ::: "memory")
; #define PG8_WAIT_L(n) asm volatile("s_waitcnt lgkmcnt(" #n ")" ::: "memory")
; #define PG8_BAR __builtin_amdgcn_s_barrier()
; #define PG8_SCHED __builtin_amdgcn_sched_barrier(0)
; template <class Epi, class Sched, bool ALIGN_EPI = false, bool SP2 = false>
; __device__ __forceinline__ void gemm_phase(PG8_LAS unsigned char* lds, const Gemm g, const Sched& S, const Epi& E, const int wv) {
;     ...
;             PG8_WAIT_V(8); PG8_WAIT_L(0); PG8_BAR; PG8_MMA(1, 0, At, B0); PG8_MMA(1, 1, At, B1); PG8_BAR; PG8_SCHED;
;             PG8_LDB(B0, 1, 0); PG8_LDB(B1, 1, 1); PG8_SCHED; PG8_LDA(At, 1, 0); PG8_STAGE(PG8_SA(0, 1), a2 + hstepA, voffA);
;             PG8_WAIT_V(8); PG8_WAIT_L(0); PG8_BAR; PG8_MMA(0, 0, At, B0); PG8_MMA(0, 1, At, B1); PG8_BAR; PG8_SCHED;
	s_waitcnt lgkmcnt(0)
	v_mfma_f32_16x16x32_bf16 v[78:81], v[26:29], v[172:175], v[78:81]
	v_mfma_f32_16x16x32_bf16 v[74:77], v[42:45], v[172:175], v[74:77]
	v_mfma_f32_16x16x32_bf16 v[62:65], v[26:29], v[180:183], v[62:65]
	v_mfma_f32_16x16x32_bf16 v[58:61], v[42:45], v[180:183], v[58:61]
	v_mfma_f32_16x16x32_bf16 v[38:41], v[26:29], v[204:207], v[38:41]
	v_mfma_f32_16x16x32_bf16 v[34:37], v[42:45], v[204:207], v[34:37]
	v_mfma_f32_16x16x32_bf16 v[14:17], v[26:29], v[212:215], v[14:17]
	v_mfma_f32_16x16x32_bf16 v[10:13], v[42:45], v[212:215], v[10:13]
	v_mfma_f32_16x16x32_bf16 v[78:81], v[30:33], v[176:179], v[78:81]
	v_mfma_f32_16x16x32_bf16 v[74:77], v[46:49], v[176:179], v[74:77]
	v_mfma_f32_16x16x32_bf16 v[62:65], v[30:33], v[200:203], v[62:65]
	v_mfma_f32_16x16x32_bf16 v[58:61], v[46:49], v[200:203], v[58:61]
	v_mfma_f32_16x16x32_bf16 v[38:41], v[30:33], v[208:211], v[38:41]
	v_mfma_f32_16x16x32_bf16 v[34:37], v[46:49], v[208:211], v[34:37]
	v_mfma_f32_16x16x32_bf16 v[14:17], v[30:33], v[216:219], v[14:17]
	v_mfma_f32_16x16x32_bf16 v[10:13], v[46:49], v[216:219], v[10:13]
	v_mfma_f32_16x16x32_bf16 v[22:25], v[146:149], v[204:207], v[22:25]
	v_mfma_f32_16x16x32_bf16 v[18:21], v[154:157], v[204:207], v[18:21]
	v_mfma_f32_16x16x32_bf16 v[6:9], v[146:149], v[212:215], v[6:9]
	v_mfma_f32_16x16x32_bf16 v[2:5], v[154:157], v[212:215], v[2:5]
	v_mfma_f32_16x16x32_bf16 v[26:29], v[146:149], v[172:175], v[70:73]
	v_mfma_f32_16x16x32_bf16 v[30:33], v[154:157], v[172:175], v[66:69]
	v_mfma_f32_16x16x32_bf16 v[42:45], v[146:149], v[180:183], v[54:57]
	v_mfma_f32_16x16x32_bf16 v[46:49], v[154:157], v[180:183], v[50:53]
	v_mfma_f32_16x16x32_bf16 v[22:25], v[150:153], v[208:211], v[22:25]
	v_mfma_f32_16x16x32_bf16 v[18:21], v[158:161], v[208:211], v[18:21]
	v_mfma_f32_16x16x32_bf16 v[6:9], v[150:153], v[216:219], v[6:9]
	v_mfma_f32_16x16x32_bf16 v[2:5], v[158:161], v[216:219], v[2:5]
	v_mfma_f32_16x16x32_bf16 v[26:29], v[150:153], v[176:179], v[26:29]
	v_mfma_f32_16x16x32_bf16 v[30:33], v[158:161], v[176:179], v[30:33]
	v_mfma_f32_16x16x32_bf16 v[42:45], v[150:153], v[200:203], v[42:45]
	v_mfma_f32_16x16x32_bf16 v[46:49], v[158:161], v[200:203], v[46:49]
	s_barrier
	s_add_i32 s41, 0, 0x18000
	s_add_i32 s44, 0, 0x1c000
	v_add_u32_e32 v70, s41, v197
	v_add_u32_e32 v158, s44, v197
	ds_read_b128 v[50:53], v70
	ds_read_b128 v[54:57], v70 offset:1024
	ds_read_b128 v[66:69], v70 offset:2048
	ds_read_b128 v[70:73], v70 offset:3072
	ds_read_b128 v[146:149], v158
	ds_read_b128 v[150:153], v158 offset:1024
	ds_read_b128 v[154:157], v158 offset:2048
	ds_read_b128 v[158:161], v158 offset:3072
	s_add_u32 s14, s14, 0x80000
	s_addc_u32 s15, s15, 0
	s_mov_b32 m0, s57
	ds_read_b128 v[172:175], v199 offset:32768
	ds_read_b128 v[176:179], v199 offset:33792
	ds_read_b128 v[180:183], v199 offset:34816
	ds_read_b128 v[200:203], v199 offset:35840
	ds_read_b128 v[204:207], v199 offset:36864
	ds_read_b128 v[208:211], v199 offset:37888
	ds_read_b128 v[212:215], v199 offset:38912
	ds_read_b128 v[216:219], v199 offset:39936
	global_load_lds_dwordx4 v166, s[14:15]
	s_mov_b32 m0, s58
	s_nop 0
	global_load_lds_dwordx4 v164, s[14:15]
	s_waitcnt vmcnt(8)
	s_waitcnt lgkmcnt(0)
	s_barrier
	s_waitcnt lgkmcnt(0)
	v_mfma_f32_16x16x32_bf16 v[138:141], v[50:53], v[172:175], v[138:141]
	v_mfma_f32_16x16x32_bf16 v[142:145], v[66:69], v[172:175], v[142:145]
	v_mfma_f32_16x16x32_bf16 v[126:129], v[50:53], v[180:183], v[126:129]
	v_mfma_f32_16x16x32_bf16 v[122:125], v[66:69], v[180:183], v[122:125]
	v_mfma_f32_16x16x32_bf16 v[110:113], v[50:53], v[204:207], v[110:113]
	v_mfma_f32_16x16x32_bf16 v[106:109], v[66:69], v[204:207], v[106:109]
	v_mfma_f32_16x16x32_bf16 v[94:97], v[50:53], v[212:215], v[94:97]
	v_mfma_f32_16x16x32_bf16 v[90:93], v[66:69], v[212:215], v[90:93]
	v_mfma_f32_16x16x32_bf16 v[138:141], v[54:57], v[176:179], v[138:141]
	v_mfma_f32_16x16x32_bf16 v[142:145], v[70:73], v[176:179], v[142:145]
	v_mfma_f32_16x16x32_bf16 v[126:129], v[54:57], v[200:203], v[126:129]
	v_mfma_f32_16x16x32_bf16 v[122:125], v[70:73], v[200:203], v[122:125]
	v_mfma_f32_16x16x32_bf16 v[110:113], v[54:57], v[208:211], v[110:113]
	v_mfma_f32_16x16x32_bf16 v[106:109], v[70:73], v[208:211], v[106:109]
	v_mfma_f32_16x16x32_bf16 v[94:97], v[54:57], v[216:219], v[94:97]
	v_mfma_f32_16x16x32_bf16 v[90:93], v[70:73], v[216:219], v[90:93]
	v_mfma_f32_16x16x32_bf16 v[134:137], v[146:149], v[172:175], v[134:137]
	v_mfma_f32_16x16x32_bf16 v[130:133], v[154:157], v[172:175], v[130:133]
	v_mfma_f32_16x16x32_bf16 v[118:121], v[146:149], v[180:183], v[118:121]
	v_mfma_f32_16x16x32_bf16 v[114:117], v[154:157], v[180:183], v[114:117]
	v_mfma_f32_16x16x32_bf16 v[102:105], v[146:149], v[204:207], v[102:105]
	v_mfma_f32_16x16x32_bf16 v[98:101], v[154:157], v[204:207], v[98:101]
	v_mfma_f32_16x16x32_bf16 v[86:89], v[146:149], v[212:215], v[86:89]
	v_mfma_f32_16x16x32_bf16 v[82:85], v[154:157], v[212:215], v[82:85]
	v_mfma_f32_16x16x32_bf16 v[134:137], v[150:153], v[176:179], v[134:137]
	v_mfma_f32_16x16x32_bf16 v[130:133], v[158:161], v[176:179], v[130:133]
	v_mfma_f32_16x16x32_bf16 v[118:121], v[150:153], v[200:203], v[118:121]
	v_mfma_f32_16x16x32_bf16 v[114:117], v[158:161], v[200:203], v[114:117]
	v_mfma_f32_16x16x32_bf16 v[102:105], v[150:153], v[208:211], v[102:105]
	v_mfma_f32_16x16x32_bf16 v[98:101], v[158:161], v[208:211], v[98:101]
	v_mfma_f32_16x16x32_bf16 v[86:89], v[150:153], v[216:219], v[86:89]
	v_mfma_f32_16x16x32_bf16 v[82:85], v[158:161], v[216:219], v[82:85]
	s_barrier
; #define PG8_STAGE(bufoff, gbase, voff) do { _Pragma("unroll") for (int _i = 0; _i < 2; ++_i) \
;         __builtin_amdgcn_global_load_lds((const unsigned*)((const char*)(gbase) + (voff)[_i]), (PG8_LAS unsigned*)(lds + (bufoff) + ldsw + _i * 8192), 16, 0, 0); } while (0)
; #define PG8_LDA(dst, b, h) do { _Pragma("unroll") for (int m = 0; m < 4; ++m) _Pragma("unroll") for (int k = 0; k < 2; ++k) dst[m][k] = *(const PG8_LAS bf16x8*)(lds + PG8_SA(b, h) + aoff + m * 2048 + k * 1024); } while (0)
; #define PG8_MMA(ai, bj, At, Bt) do { __builtin_amdgcn_s_setprio(1); _Pragma("unroll") for (int m = 0; m < 4; ++m) _Pragma("unroll") for (int n = 0; n < 2; ++n) _Pragma("unroll") for (int k = 0; k < 2; ++k) \
;         acc[ai][bj][m][n] = __builtin_amdgcn_mfma_f32_16x16x32_bf16(Bt[n][k], At[m][k], acc[ai][bj][m][n], 0, 0, 0); __builtin_amdgcn_s_setprio(0); } while (0)
; #define PG8_WAIT_V(n) asm volatile("s_waitcnt vmcnt(" #n ")" ::: "memory")
; #define PG8_WAIT_L(n) asm volatile("s_waitcnt lgkmcnt(" #n ")" ::: "memory")
; #define PG8_BAR __builtin_amdgcn_s_barrier()
; #define PG8_SCHED __builtin_amdgcn_sched_barrier(0)
; template <class Epi, class Sched, bool ALIGN_EPI = false, bool SP2 = false>
; __device__ __forceinline__ void gemm_phase(PG8_LAS unsigned char* lds, const Gemm g, const Sched& S, const Epi& E, const int wv) {
;     ...
;         for (int t = 0; t < nt; t += 2) {
;             const bool last = (t == nt - 2);
;             const char* a1 = cA + (size_t)(t + 1) * kstep;
;             const char* a2 = last ? nA : cA + (size_t)(t + 2) * kstep; const char* b2 = last ? nB : cB + (size_t)(t + 2) * kstep;
;     ...
;             PG8_LDA(At, 1, 1); PG8_STAGE(PG8_SB(1, 0), b3, voffB); PG8_STAGE(PG8_SB(1, 1), b3 + hstepB, voffB); PG8_STAGE(PG8_SA(1, 0), a3, voffA);
;             PG8_WAIT_V(8); PG8_WAIT_L(0); PG8_BAR; PG8_MMA(1, 0, At, B0); PG8_MMA(1, 1, At, B1); PG8_BAR; PG8_SCHED;
	s_add_i32 s14, s41, s54
	s_add_i32 m0, s14, 0xffffff80
	ds_read_b128 v[172:175], v199 offset:49152
	ds_read_b128 v[176:179], v199 offset:50176
	ds_read_b128 v[180:183], v199 offset:51200
	ds_read_b128 v[200:203], v199 offset:52224
	ds_read_b128 v[204:207], v199 offset:53248
	ds_read_b128 v[208:211], v199 offset:54272
	ds_read_b128 v[212:215], v199 offset:55296
	ds_read_b128 v[216:219], v199 offset:56320
	global_load_lds_dwordx4 v[184:185], off offset:128
	s_add_i32 m0, s14, 0x1f80
	s_add_i32 s14, s44, s54
	global_load_lds_dwordx4 v[194:195], off offset:128
	s_add_i32 m0, s14, 0xffffff80
	s_nop 0
	global_load_lds_dwordx4 v[228:229], off offset:128
	s_add_i32 m0, s14, 0x1f80
	s_nop 0
	global_load_lds_dwordx4 v[230:231], off offset:128
	s_add_i32 m0, s60, 0xffffff80
	s_nop 0
	global_load_lds_dwordx4 v[232:233], off offset:128
	s_add_i32 m0, s61, 0xffffff80
	s_nop 0
	global_load_lds_dwordx4 v[234:235], off offset:128
	s_waitcnt vmcnt(8)
	s_waitcnt lgkmcnt(0)
	s_barrier
	s_waitcnt lgkmcnt(0)
	v_mfma_f32_16x16x32_bf16 v[78:81], v[50:53], v[172:175], v[78:81]
	v_mfma_f32_16x16x32_bf16 v[74:77], v[66:69], v[172:175], v[74:77]
	v_mfma_f32_16x16x32_bf16 v[62:65], v[50:53], v[180:183], v[62:65]
	v_mfma_f32_16x16x32_bf16 v[58:61], v[66:69], v[180:183], v[58:61]
	v_mfma_f32_16x16x32_bf16 v[38:41], v[50:53], v[204:207], v[38:41]
	v_mfma_f32_16x16x32_bf16 v[34:37], v[66:69], v[204:207], v[34:37]
	v_mfma_f32_16x16x32_bf16 v[14:17], v[50:53], v[212:215], v[14:17]
	v_mfma_f32_16x16x32_bf16 v[10:13], v[66:69], v[212:215], v[10:13]
	v_mfma_f32_16x16x32_bf16 v[78:81], v[54:57], v[176:179], v[78:81]
	v_mfma_f32_16x16x32_bf16 v[74:77], v[70:73], v[176:179], v[74:77]
	v_mfma_f32_16x16x32_bf16 v[62:65], v[54:57], v[200:203], v[62:65]
	v_mfma_f32_16x16x32_bf16 v[58:61], v[70:73], v[200:203], v[58:61]
	v_mfma_f32_16x16x32_bf16 v[38:41], v[54:57], v[208:211], v[38:41]
	v_mfma_f32_16x16x32_bf16 v[34:37], v[70:73], v[208:211], v[34:37]
	v_mfma_f32_16x16x32_bf16 v[14:17], v[54:57], v[216:219], v[14:17]
	v_mfma_f32_16x16x32_bf16 v[10:13], v[70:73], v[216:219], v[10:13]
	v_mfma_f32_16x16x32_bf16 v[26:29], v[146:149], v[172:175], v[26:29]
	v_mfma_f32_16x16x32_bf16 v[70:73], v[150:153], v[176:179], v[26:29]
	v_mfma_f32_16x16x32_bf16 v[26:29], v[154:157], v[172:175], v[30:33]
	v_mfma_f32_16x16x32_bf16 v[66:69], v[158:161], v[176:179], v[26:29]
	v_mfma_f32_16x16x32_bf16 v[26:29], v[146:149], v[180:183], v[42:45]
	v_mfma_f32_16x16x32_bf16 v[54:57], v[150:153], v[200:203], v[26:29]
	v_mfma_f32_16x16x32_bf16 v[26:29], v[154:157], v[180:183], v[46:49]
	v_mfma_f32_16x16x32_bf16 v[22:25], v[146:149], v[204:207], v[22:25]
	v_mfma_f32_16x16x32_bf16 v[18:21], v[154:157], v[204:207], v[18:21]
	v_mfma_f32_16x16x32_bf16 v[6:9], v[146:149], v[212:215], v[6:9]
	v_mfma_f32_16x16x32_bf16 v[2:5], v[154:157], v[212:215], v[2:5]
	v_mfma_f32_16x16x32_bf16 v[50:53], v[158:161], v[200:203], v[26:29]
	v_mfma_f32_16x16x32_bf16 v[22:25], v[150:153], v[208:211], v[22:25]
	v_mfma_f32_16x16x32_bf16 v[18:21], v[158:161], v[208:211], v[18:21]
	v_mfma_f32_16x16x32_bf16 v[6:9], v[150:153], v[216:219], v[6:9]
	v_mfma_f32_16x16x32_bf16 v[2:5], v[158:161], v[216:219], v[2:5]
	s_barrier
	s_add_u32 s12, s12, 0x100
	s_addc_u32 s13, s13, 0
	s_add_u32 s11, s11, 0x100
	s_addc_u32 s17, s17, 0
	s_cmp_ge_i32 s40, s59
	s_mov_b32 s14, s40
	s_cbranch_scc0 .LBB0_336

; #define PG8_STAGE(bufoff, gbase, voff) do { _Pragma("unroll") for (int _i = 0; _i < 2; ++_i) \
;         __builtin_amdgcn_global_load_lds((const unsigned*)((const char*)(gbase) + (voff)[_i]), (PG8_LAS unsigned*)(lds + (bufoff) + ldsw + _i * 8192), 16, 0, 0); } while (0)
; #define PG8_LDA(dst, b, h) do { _Pragma("unroll") for (int m = 0; m < 4; ++m) _Pragma("unroll") for (int k = 0; k < 2; ++k) dst[m][k] = *(const PG8_LAS bf16x8*)(lds + PG8_SA(b, h) + aoff + m * 2048 + k * 1024); } while (0)
; #define PG8_LDB(dst, b, h) do { _Pragma("unroll") for (int n = 0; n < 2; ++n) _Pragma("unroll") for (int k = 0; k < 2; ++k) dst[n][k] = *(const PG8_LAS bf16x8*)(lds + PG8_SB(b, h) + boff + n * 2048 + k * 1024); } while (0)
; #define PG8_MMA(ai, bj, At, Bt) do { __builtin_amdgcn_s_setprio(1); _Pragma("unroll") for (int m = 0; m < 4; ++m) _Pragma("unroll") for (int n = 0; n < 2; ++n) _Pragma("unroll") for (int k = 0; k < 2; ++k) \
;         acc[ai][bj][m][n] = __builtin_amdgcn_mfma_f32_16x16x32_bf16(Bt[n][k], At[m][k], acc[ai][bj][m][n], 0, 0, 0); __builtin_amdgcn_s_setprio(0); } while (0)
; #define PG8_WAIT_V(n) asm volatile("s_waitcnt vmcnt(" #n ")" ::: "memory")
; #define PG8_WAIT_L(n) asm volatile("s_waitcnt lgkmcnt(" #n ")" ::: "memory")
; #define PG8_BAR __builtin_amdgcn_s_barrier()
; template <class Epi, class Sched, bool ALIGN_EPI = false, bool SP2 = false>
; __device__ __forceinline__ void gemm_phase(PG8_LAS unsigned char* lds, const Gemm g, const Sched& S, const Epi& E, const int wv) {
;     ...
;         for (int t = 0; t < nt; t += 2) {
;             const bool last = (t == nt - 2);
;             const char* a1 = cA + (size_t)(t + 1) * kstep;
;             const char* a2 = last ? nA : cA + (size_t)(t + 2) * kstep; const char* b2 = last ? nB : cB + (size_t)(t + 2) * kstep;
;             const char* a3 = a2 + kstep; const char* b3 = b2 + kstep;
;             if (last && has_next) S.a_ready(nxt);
;             if constexpr (SP2) {
;             PG8_LDB(B0, 0, 0); PG8_LDB(B1, 0, 1); PG8_SCHED; PG8_LDA(At, 0, 0); PG8_STAGE(PG8_SA(1, 1), a1 + hstepA, voffA);
;             PG8_WAIT_V(8); PG8_WAIT_L(0); PG8_BAR; PG8_MMA(0, 0, At, B0); PG8_MMA(0, 1, At, B1); PG8_BAR; PG8_SCHED;
;             PG8_LDA(At, 0, 1); PG8_STAGE(PG8_SB(0, 0), b2, voffB); PG8_STAGE(PG8_SB(0, 1), b2 + hstepB, voffB); PG8_STAGE(PG8_SA(0, 0), a2, voffA);
.LBB0_699:
	s_add_i32 s72, s54, 2
	s_add_u32 s73, s44, 0xfff80080
	s_addc_u32 s55, s45, -1
	s_add_i32 s76, 0, 0x10000
	s_cmp_eq_u32 s66, s54
	s_cselect_b32 s55, s31, s55
	s_cselect_b32 s54, s71, s73
	v_add_u32_e32 v115, s76, v230
	s_cselect_b32 s75, s13, s57
	s_cselect_b32 s74, s12, s56
	s_add_i32 s73, 0, 0x14000
	ds_read_b128 v[126:129], v115
	ds_read_b128 v[138:141], v115 offset:1024
	ds_read_b128 v[142:145], v115 offset:2048
	ds_read_b128 v[146:149], v115 offset:3072
	v_add_u32_e32 v115, s73, v230
	ds_read_b128 v[150:153], v115
	ds_read_b128 v[154:157], v115 offset:1024
	ds_read_b128 v[158:161], v115 offset:2048
	ds_read_b128 v[162:165], v115 offset:3072
	s_add_i32 m0, s59, 0xc000
	ds_read_b128 v[166:169], v235
	ds_read_b128 v[170:173], v235 offset:1024
	ds_read_b128 v[174:177], v235 offset:2048
	ds_read_b128 v[178:181], v235 offset:3072
	ds_read_b128 v[182:185], v235 offset:4096
	ds_read_b128 v[204:207], v235 offset:5120
	ds_read_b128 v[208:211], v235 offset:6144
	ds_read_b128 v[212:215], v235 offset:7168
	global_load_lds_dwordx4 v200, s[44:45]
	s_add_i32 m0, s59, 0xe000
	s_nop 0
	global_load_lds_dwordx4 v202, s[44:45]
	s_waitcnt vmcnt(8)
	s_waitcnt lgkmcnt(0)
	s_barrier
	s_waitcnt lgkmcnt(0)
	v_mfma_f32_16x16x32_bf16 v[134:137], v[126:129], v[166:169], v[134:137]
	v_mfma_f32_16x16x32_bf16 v[130:133], v[142:145], v[166:169], v[130:133]
	v_mfma_f32_16x16x32_bf16 v[110:113], v[126:129], v[174:177], v[110:113]
	v_mfma_f32_16x16x32_bf16 v[106:109], v[142:145], v[174:177], v[106:109]
	v_mfma_f32_16x16x32_bf16 v[94:97], v[126:129], v[182:185], v[94:97]
	v_mfma_f32_16x16x32_bf16 v[90:93], v[142:145], v[182:185], v[90:93]
	v_mfma_f32_16x16x32_bf16 v[78:81], v[126:129], v[208:211], v[78:81]
	v_mfma_f32_16x16x32_bf16 v[74:77], v[142:145], v[208:211], v[74:77]
	v_mfma_f32_16x16x32_bf16 v[134:137], v[138:141], v[170:173], v[134:137]
	v_mfma_f32_16x16x32_bf16 v[130:133], v[146:149], v[170:173], v[130:133]
	v_mfma_f32_16x16x32_bf16 v[110:113], v[138:141], v[178:181], v[110:113]
	v_mfma_f32_16x16x32_bf16 v[106:109], v[146:149], v[178:181], v[106:109]
	v_mfma_f32_16x16x32_bf16 v[94:97], v[138:141], v[204:207], v[94:97]
	v_mfma_f32_16x16x32_bf16 v[90:93], v[146:149], v[204:207], v[90:93]
	v_mfma_f32_16x16x32_bf16 v[78:81], v[138:141], v[212:215], v[78:81]
	v_mfma_f32_16x16x32_bf16 v[74:77], v[146:149], v[212:215], v[74:77]
	v_mfma_f32_16x16x32_bf16 v[122:125], v[150:153], v[166:169], v[122:125]
	v_mfma_f32_16x16x32_bf16 v[116:119], v[158:161], v[166:169], v[118:121]
	v_mfma_f32_16x16x32_bf16 v[102:105], v[150:153], v[174:177], v[102:105]
	v_mfma_f32_16x16x32_bf16 v[98:101], v[158:161], v[174:177], v[98:101]
	v_mfma_f32_16x16x32_bf16 v[86:89], v[150:153], v[182:185], v[86:89]
	v_mfma_f32_16x16x32_bf16 v[82:85], v[158:161], v[182:185], v[82:85]
	v_mfma_f32_16x16x32_bf16 v[70:73], v[150:153], v[208:211], v[70:73]
	v_mfma_f32_16x16x32_bf16 v[66:69], v[158:161], v[208:211], v[66:69]
	v_mfma_f32_16x16x32_bf16 v[122:125], v[154:157], v[170:173], v[122:125]
	v_mfma_f32_16x16x32_bf16 v[116:119], v[162:165], v[170:173], v[116:119]
	v_mfma_f32_16x16x32_bf16 v[102:105], v[154:157], v[178:181], v[102:105]
	v_mfma_f32_16x16x32_bf16 v[98:101], v[162:165], v[178:181], v[98:101]
	v_mfma_f32_16x16x32_bf16 v[86:89], v[154:157], v[204:207], v[86:89]
	v_mfma_f32_16x16x32_bf16 v[82:85], v[162:165], v[204:207], v[82:85]
	v_mfma_f32_16x16x32_bf16 v[70:73], v[154:157], v[212:215], v[70:73]
	v_mfma_f32_16x16x32_bf16 v[66:69], v[162:165], v[212:215], v[66:69]
	s_barrier
	s_add_i32 s76, s76, s53
	v_lshl_add_u64 v[216:217], s[74:75], 0, v[0:1]
	s_mov_b32 m0, s76
	ds_read_b128 v[166:169], v235 offset:16384
	ds_read_b128 v[170:173], v235 offset:17408
	ds_read_b128 v[174:177], v235 offset:18432
	ds_read_b128 v[178:181], v235 offset:19456
	ds_read_b128 v[182:185], v235 offset:20480
	ds_read_b128 v[204:207], v235 offset:21504
	ds_read_b128 v[208:211], v235 offset:22528
	ds_read_b128 v[212:215], v235 offset:23552
	global_load_lds_dwordx4 v[216:217], off
	s_add_i32 m0, s76, 0x2000
	v_lshl_add_u64 v[218:219], s[74:75], 0, v[198:199]
	s_add_u32 s74, s74, s34
	s_addc_u32 s75, s75, s35
	s_add_i32 s73, s73, s53
	global_load_lds_dwordx4 v[218:219], off
	v_lshl_add_u64 v[236:237], s[74:75], 0, v[0:1]
	s_mov_b32 m0, s73
	v_lshl_add_u64 v[238:239], s[74:75], 0, v[198:199]
	global_load_lds_dwordx4 v[236:237], off
	s_add_i32 m0, s73, 0x2000
	v_lshl_add_u64 v[240:241], s[54:55], 0, v[194:195]
	global_load_lds_dwordx4 v[238:239], off
	s_mov_b32 m0, s59
	v_lshl_add_u64 v[242:243], s[54:55], 0, v[196:197]
	global_load_lds_dwordx4 v[240:241], off
	s_mov_b32 m0, s60
	s_nop 0
	global_load_lds_dwordx4 v[242:243], off
	s_waitcnt vmcnt(8)
	s_waitcnt lgkmcnt(0)
	s_barrier
; #define PG8_STAGE(bufoff, gbase, voff) do { _Pragma("unroll") for (int _i = 0; _i < 2; ++_i) \
;         __builtin_amdgcn_global_load_lds((const unsigned*)((const char*)(gbase) + (voff)[_i]), (PG8_LAS unsigned*)(lds + (bufoff) + ldsw + _i * 8192), 16, 0, 0); } while (0)
; #define PG8_LDA(dst, b, h) do { _Pragma("unroll") for (int m = 0; m < 4; ++m) _Pragma("unroll") for (int k = 0; k < 2; ++k) dst[m][k] = *(const PG8_LAS bf16x8*)(lds + PG8_SA(b, h) + aoff + m * 2048 + k * 1024); } while (0)
; #define PG8_LDB(dst, b, h) do { _Pragma("unroll") for (int n = 0; n < 2; ++n) _Pragma("unroll") for (int k = 0; k < 2; ++k) dst[n][k] = *(const PG8_LAS bf16x8*)(lds + PG8_SB(b, h) + boff + n * 2048 + k * 1024); } while (0)
; #define PG8_MMA(ai, bj, At, Bt) do { __builtin_amdgcn_s_setprio(1); _Pragma("unroll") for (int m = 0; m < 4; ++m) _Pragma("unroll") for (int n = 0; n < 2; ++n) _Pragma("unroll") for (int k = 0; k < 2; ++k) \
;         acc[ai][bj][m][n] = __builtin_amdgcn_mfma_f32_16x16x32_bf16(Bt[n][k], At[m][k], acc[ai][bj][m][n], 0, 0, 0); __builtin_amdgcn_s_setprio(0); } while (0)
; #define PG8_WAIT_V(n) asm volatile("s_waitcnt vmcnt(" #n ")" ::: "memory")
; #define PG8_WAIT_L(n) asm volatile("s_waitcnt lgkmcnt(" #n ")" ::: "memory")
; #define PG8_BAR __builtin_amdgcn_s_barrier()
; #define PG8_SCHED __builtin_amdgcn_sched_barrier(0)
; template <class Epi, class Sched, bool ALIGN_EPI = false, bool SP2 = false>
; __device__ __forceinline__ void gemm_phase(PG8_LAS unsigned char* lds, const Gemm g, const Sched& S, const Epi& E, const int wv) {
;     ...
;             PG8_WAIT_V(8); PG8_WAIT_L(0); PG8_BAR; PG8_MMA(1, 0, At, B0); PG8_MMA(1, 1, At, B1); PG8_BAR; PG8_SCHED;
;             PG8_LDB(B0, 1, 0); PG8_LDB(B1, 1, 1); PG8_SCHED; PG8_LDA(At, 1, 0); PG8_STAGE(PG8_SA(0, 1), a2 + hstepA, voffA);
;             PG8_WAIT_V(8); PG8_WAIT_L(0); PG8_BAR; PG8_MMA(0, 0, At, B0); PG8_MMA(0, 1, At, B1); PG8_BAR; PG8_SCHED;
	s_waitcnt lgkmcnt(0)
	v_mfma_f32_16x16x32_bf16 v[62:65], v[126:129], v[166:169], v[62:65]
	v_mfma_f32_16x16x32_bf16 v[58:61], v[142:145], v[166:169], v[58:61]
	v_mfma_f32_16x16x32_bf16 v[46:49], v[126:129], v[174:177], v[46:49]
	v_mfma_f32_16x16x32_bf16 v[42:45], v[142:145], v[174:177], v[42:45]
	v_mfma_f32_16x16x32_bf16 v[30:33], v[126:129], v[182:185], v[30:33]
	v_mfma_f32_16x16x32_bf16 v[26:29], v[142:145], v[182:185], v[26:29]
	v_mfma_f32_16x16x32_bf16 v[14:17], v[126:129], v[208:211], v[14:17]
	v_mfma_f32_16x16x32_bf16 v[10:13], v[142:145], v[208:211], v[10:13]
	v_mfma_f32_16x16x32_bf16 v[62:65], v[138:141], v[170:173], v[62:65]
	v_mfma_f32_16x16x32_bf16 v[58:61], v[146:149], v[170:173], v[58:61]
	v_mfma_f32_16x16x32_bf16 v[46:49], v[138:141], v[178:181], v[46:49]
	v_mfma_f32_16x16x32_bf16 v[42:45], v[146:149], v[178:181], v[42:45]
	v_mfma_f32_16x16x32_bf16 v[30:33], v[138:141], v[204:207], v[30:33]
	v_mfma_f32_16x16x32_bf16 v[26:29], v[146:149], v[204:207], v[26:29]
	v_mfma_f32_16x16x32_bf16 v[14:17], v[138:141], v[212:215], v[14:17]
	v_mfma_f32_16x16x32_bf16 v[10:13], v[146:149], v[212:215], v[10:13]
	v_mfma_f32_16x16x32_bf16 v[54:57], v[150:153], v[166:169], v[54:57]
	v_mfma_f32_16x16x32_bf16 v[50:53], v[158:161], v[166:169], v[50:53]
	v_mfma_f32_16x16x32_bf16 v[38:41], v[150:153], v[174:177], v[38:41]
	v_mfma_f32_16x16x32_bf16 v[34:37], v[158:161], v[174:177], v[34:37]
	v_mfma_f32_16x16x32_bf16 v[22:25], v[150:153], v[182:185], v[22:25]
	v_mfma_f32_16x16x32_bf16 v[18:21], v[158:161], v[182:185], v[18:21]
	v_mfma_f32_16x16x32_bf16 v[6:9], v[150:153], v[208:211], v[6:9]
	v_mfma_f32_16x16x32_bf16 v[2:5], v[158:161], v[208:211], v[2:5]
	v_mfma_f32_16x16x32_bf16 v[54:57], v[154:157], v[170:173], v[54:57]
	v_mfma_f32_16x16x32_bf16 v[50:53], v[162:165], v[170:173], v[50:53]
	v_mfma_f32_16x16x32_bf16 v[38:41], v[154:157], v[178:181], v[38:41]
	v_mfma_f32_16x16x32_bf16 v[34:37], v[162:165], v[178:181], v[34:37]
	v_mfma_f32_16x16x32_bf16 v[22:25], v[154:157], v[204:207], v[22:25]
	v_mfma_f32_16x16x32_bf16 v[18:21], v[162:165], v[204:207], v[18:21]
	v_mfma_f32_16x16x32_bf16 v[6:9], v[154:157], v[212:215], v[6:9]
	v_mfma_f32_16x16x32_bf16 v[2:5], v[162:165], v[212:215], v[2:5]
	s_barrier
	s_add_i32 s73, 0, 0x18000
	v_add_u32_e32 v115, s73, v230
	s_add_i32 s74, 0, 0x1c000
	ds_read_b128 v[126:129], v115
	ds_read_b128 v[138:141], v115 offset:1024
	ds_read_b128 v[142:145], v115 offset:2048
	ds_read_b128 v[146:149], v115 offset:3072
	v_add_u32_e32 v115, s74, v230
	ds_read_b128 v[150:153], v115
	ds_read_b128 v[154:157], v115 offset:1024
	ds_read_b128 v[158:161], v115 offset:2048
	ds_read_b128 v[162:165], v115 offset:3072
	s_add_u32 s54, s54, 0x80000
	s_addc_u32 s55, s55, 0
	s_mov_b32 m0, s61
	ds_read_b128 v[166:169], v235 offset:32768
	ds_read_b128 v[170:173], v235 offset:33792
	ds_read_b128 v[174:177], v235 offset:34816
	ds_read_b128 v[178:181], v235 offset:35840
	ds_read_b128 v[182:185], v235 offset:36864
	ds_read_b128 v[204:207], v235 offset:37888
	ds_read_b128 v[208:211], v235 offset:38912
	ds_read_b128 v[212:215], v235 offset:39936
	global_load_lds_dwordx4 v194, s[54:55]
	s_mov_b32 m0, s62
	s_nop 0
	global_load_lds_dwordx4 v196, s[54:55]
	s_waitcnt vmcnt(8)
	s_waitcnt lgkmcnt(0)
	s_barrier
	s_waitcnt lgkmcnt(0)
	v_mfma_f32_16x16x32_bf16 v[134:137], v[126:129], v[166:169], v[134:137]
	v_mfma_f32_16x16x32_bf16 v[130:133], v[142:145], v[166:169], v[130:133]
	v_mfma_f32_16x16x32_bf16 v[110:113], v[126:129], v[174:177], v[110:113]
	v_mfma_f32_16x16x32_bf16 v[106:109], v[142:145], v[174:177], v[106:109]
	v_mfma_f32_16x16x32_bf16 v[94:97], v[126:129], v[182:185], v[94:97]
	v_mfma_f32_16x16x32_bf16 v[90:93], v[142:145], v[182:185], v[90:93]
	v_mfma_f32_16x16x32_bf16 v[78:81], v[126:129], v[208:211], v[78:81]
	v_mfma_f32_16x16x32_bf16 v[74:77], v[142:145], v[208:211], v[74:77]
	v_mfma_f32_16x16x32_bf16 v[134:137], v[138:141], v[170:173], v[134:137]
	v_mfma_f32_16x16x32_bf16 v[130:133], v[146:149], v[170:173], v[130:133]
	v_mfma_f32_16x16x32_bf16 v[110:113], v[138:141], v[178:181], v[110:113]
	v_mfma_f32_16x16x32_bf16 v[106:109], v[146:149], v[178:181], v[106:109]
	v_mfma_f32_16x16x32_bf16 v[94:97], v[138:141], v[204:207], v[94:97]
	v_mfma_f32_16x16x32_bf16 v[90:93], v[146:149], v[204:207], v[90:93]
	v_mfma_f32_16x16x32_bf16 v[78:81], v[138:141], v[212:215], v[78:81]
	v_mfma_f32_16x16x32_bf16 v[74:77], v[146:149], v[212:215], v[74:77]
	v_mfma_f32_16x16x32_bf16 v[120:123], v[150:153], v[166:169], v[122:125]
	v_mfma_f32_16x16x32_bf16 v[116:119], v[158:161], v[166:169], v[116:119]
	v_mfma_f32_16x16x32_bf16 v[102:105], v[150:153], v[174:177], v[102:105]
	v_mfma_f32_16x16x32_bf16 v[98:101], v[158:161], v[174:177], v[98:101]
	v_mfma_f32_16x16x32_bf16 v[86:89], v[150:153], v[182:185], v[86:89]
	v_mfma_f32_16x16x32_bf16 v[82:85], v[158:161], v[182:185], v[82:85]
	v_mfma_f32_16x16x32_bf16 v[70:73], v[150:153], v[208:211], v[70:73]
	v_mfma_f32_16x16x32_bf16 v[66:69], v[158:161], v[208:211], v[66:69]
	v_mfma_f32_16x16x32_bf16 v[122:125], v[154:157], v[170:173], v[120:123]
	v_mfma_f32_16x16x32_bf16 v[118:121], v[162:165], v[170:173], v[116:119]
	v_mfma_f32_16x16x32_bf16 v[102:105], v[154:157], v[178:181], v[102:105]
	v_mfma_f32_16x16x32_bf16 v[98:101], v[162:165], v[178:181], v[98:101]
	v_mfma_f32_16x16x32_bf16 v[86:89], v[154:157], v[204:207], v[86:89]
	v_mfma_f32_16x16x32_bf16 v[82:85], v[162:165], v[204:207], v[82:85]
	v_mfma_f32_16x16x32_bf16 v[70:73], v[154:157], v[212:215], v[70:73]
	v_mfma_f32_16x16x32_bf16 v[66:69], v[162:165], v[212:215], v[66:69]
	s_barrier
; #define PG8_STAGE(bufoff, gbase, voff) do { _Pragma("unroll") for (int _i = 0; _i < 2; ++_i) \
;         __builtin_amdgcn_global_load_lds((const unsigned*)((const char*)(gbase) + (voff)[_i]), (PG8_LAS unsigned*)(lds + (bufoff) + ldsw + _i * 8192), 16, 0, 0); } while (0)
; #define PG8_LDA(dst, b, h) do { _Pragma("unroll") for (int m = 0; m < 4; ++m) _Pragma("unroll") for (int k = 0; k < 2; ++k) dst[m][k] = *(const PG8_LAS bf16x8*)(lds + PG8_SA(b, h) + aoff + m * 2048 + k * 1024); } while (0)
; #define PG8_MMA(ai, bj, At, Bt) do { __builtin_amdgcn_s_setprio(1); _Pragma("unroll") for (int m = 0; m < 4; ++m) _Pragma("unroll") for (int n = 0; n < 2; ++n) _Pragma("unroll") for (int k = 0; k < 2; ++k) \
;         acc[ai][bj][m][n] = __builtin_amdgcn_mfma_f32_16x16x32_bf16(Bt[n][k], At[m][k], acc[ai][bj][m][n], 0, 0, 0); __builtin_amdgcn_s_setprio(0); } while (0)
; #define PG8_WAIT_V(n) asm volatile("s_waitcnt vmcnt(" #n ")" ::: "memory")
; #define PG8_WAIT_L(n) asm volatile("s_waitcnt lgkmcnt(" #n ")" ::: "memory")
; #define PG8_BAR __builtin_amdgcn_s_barrier()
; #define PG8_SCHED __builtin_amdgcn_sched_barrier(0)
; template <class Epi, class Sched, bool ALIGN_EPI = false, bool SP2 = false>
; __device__ __forceinline__ void gemm_phase(PG8_LAS unsigned char* lds, const Gemm g, const Sched& S, const Epi& E, const int wv) {
;     ...
;         for (int t = 0; t < nt; t += 2) {
;             const bool last = (t == nt - 2);
;             const char* a1 = cA + (size_t)(t + 1) * kstep;
;             const char* a2 = last ? nA : cA + (size_t)(t + 2) * kstep; const char* b2 = last ? nB : cB + (size_t)(t + 2) * kstep;
;     ...
;             PG8_LDA(At, 1, 1); PG8_STAGE(PG8_SB(1, 0), b3, voffB); PG8_STAGE(PG8_SB(1, 1), b3 + hstepB, voffB); PG8_STAGE(PG8_SA(1, 0), a3, voffA);
;             PG8_WAIT_V(8); PG8_WAIT_L(0); PG8_BAR; PG8_MMA(1, 0, At, B0); PG8_MMA(1, 1, At, B1); PG8_BAR; PG8_SCHED;
	s_add_i32 s54, s73, s53
	s_add_i32 m0, s54, 0xffffff80
	ds_read_b128 v[166:169], v235 offset:49152
	ds_read_b128 v[170:173], v235 offset:50176
	ds_read_b128 v[174:177], v235 offset:51200
	ds_read_b128 v[178:181], v235 offset:52224
	ds_read_b128 v[182:185], v235 offset:53248
	ds_read_b128 v[204:207], v235 offset:54272
	ds_read_b128 v[208:211], v235 offset:55296
	ds_read_b128 v[212:215], v235 offset:56320
	global_load_lds_dwordx4 v[216:217], off offset:128
	s_add_i32 m0, s54, 0x1f80
	s_add_i32 s54, s74, s53
	global_load_lds_dwordx4 v[218:219], off offset:128
	s_add_i32 m0, s54, 0xffffff80
	s_nop 0
	global_load_lds_dwordx4 v[236:237], off offset:128
	s_add_i32 m0, s54, 0x1f80
	s_nop 0
	global_load_lds_dwordx4 v[238:239], off offset:128
	s_add_i32 m0, s64, 0xffffff80
	s_nop 0
	global_load_lds_dwordx4 v[240:241], off offset:128
	s_add_i32 m0, s65, 0xffffff80
	s_nop 0
	global_load_lds_dwordx4 v[242:243], off offset:128
	s_waitcnt vmcnt(8)
	s_waitcnt lgkmcnt(0)
	s_barrier
	s_waitcnt lgkmcnt(0)
	v_mfma_f32_16x16x32_bf16 v[62:65], v[126:129], v[166:169], v[62:65]
	v_mfma_f32_16x16x32_bf16 v[58:61], v[142:145], v[166:169], v[58:61]
	v_mfma_f32_16x16x32_bf16 v[46:49], v[126:129], v[174:177], v[46:49]
	v_mfma_f32_16x16x32_bf16 v[42:45], v[142:145], v[174:177], v[42:45]
	v_mfma_f32_16x16x32_bf16 v[30:33], v[126:129], v[182:185], v[30:33]
	v_mfma_f32_16x16x32_bf16 v[26:29], v[142:145], v[182:185], v[26:29]
	v_mfma_f32_16x16x32_bf16 v[14:17], v[126:129], v[208:211], v[14:17]
	v_mfma_f32_16x16x32_bf16 v[10:13], v[142:145], v[208:211], v[10:13]
	v_mfma_f32_16x16x32_bf16 v[62:65], v[138:141], v[170:173], v[62:65]
	v_mfma_f32_16x16x32_bf16 v[58:61], v[146:149], v[170:173], v[58:61]
	v_mfma_f32_16x16x32_bf16 v[46:49], v[138:141], v[178:181], v[46:49]
	v_mfma_f32_16x16x32_bf16 v[42:45], v[146:149], v[178:181], v[42:45]
	v_mfma_f32_16x16x32_bf16 v[30:33], v[138:141], v[204:207], v[30:33]
	v_mfma_f32_16x16x32_bf16 v[26:29], v[146:149], v[204:207], v[26:29]
	v_mfma_f32_16x16x32_bf16 v[14:17], v[138:141], v[212:215], v[14:17]
	v_mfma_f32_16x16x32_bf16 v[10:13], v[146:149], v[212:215], v[10:13]
	v_mfma_f32_16x16x32_bf16 v[54:57], v[150:153], v[166:169], v[54:57]
	v_mfma_f32_16x16x32_bf16 v[50:53], v[158:161], v[166:169], v[50:53]
	v_mfma_f32_16x16x32_bf16 v[38:41], v[150:153], v[174:177], v[38:41]
	v_mfma_f32_16x16x32_bf16 v[34:37], v[158:161], v[174:177], v[34:37]
	v_mfma_f32_16x16x32_bf16 v[22:25], v[150:153], v[182:185], v[22:25]
	v_mfma_f32_16x16x32_bf16 v[18:21], v[158:161], v[182:185], v[18:21]
	v_mfma_f32_16x16x32_bf16 v[6:9], v[150:153], v[208:211], v[6:9]
	v_mfma_f32_16x16x32_bf16 v[2:5], v[158:161], v[208:211], v[2:5]
	v_mfma_f32_16x16x32_bf16 v[54:57], v[154:157], v[170:173], v[54:57]
	v_mfma_f32_16x16x32_bf16 v[50:53], v[162:165], v[170:173], v[50:53]
	v_mfma_f32_16x16x32_bf16 v[38:41], v[154:157], v[178:181], v[38:41]
	v_mfma_f32_16x16x32_bf16 v[34:37], v[162:165], v[178:181], v[34:37]
	v_mfma_f32_16x16x32_bf16 v[22:25], v[154:157], v[204:207], v[22:25]
	v_mfma_f32_16x16x32_bf16 v[18:21], v[162:165], v[204:207], v[18:21]
	v_mfma_f32_16x16x32_bf16 v[6:9], v[154:157], v[212:215], v[6:9]
	v_mfma_f32_16x16x32_bf16 v[2:5], v[162:165], v[212:215], v[2:5]
	s_barrier
	s_add_u32 s44, s44, 0x100
	s_addc_u32 s45, s45, 0
	s_add_u32 s56, s56, 0x100
	s_addc_u32 s57, s57, 0
	s_cmp_ge_i32 s72, s63
	s_mov_b32 s54, s72
	s_cbranch_scc0 .LBB0_699
	s_movk_i32 s75, 0x2000
	s_mov_b32 s72, 0x10000
	s_mov_b32 s73, 0x12000
	s_mov_b32 s74, 0x14000
	s_mov_b32 s71, 0x3f317217
	s_and_b64 vcc, exec, s[48:49]
	s_cbranch_vccz .LBB0_673

; #define PG8_STAGE(bufoff, gbase, voff) do { _Pragma("unroll") for (int _i = 0; _i < 2; ++_i) \
;         __builtin_amdgcn_global_load_lds((const unsigned*)((const char*)(gbase) + (voff)[_i]), (PG8_LAS unsigned*)(lds + (bufoff) + ldsw + _i * 8192), 16, 0, 0); } while (0)
; #define PG8_LDA(dst, b, h) do { _Pragma("unroll") for (int m = 0; m < 4; ++m) _Pragma("unroll") for (int k = 0; k < 2; ++k) dst[m][k] = *(const PG8_LAS bf16x8*)(lds + PG8_SA(b, h) + aoff + m * 2048 + k * 1024); } while (0)
; #define PG8_LDB(dst, b, h) do { _Pragma("unroll") for (int n = 0; n < 2; ++n) _Pragma("unroll") for (int k = 0; k < 2; ++k) dst[n][k] = *(const PG8_LAS bf16x8*)(lds + PG8_SB(b, h) + boff + n * 2048 + k * 1024); } while (0)
; #define PG8_MMA(ai, bj, At, Bt) do { __builtin_amdgcn_s_setprio(1); _Pragma("unroll") for (int m = 0; m < 4; ++m) _Pragma("unroll") for (int n = 0; n < 2; ++n) _Pragma("unroll") for (int k = 0; k < 2; ++k) \
;         acc[ai][bj][m][n] = __builtin_amdgcn_mfma_f32_16x16x32_bf16(Bt[n][k], At[m][k], acc[ai][bj][m][n], 0, 0, 0); __builtin_amdgcn_s_setprio(0); } while (0)
; #define PG8_WAIT_V(n) asm volatile("s_waitcnt vmcnt(" #n ")" ::: "memory")
; #define PG8_WAIT_L(n) asm volatile("s_waitcnt lgkmcnt(" #n ")" ::: "memory")
; #define PG8_BAR __builtin_amdgcn_s_barrier()
; template <class Epi, class Sched, bool ALIGN_EPI = false, bool SP2 = false>
; __device__ __forceinline__ void gemm_phase(PG8_LAS unsigned char* lds, const Gemm g, const Sched& S, const Epi& E, const int wv) {
;     ...
;         for (int t = 0; t < nt; t += 2) {
;             const bool last = (t == nt - 2);
;             const char* a1 = cA + (size_t)(t + 1) * kstep;
;             const char* a2 = last ? nA : cA + (size_t)(t + 2) * kstep; const char* b2 = last ? nB : cB + (size_t)(t + 2) * kstep;
;             const char* a3 = a2 + kstep; const char* b3 = b2 + kstep;
;             if (last && has_next) S.a_ready(nxt);
;             if constexpr (SP2) {
;             PG8_LDB(B0, 0, 0); PG8_LDB(B1, 0, 1); PG8_SCHED; PG8_LDA(At, 0, 0); PG8_STAGE(PG8_SA(1, 1), a1 + hstepA, voffA);
;             PG8_WAIT_V(8); PG8_WAIT_L(0); PG8_BAR; PG8_MMA(0, 0, At, B0); PG8_MMA(0, 1, At, B1); PG8_BAR; PG8_SCHED;
;             PG8_LDA(At, 0, 1); PG8_STAGE(PG8_SB(0, 0), b2, voffB); PG8_STAGE(PG8_SB(0, 1), b2 + hstepB, voffB); PG8_STAGE(PG8_SA(0, 0), a2, voffA);
.LBB0_809:
	s_add_i32 s52, s46, 2
	s_add_u32 s14, s48, 0x100
	s_addc_u32 s15, s49, 0
	s_add_i32 s53, 0, 0x10000
	s_cmp_eq_u32 s71, s46
	s_cselect_b32 s47, s11, s15
	s_cselect_b32 s46, s13, s14
	s_cselect_b32 s77, s87, s51
	s_cselect_b32 s76, s86, s35
	s_add_i32 s75, 0, 0x14000
	v_add_u32_e32 v150, s53, v208
	v_add_u32_e32 v166, s75, v208
	ds_read_b128 v[138:141], v150
	ds_read_b128 v[142:145], v150 offset:1024
	ds_read_b128 v[146:149], v150 offset:2048
	ds_read_b128 v[150:153], v150 offset:3072
	ds_read_b128 v[154:157], v166
	ds_read_b128 v[158:161], v166 offset:1024
	ds_read_b128 v[162:165], v166 offset:2048
	ds_read_b128 v[166:169], v166 offset:3072
	v_lshl_add_u64 v[190:191], s[48:49], 0, v[182:183]
	s_add_i32 m0, s63, 0xc000
	ds_read_b128 v[194:197], v211
	ds_read_b128 v[198:201], v211 offset:1024
	ds_read_b128 v[202:205], v211 offset:2048
	ds_read_b128 v[214:217], v211 offset:3072
	ds_read_b128 v[228:231], v211 offset:4096
	ds_read_b128 v[232:235], v211 offset:5120
	ds_read_b128 v[236:239], v211 offset:6144
	ds_read_b128 v[240:243], v211 offset:7168
	global_load_lds_dwordx4 v[190:191], off
	v_lshl_add_u64 v[190:191], s[48:49], 0, v[184:185]
	s_add_i32 m0, s63, 0xe000
	s_nop 0
	global_load_lds_dwordx4 v[190:191], off
	s_waitcnt vmcnt(8)
	s_waitcnt lgkmcnt(0)
	s_barrier
	s_waitcnt lgkmcnt(0)
	v_mfma_f32_16x16x32_bf16 v[118:121], v[138:141], v[194:197], v[118:121]
	v_mfma_f32_16x16x32_bf16 v[46:49], v[146:149], v[194:197], v[46:49]
	v_mfma_f32_16x16x32_bf16 v[110:113], v[138:141], v[202:205], v[110:113]
	v_mfma_f32_16x16x32_bf16 v[38:41], v[146:149], v[202:205], v[38:41]
	v_mfma_f32_16x16x32_bf16 v[134:137], v[138:141], v[228:231], v[134:137]
	v_mfma_f32_16x16x32_bf16 v[62:65], v[146:149], v[228:231], v[62:65]
	v_mfma_f32_16x16x32_bf16 v[130:133], v[138:141], v[236:239], v[130:133]
	v_mfma_f32_16x16x32_bf16 v[58:61], v[146:149], v[236:239], v[58:61]
	v_mfma_f32_16x16x32_bf16 v[118:121], v[142:145], v[198:201], v[118:121]
	v_mfma_f32_16x16x32_bf16 v[46:49], v[150:153], v[198:201], v[46:49]
	v_mfma_f32_16x16x32_bf16 v[110:113], v[142:145], v[214:217], v[110:113]
	v_mfma_f32_16x16x32_bf16 v[38:41], v[150:153], v[214:217], v[38:41]
	v_mfma_f32_16x16x32_bf16 v[134:137], v[142:145], v[232:235], v[134:137]
	v_mfma_f32_16x16x32_bf16 v[62:65], v[150:153], v[232:235], v[62:65]
	v_mfma_f32_16x16x32_bf16 v[130:133], v[142:145], v[240:243], v[130:133]
	v_mfma_f32_16x16x32_bf16 v[58:61], v[150:153], v[240:243], v[58:61]
	v_mfma_f32_16x16x32_bf16 v[114:117], v[154:157], v[194:197], v[114:117]
	v_mfma_f32_16x16x32_bf16 v[42:45], v[162:165], v[194:197], v[42:45]
	v_mfma_f32_16x16x32_bf16 v[106:109], v[154:157], v[202:205], v[106:109]
	v_mfma_f32_16x16x32_bf16 v[34:37], v[162:165], v[202:205], v[34:37]
	v_mfma_f32_16x16x32_bf16 v[126:129], v[154:157], v[228:231], v[126:129]
	v_mfma_f32_16x16x32_bf16 v[54:57], v[162:165], v[228:231], v[54:57]
	v_mfma_f32_16x16x32_bf16 v[122:125], v[154:157], v[236:239], v[122:125]
	v_mfma_f32_16x16x32_bf16 v[50:53], v[162:165], v[236:239], v[50:53]
	v_mfma_f32_16x16x32_bf16 v[114:117], v[158:161], v[198:201], v[114:117]
	v_mfma_f32_16x16x32_bf16 v[42:45], v[166:169], v[198:201], v[42:45]
	v_mfma_f32_16x16x32_bf16 v[106:109], v[158:161], v[214:217], v[106:109]
	v_mfma_f32_16x16x32_bf16 v[34:37], v[166:169], v[214:217], v[34:37]
	v_mfma_f32_16x16x32_bf16 v[126:129], v[158:161], v[232:235], v[126:129]
	v_mfma_f32_16x16x32_bf16 v[54:57], v[166:169], v[232:235], v[54:57]
	v_mfma_f32_16x16x32_bf16 v[122:125], v[158:161], v[240:243], v[122:125]
	v_mfma_f32_16x16x32_bf16 v[50:53], v[166:169], v[240:243], v[50:53]
	s_barrier
	s_add_i32 s48, s53, s62
	v_lshl_add_u64 v[190:191], s[76:77], 0, v[0:1]
	s_mov_b32 m0, s48
	ds_read_b128 v[194:197], v211 offset:16384
	ds_read_b128 v[198:201], v211 offset:17408
	ds_read_b128 v[202:205], v211 offset:18432
	ds_read_b128 v[214:217], v211 offset:19456
	ds_read_b128 v[228:231], v211 offset:20480
	ds_read_b128 v[232:235], v211 offset:21504
	ds_read_b128 v[236:239], v211 offset:22528
	ds_read_b128 v[240:243], v211 offset:23552
	global_load_lds_dwordx4 v[190:191], off
	s_add_i32 m0, s48, 0x2000
	s_add_u32 s48, s76, s16
	v_lshl_add_u64 v[192:193], s[76:77], 0, v[174:175]
	s_addc_u32 s49, s77, s17
	s_add_i32 s53, s75, s62
	global_load_lds_dwordx4 v[192:193], off
	v_lshl_add_u64 v[218:219], s[48:49], 0, v[0:1]
	s_mov_b32 m0, s53
	v_lshl_add_u64 v[244:245], s[48:49], 0, v[174:175]
	global_load_lds_dwordx4 v[218:219], off
	s_add_i32 m0, s53, 0x2000
	v_lshl_add_u64 v[246:247], s[46:47], 0, v[170:171]
	global_load_lds_dwordx4 v[244:245], off
	s_mov_b32 m0, s63
	v_lshl_add_u64 v[248:249], s[46:47], 0, v[172:173]
	global_load_lds_dwordx4 v[246:247], off
	s_mov_b32 m0, s64
	s_nop 0
	global_load_lds_dwordx4 v[248:249], off
	s_waitcnt vmcnt(8)
	s_waitcnt lgkmcnt(0)
	s_barrier
; #define PG8_STAGE(bufoff, gbase, voff) do { _Pragma("unroll") for (int _i = 0; _i < 2; ++_i) \
;         __builtin_amdgcn_global_load_lds((const unsigned*)((const char*)(gbase) + (voff)[_i]), (PG8_LAS unsigned*)(lds + (bufoff) + ldsw + _i * 8192), 16, 0, 0); } while (0)
; #define PG8_LDA(dst, b, h) do { _Pragma("unroll") for (int m = 0; m < 4; ++m) _Pragma("unroll") for (int k = 0; k < 2; ++k) dst[m][k] = *(const PG8_LAS bf16x8*)(lds + PG8_SA(b, h) + aoff + m * 2048 + k * 1024); } while (0)
; #define PG8_LDB(dst, b, h) do { _Pragma("unroll") for (int n = 0; n < 2; ++n) _Pragma("unroll") for (int k = 0; k < 2; ++k) dst[n][k] = *(const PG8_LAS bf16x8*)(lds + PG8_SB(b, h) + boff + n * 2048 + k * 1024); } while (0)
; #define PG8_MMA(ai, bj, At, Bt) do { __builtin_amdgcn_s_setprio(1); _Pragma("unroll") for (int m = 0; m < 4; ++m) _Pragma("unroll") for (int n = 0; n < 2; ++n) _Pragma("unroll") for (int k = 0; k < 2; ++k) \
;         acc[ai][bj][m][n] = __builtin_amdgcn_mfma_f32_16x16x32_bf16(Bt[n][k], At[m][k], acc[ai][bj][m][n], 0, 0, 0); __builtin_amdgcn_s_setprio(0); } while (0)
; #define PG8_WAIT_V(n) asm volatile("s_waitcnt vmcnt(" #n ")" ::: "memory")
; #define PG8_WAIT_L(n) asm volatile("s_waitcnt lgkmcnt(" #n ")" ::: "memory")
; #define PG8_BAR __builtin_amdgcn_s_barrier()
; #define PG8_SCHED __builtin_amdgcn_sched_barrier(0)
; template <class Epi, class Sched, bool ALIGN_EPI = false, bool SP2 = false>
; __device__ __forceinline__ void gemm_phase(PG8_LAS unsigned char* lds, const Gemm g, const Sched& S, const Epi& E, const int wv) {
;     ...
;             PG8_WAIT_V(8); PG8_WAIT_L(0); PG8_BAR; PG8_MMA(1, 0, At, B0); PG8_MMA(1, 1, At, B1); PG8_BAR; PG8_SCHED;
;             PG8_LDB(B0, 1, 0); PG8_LDB(B1, 1, 1); PG8_SCHED; PG8_LDA(At, 1, 0); PG8_STAGE(PG8_SA(0, 1), a2 + hstepA, voffA);
;             PG8_WAIT_V(8); PG8_WAIT_L(0); PG8_BAR; PG8_MMA(0, 0, At, B0); PG8_MMA(0, 1, At, B1); PG8_BAR; PG8_SCHED;
	s_waitcnt lgkmcnt(0)
	v_mfma_f32_16x16x32_bf16 v[86:89], v[138:141], v[194:197], v[86:89]
	v_mfma_f32_16x16x32_bf16 v[14:17], v[146:149], v[194:197], v[14:17]
	v_mfma_f32_16x16x32_bf16 v[70:73], v[138:141], v[202:205], v[70:73]
	v_mfma_f32_16x16x32_bf16 v[6:9], v[146:149], v[202:205], v[6:9]
	v_mfma_f32_16x16x32_bf16 v[102:105], v[138:141], v[228:231], v[102:105]
	v_mfma_f32_16x16x32_bf16 v[30:33], v[146:149], v[228:231], v[30:33]
	v_mfma_f32_16x16x32_bf16 v[98:101], v[138:141], v[236:239], v[98:101]
	v_mfma_f32_16x16x32_bf16 v[26:29], v[146:149], v[236:239], v[26:29]
	v_mfma_f32_16x16x32_bf16 v[86:89], v[142:145], v[198:201], v[86:89]
	v_mfma_f32_16x16x32_bf16 v[14:17], v[150:153], v[198:201], v[14:17]
	v_mfma_f32_16x16x32_bf16 v[70:73], v[142:145], v[214:217], v[70:73]
	v_mfma_f32_16x16x32_bf16 v[6:9], v[150:153], v[214:217], v[6:9]
	v_mfma_f32_16x16x32_bf16 v[102:105], v[142:145], v[232:235], v[102:105]
	v_mfma_f32_16x16x32_bf16 v[30:33], v[150:153], v[232:235], v[30:33]
	v_mfma_f32_16x16x32_bf16 v[98:101], v[142:145], v[240:243], v[98:101]
	v_mfma_f32_16x16x32_bf16 v[26:29], v[150:153], v[240:243], v[26:29]
	v_mfma_f32_16x16x32_bf16 v[82:85], v[154:157], v[194:197], v[82:85]
	v_mfma_f32_16x16x32_bf16 v[10:13], v[162:165], v[194:197], v[10:13]
	v_mfma_f32_16x16x32_bf16 v[66:69], v[154:157], v[202:205], v[66:69]
	v_mfma_f32_16x16x32_bf16 v[2:5], v[162:165], v[202:205], v[2:5]
	v_mfma_f32_16x16x32_bf16 v[94:97], v[154:157], v[228:231], v[94:97]
	v_mfma_f32_16x16x32_bf16 v[22:25], v[162:165], v[228:231], v[22:25]
	v_mfma_f32_16x16x32_bf16 v[90:93], v[154:157], v[236:239], v[90:93]
	v_mfma_f32_16x16x32_bf16 v[18:21], v[162:165], v[236:239], v[18:21]
	v_mfma_f32_16x16x32_bf16 v[82:85], v[158:161], v[198:201], v[82:85]
	v_mfma_f32_16x16x32_bf16 v[10:13], v[166:169], v[198:201], v[10:13]
	v_mfma_f32_16x16x32_bf16 v[66:69], v[158:161], v[214:217], v[66:69]
	v_mfma_f32_16x16x32_bf16 v[2:5], v[166:169], v[214:217], v[2:5]
	v_mfma_f32_16x16x32_bf16 v[94:97], v[158:161], v[232:235], v[94:97]
	v_mfma_f32_16x16x32_bf16 v[22:25], v[166:169], v[232:235], v[22:25]
	v_mfma_f32_16x16x32_bf16 v[90:93], v[158:161], v[240:243], v[90:93]
	v_mfma_f32_16x16x32_bf16 v[18:21], v[166:169], v[240:243], v[18:21]
	s_barrier
	s_add_i32 s48, 0, 0x18000
	s_add_i32 s49, 0, 0x1c000
	v_add_u32_e32 v150, s48, v208
	v_add_u32_e32 v166, s49, v208
	ds_read_b128 v[138:141], v150
	ds_read_b128 v[142:145], v150 offset:1024
	ds_read_b128 v[146:149], v150 offset:2048
	ds_read_b128 v[150:153], v150 offset:3072
	ds_read_b128 v[154:157], v166
	ds_read_b128 v[158:161], v166 offset:1024
	ds_read_b128 v[162:165], v166 offset:2048
	ds_read_b128 v[166:169], v166 offset:3072
	s_add_u32 s46, s46, 0x80000
	s_addc_u32 s47, s47, 0
	s_mov_b32 m0, s65
	ds_read_b128 v[194:197], v211 offset:32768
	ds_read_b128 v[198:201], v211 offset:33792
	ds_read_b128 v[202:205], v211 offset:34816
	ds_read_b128 v[214:217], v211 offset:35840
	ds_read_b128 v[228:231], v211 offset:36864
	ds_read_b128 v[232:235], v211 offset:37888
	ds_read_b128 v[236:239], v211 offset:38912
	ds_read_b128 v[240:243], v211 offset:39936
	global_load_lds_dwordx4 v170, s[46:47]
	s_mov_b32 m0, s66
	s_nop 0
	global_load_lds_dwordx4 v172, s[46:47]
	s_waitcnt vmcnt(8)
	s_waitcnt lgkmcnt(0)
	s_barrier
	s_waitcnt lgkmcnt(0)
	v_mfma_f32_16x16x32_bf16 v[118:121], v[138:141], v[194:197], v[118:121]
	v_mfma_f32_16x16x32_bf16 v[46:49], v[146:149], v[194:197], v[46:49]
	v_mfma_f32_16x16x32_bf16 v[110:113], v[138:141], v[202:205], v[110:113]
	v_mfma_f32_16x16x32_bf16 v[38:41], v[146:149], v[202:205], v[38:41]
	v_mfma_f32_16x16x32_bf16 v[134:137], v[138:141], v[228:231], v[134:137]
	v_mfma_f32_16x16x32_bf16 v[62:65], v[146:149], v[228:231], v[62:65]
	v_mfma_f32_16x16x32_bf16 v[130:133], v[138:141], v[236:239], v[130:133]
	v_mfma_f32_16x16x32_bf16 v[58:61], v[146:149], v[236:239], v[58:61]
	v_mfma_f32_16x16x32_bf16 v[118:121], v[142:145], v[198:201], v[118:121]
	v_mfma_f32_16x16x32_bf16 v[46:49], v[150:153], v[198:201], v[46:49]
	v_mfma_f32_16x16x32_bf16 v[110:113], v[142:145], v[214:217], v[110:113]
	v_mfma_f32_16x16x32_bf16 v[38:41], v[150:153], v[214:217], v[38:41]
	v_mfma_f32_16x16x32_bf16 v[134:137], v[142:145], v[232:235], v[134:137]
	v_mfma_f32_16x16x32_bf16 v[62:65], v[150:153], v[232:235], v[62:65]
	v_mfma_f32_16x16x32_bf16 v[130:133], v[142:145], v[240:243], v[130:133]
	v_mfma_f32_16x16x32_bf16 v[58:61], v[150:153], v[240:243], v[58:61]
	v_mfma_f32_16x16x32_bf16 v[114:117], v[154:157], v[194:197], v[114:117]
	v_mfma_f32_16x16x32_bf16 v[42:45], v[162:165], v[194:197], v[42:45]
	v_mfma_f32_16x16x32_bf16 v[106:109], v[154:157], v[202:205], v[106:109]
	v_mfma_f32_16x16x32_bf16 v[34:37], v[162:165], v[202:205], v[34:37]
	v_mfma_f32_16x16x32_bf16 v[126:129], v[154:157], v[228:231], v[126:129]
	v_mfma_f32_16x16x32_bf16 v[54:57], v[162:165], v[228:231], v[54:57]
	v_mfma_f32_16x16x32_bf16 v[122:125], v[154:157], v[236:239], v[122:125]
	v_mfma_f32_16x16x32_bf16 v[50:53], v[162:165], v[236:239], v[50:53]
	v_mfma_f32_16x16x32_bf16 v[114:117], v[158:161], v[198:201], v[114:117]
	v_mfma_f32_16x16x32_bf16 v[42:45], v[166:169], v[198:201], v[42:45]
	v_mfma_f32_16x16x32_bf16 v[106:109], v[158:161], v[214:217], v[106:109]
	v_mfma_f32_16x16x32_bf16 v[34:37], v[166:169], v[214:217], v[34:37]
	v_mfma_f32_16x16x32_bf16 v[126:129], v[158:161], v[232:235], v[126:129]
	v_mfma_f32_16x16x32_bf16 v[54:57], v[166:169], v[232:235], v[54:57]
	v_mfma_f32_16x16x32_bf16 v[122:125], v[158:161], v[240:243], v[122:125]
	v_mfma_f32_16x16x32_bf16 v[50:53], v[166:169], v[240:243], v[50:53]
	s_barrier
; #define PG8_STAGE(bufoff, gbase, voff) do { _Pragma("unroll") for (int _i = 0; _i < 2; ++_i) \
;         __builtin_amdgcn_global_load_lds((const unsigned*)((const char*)(gbase) + (voff)[_i]), (PG8_LAS unsigned*)(lds + (bufoff) + ldsw + _i * 8192), 16, 0, 0); } while (0)
; #define PG8_LDA(dst, b, h) do { _Pragma("unroll") for (int m = 0; m < 4; ++m) _Pragma("unroll") for (int k = 0; k < 2; ++k) dst[m][k] = *(const PG8_LAS bf16x8*)(lds + PG8_SA(b, h) + aoff + m * 2048 + k * 1024); } while (0)
; #define PG8_MMA(ai, bj, At, Bt) do { __builtin_amdgcn_s_setprio(1); _Pragma("unroll") for (int m = 0; m < 4; ++m) _Pragma("unroll") for (int n = 0; n < 2; ++n) _Pragma("unroll") for (int k = 0; k < 2; ++k) \
;         acc[ai][bj][m][n] = __builtin_amdgcn_mfma_f32_16x16x32_bf16(Bt[n][k], At[m][k], acc[ai][bj][m][n], 0, 0, 0); __builtin_amdgcn_s_setprio(0); } while (0)
; #define PG8_WAIT_V(n) asm volatile("s_waitcnt vmcnt(" #n ")" ::: "memory")
; #define PG8_WAIT_L(n) asm volatile("s_waitcnt lgkmcnt(" #n ")" ::: "memory")
; #define PG8_BAR __builtin_amdgcn_s_barrier()
; #define PG8_SCHED __builtin_amdgcn_sched_barrier(0)
; template <class Epi, class Sched, bool ALIGN_EPI = false, bool SP2 = false>
; __device__ __forceinline__ void gemm_phase(PG8_LAS unsigned char* lds, const Gemm g, const Sched& S, const Epi& E, const int wv) {
;     ...
;         for (int t = 0; t < nt; t += 2) {
;             const bool last = (t == nt - 2);
;             const char* a1 = cA + (size_t)(t + 1) * kstep;
;             const char* a2 = last ? nA : cA + (size_t)(t + 2) * kstep; const char* b2 = last ? nB : cB + (size_t)(t + 2) * kstep;
;     ...
;             PG8_LDA(At, 1, 1); PG8_STAGE(PG8_SB(1, 0), b3, voffB); PG8_STAGE(PG8_SB(1, 1), b3 + hstepB, voffB); PG8_STAGE(PG8_SA(1, 0), a3, voffA);
;             PG8_WAIT_V(8); PG8_WAIT_L(0); PG8_BAR; PG8_MMA(1, 0, At, B0); PG8_MMA(1, 1, At, B1); PG8_BAR; PG8_SCHED;
	s_add_i32 s46, s48, s62
	s_add_i32 m0, s46, 0xffffff80
	ds_read_b128 v[194:197], v211 offset:49152
	ds_read_b128 v[198:201], v211 offset:50176
	ds_read_b128 v[202:205], v211 offset:51200
	ds_read_b128 v[214:217], v211 offset:52224
	ds_read_b128 v[228:231], v211 offset:53248
	ds_read_b128 v[232:235], v211 offset:54272
	ds_read_b128 v[236:239], v211 offset:55296
	ds_read_b128 v[240:243], v211 offset:56320
	global_load_lds_dwordx4 v[190:191], off offset:128
	s_add_i32 m0, s46, 0x1f80
	s_add_i32 s46, s49, s62
	global_load_lds_dwordx4 v[192:193], off offset:128
	s_add_i32 m0, s46, 0xffffff80
	s_nop 0
	global_load_lds_dwordx4 v[218:219], off offset:128
	s_add_i32 m0, s46, 0x1f80
	s_nop 0
	global_load_lds_dwordx4 v[244:245], off offset:128
	s_add_i32 m0, s69, 0xffffff80
	s_nop 0
	global_load_lds_dwordx4 v[246:247], off offset:128
	s_add_i32 m0, s70, 0xffffff80
	s_nop 0
	global_load_lds_dwordx4 v[248:249], off offset:128
	s_waitcnt vmcnt(8)
	s_waitcnt lgkmcnt(0)
	s_barrier
	s_waitcnt lgkmcnt(0)
	v_mfma_f32_16x16x32_bf16 v[86:89], v[138:141], v[194:197], v[86:89]
	v_mfma_f32_16x16x32_bf16 v[14:17], v[146:149], v[194:197], v[14:17]
	v_mfma_f32_16x16x32_bf16 v[70:73], v[138:141], v[202:205], v[70:73]
	v_mfma_f32_16x16x32_bf16 v[6:9], v[146:149], v[202:205], v[6:9]
	v_mfma_f32_16x16x32_bf16 v[102:105], v[138:141], v[228:231], v[102:105]
	v_mfma_f32_16x16x32_bf16 v[30:33], v[146:149], v[228:231], v[30:33]
	v_mfma_f32_16x16x32_bf16 v[98:101], v[138:141], v[236:239], v[98:101]
	v_mfma_f32_16x16x32_bf16 v[26:29], v[146:149], v[236:239], v[26:29]
	v_mfma_f32_16x16x32_bf16 v[86:89], v[142:145], v[198:201], v[86:89]
	v_mfma_f32_16x16x32_bf16 v[14:17], v[150:153], v[198:201], v[14:17]
	v_mfma_f32_16x16x32_bf16 v[70:73], v[142:145], v[214:217], v[70:73]
	v_mfma_f32_16x16x32_bf16 v[6:9], v[150:153], v[214:217], v[6:9]
	v_mfma_f32_16x16x32_bf16 v[102:105], v[142:145], v[232:235], v[102:105]
	v_mfma_f32_16x16x32_bf16 v[30:33], v[150:153], v[232:235], v[30:33]
	v_mfma_f32_16x16x32_bf16 v[98:101], v[142:145], v[240:243], v[98:101]
	v_mfma_f32_16x16x32_bf16 v[26:29], v[150:153], v[240:243], v[26:29]
	v_mfma_f32_16x16x32_bf16 v[82:85], v[154:157], v[194:197], v[82:85]
	v_mfma_f32_16x16x32_bf16 v[10:13], v[162:165], v[194:197], v[10:13]
	v_mfma_f32_16x16x32_bf16 v[66:69], v[154:157], v[202:205], v[66:69]
	v_mfma_f32_16x16x32_bf16 v[2:5], v[162:165], v[202:205], v[2:5]
	v_mfma_f32_16x16x32_bf16 v[94:97], v[154:157], v[228:231], v[94:97]
	v_mfma_f32_16x16x32_bf16 v[22:25], v[162:165], v[228:231], v[22:25]
	v_mfma_f32_16x16x32_bf16 v[90:93], v[154:157], v[236:239], v[90:93]
	v_mfma_f32_16x16x32_bf16 v[18:21], v[162:165], v[236:239], v[18:21]
	v_mfma_f32_16x16x32_bf16 v[82:85], v[158:161], v[198:201], v[82:85]
	v_mfma_f32_16x16x32_bf16 v[10:13], v[166:169], v[198:201], v[10:13]
	v_mfma_f32_16x16x32_bf16 v[66:69], v[158:161], v[214:217], v[66:69]
	v_mfma_f32_16x16x32_bf16 v[2:5], v[166:169], v[214:217], v[2:5]
	v_mfma_f32_16x16x32_bf16 v[94:97], v[158:161], v[232:235], v[94:97]
	v_mfma_f32_16x16x32_bf16 v[22:25], v[166:169], v[232:235], v[22:25]
	v_mfma_f32_16x16x32_bf16 v[90:93], v[158:161], v[240:243], v[90:93]
	v_mfma_f32_16x16x32_bf16 v[18:21], v[166:169], v[240:243], v[18:21]
	s_barrier
	s_add_u32 s35, s35, 0x100
	s_addc_u32 s51, s51, 0
	s_cmp_ge_i32 s52, s67
	s_mov_b64 s[48:49], s[14:15]
	s_mov_b32 s46, s52
	s_cbranch_scc0 .LBB0_809
	s_movk_i32 s75, 0x2000
	s_movk_i32 s76, 0x3000
	s_and_b64 vcc, exec, s[30:31]
	s_cbranch_vccz .LBB0_784

; #define PG8_STAGE(bufoff, gbase, voff) do { _Pragma("unroll") for (int _i = 0; _i < 2; ++_i) \
;         __builtin_amdgcn_global_load_lds((const unsigned*)((const char*)(gbase) + (voff)[_i]), (PG8_LAS unsigned*)(lds + (bufoff) + ldsw + _i * 8192), 16, 0, 0); } while (0)
; #define PG8_LDA(dst, b, h) do { _Pragma("unroll") for (int m = 0; m < 4; ++m) _Pragma("unroll") for (int k = 0; k < 2; ++k) dst[m][k] = *(const PG8_LAS bf16x8*)(lds + PG8_SA(b, h) + aoff + m * 2048 + k * 1024); } while (0)
; #define PG8_LDB(dst, b, h) do { _Pragma("unroll") for (int n = 0; n < 2; ++n) _Pragma("unroll") for (int k = 0; k < 2; ++k) dst[n][k] = *(const PG8_LAS bf16x8*)(lds + PG8_SB(b, h) + boff + n * 2048 + k * 1024); } while (0)
; #define PG8_MMA(ai, bj, At, Bt) do { __builtin_amdgcn_s_setprio(1); _Pragma("unroll") for (int m = 0; m < 4; ++m) _Pragma("unroll") for (int n = 0; n < 2; ++n) _Pragma("unroll") for (int k = 0; k < 2; ++k) \
;         acc[ai][bj][m][n] = __builtin_amdgcn_mfma_f32_16x16x32_bf16(Bt[n][k], At[m][k], acc[ai][bj][m][n], 0, 0, 0); __builtin_amdgcn_s_setprio(0); } while (0)
; #define PG8_WAIT_V(n) asm volatile("s_waitcnt vmcnt(" #n ")" ::: "memory")
; #define PG8_WAIT_L(n) asm volatile("s_waitcnt lgkmcnt(" #n ")" ::: "memory")
; #define PG8_BAR __builtin_amdgcn_s_barrier()
; template <class Epi, class Sched, bool ALIGN_EPI = false, bool SP2 = false>
; __device__ __forceinline__ void gemm_phase(PG8_LAS unsigned char* lds, const Gemm g, const Sched& S, const Epi& E, const int wv) {
;     ...
;         for (int t = 0; t < nt; t += 2) {
;             const bool last = (t == nt - 2);
;             const char* a1 = cA + (size_t)(t + 1) * kstep;
;             const char* a2 = last ? nA : cA + (size_t)(t + 2) * kstep; const char* b2 = last ? nB : cB + (size_t)(t + 2) * kstep;
;             const char* a3 = a2 + kstep; const char* b3 = b2 + kstep;
;             if (last && has_next) S.a_ready(nxt);
;             if constexpr (SP2) {
;             PG8_LDB(B0, 0, 0); PG8_LDB(B1, 0, 1); PG8_SCHED; PG8_LDA(At, 0, 0); PG8_STAGE(PG8_SA(1, 1), a1 + hstepA, voffA);
;             PG8_WAIT_V(8); PG8_WAIT_L(0); PG8_BAR; PG8_MMA(0, 0, At, B0); PG8_MMA(0, 1, At, B1); PG8_BAR; PG8_SCHED;
;             PG8_LDA(At, 0, 1); PG8_STAGE(PG8_SB(0, 0), b2, voffB); PG8_STAGE(PG8_SB(0, 1), b2 + hstepB, voffB); PG8_STAGE(PG8_SA(0, 0), a2, voffA);
.LBB0_990:
	s_add_i32 s67, s44, 2
	s_add_u32 s34, s30, 0x100
	s_addc_u32 s35, s31, 0
	s_add_i32 s70, 0, 0x10000
	s_cmp_eq_u32 s59, s44
	s_cselect_b32 s45, s13, s35
	s_cselect_b32 s44, s12, s34
	s_cselect_b32 s69, s15, s66
	s_cselect_b32 s68, s14, s65
	s_add_i32 s71, 0, 0x14000
	v_add_u32_e32 v142, s70, v230
	v_add_u32_e32 v158, s71, v230
	ds_read_b128 v[114:117], v142
	ds_read_b128 v[126:129], v142 offset:1024
	ds_read_b128 v[138:141], v142 offset:2048
	ds_read_b128 v[142:145], v142 offset:3072
	ds_read_b128 v[146:149], v158
	ds_read_b128 v[150:153], v158 offset:1024
	ds_read_b128 v[154:157], v158 offset:2048
	ds_read_b128 v[158:161], v158 offset:3072
	v_lshl_add_u64 v[190:191], s[30:31], 0, v[200:201]
	s_add_i32 m0, s52, 0xc000
	ds_read_b128 v[162:165], v235
	ds_read_b128 v[166:169], v235 offset:1024
	ds_read_b128 v[170:173], v235 offset:2048
	ds_read_b128 v[174:177], v235 offset:3072
	ds_read_b128 v[178:181], v235 offset:4096
	ds_read_b128 v[182:185], v235 offset:5120
	ds_read_b128 v[204:207], v235 offset:6144
	ds_read_b128 v[208:211], v235 offset:7168
	global_load_lds_dwordx4 v[190:191], off
	v_lshl_add_u64 v[190:191], s[30:31], 0, v[202:203]
	s_add_i32 m0, s52, 0xe000
	s_nop 0
	global_load_lds_dwordx4 v[190:191], off
	s_waitcnt vmcnt(8)
	s_waitcnt lgkmcnt(0)
	s_barrier
	s_waitcnt lgkmcnt(0)
	v_mfma_f32_16x16x32_bf16 v[134:137], v[114:117], v[162:165], v[134:137]
	v_mfma_f32_16x16x32_bf16 v[130:133], v[138:141], v[162:165], v[130:133]
	v_mfma_f32_16x16x32_bf16 v[110:113], v[114:117], v[170:173], v[110:113]
	v_mfma_f32_16x16x32_bf16 v[106:109], v[138:141], v[170:173], v[106:109]
	v_mfma_f32_16x16x32_bf16 v[94:97], v[114:117], v[178:181], v[94:97]
	v_mfma_f32_16x16x32_bf16 v[90:93], v[138:141], v[178:181], v[90:93]
	v_mfma_f32_16x16x32_bf16 v[78:81], v[114:117], v[204:207], v[78:81]
	v_mfma_f32_16x16x32_bf16 v[74:77], v[138:141], v[204:207], v[74:77]
	v_mfma_f32_16x16x32_bf16 v[134:137], v[126:129], v[166:169], v[134:137]
	v_mfma_f32_16x16x32_bf16 v[130:133], v[142:145], v[166:169], v[130:133]
	v_mfma_f32_16x16x32_bf16 v[110:113], v[126:129], v[174:177], v[110:113]
	v_mfma_f32_16x16x32_bf16 v[106:109], v[142:145], v[174:177], v[106:109]
	v_mfma_f32_16x16x32_bf16 v[94:97], v[126:129], v[182:185], v[94:97]
	v_mfma_f32_16x16x32_bf16 v[90:93], v[142:145], v[182:185], v[90:93]
	v_mfma_f32_16x16x32_bf16 v[78:81], v[126:129], v[208:211], v[78:81]
	v_mfma_f32_16x16x32_bf16 v[74:77], v[142:145], v[208:211], v[74:77]
	v_mfma_f32_16x16x32_bf16 v[122:125], v[146:149], v[162:165], v[122:125]
	v_mfma_f32_16x16x32_bf16 v[118:121], v[154:157], v[162:165], v[118:121]
	v_mfma_f32_16x16x32_bf16 v[102:105], v[146:149], v[170:173], v[102:105]
	v_mfma_f32_16x16x32_bf16 v[98:101], v[154:157], v[170:173], v[98:101]
	v_mfma_f32_16x16x32_bf16 v[86:89], v[146:149], v[178:181], v[86:89]
	v_mfma_f32_16x16x32_bf16 v[82:85], v[154:157], v[178:181], v[82:85]
	v_mfma_f32_16x16x32_bf16 v[70:73], v[146:149], v[204:207], v[70:73]
	v_mfma_f32_16x16x32_bf16 v[66:69], v[154:157], v[204:207], v[66:69]
	v_mfma_f32_16x16x32_bf16 v[122:125], v[150:153], v[166:169], v[122:125]
	v_mfma_f32_16x16x32_bf16 v[118:121], v[158:161], v[166:169], v[118:121]
	v_mfma_f32_16x16x32_bf16 v[102:105], v[150:153], v[174:177], v[102:105]
	v_mfma_f32_16x16x32_bf16 v[98:101], v[158:161], v[174:177], v[98:101]
	v_mfma_f32_16x16x32_bf16 v[86:89], v[150:153], v[182:185], v[86:89]
	v_mfma_f32_16x16x32_bf16 v[82:85], v[158:161], v[182:185], v[82:85]
	v_mfma_f32_16x16x32_bf16 v[70:73], v[150:153], v[208:211], v[70:73]
	v_mfma_f32_16x16x32_bf16 v[66:69], v[158:161], v[208:211], v[66:69]
	s_barrier
	s_add_i32 s30, s70, s47
	v_lshl_add_u64 v[190:191], s[68:69], 0, v[0:1]
	s_mov_b32 m0, s30
	ds_read_b128 v[162:165], v235 offset:16384
	ds_read_b128 v[166:169], v235 offset:17408
	ds_read_b128 v[170:173], v235 offset:18432
	ds_read_b128 v[174:177], v235 offset:19456
	ds_read_b128 v[178:181], v235 offset:20480
	ds_read_b128 v[182:185], v235 offset:21504
	ds_read_b128 v[204:207], v235 offset:22528
	ds_read_b128 v[208:211], v235 offset:23552
	global_load_lds_dwordx4 v[190:191], off
	s_add_i32 m0, s30, 0x2000
	s_add_u32 s30, s68, s2
	v_lshl_add_u64 v[192:193], s[68:69], 0, v[198:199]
	s_addc_u32 s31, s69, s3
	s_add_i32 s68, s71, s47
	global_load_lds_dwordx4 v[192:193], off
	v_lshl_add_u64 v[212:213], s[30:31], 0, v[0:1]
	s_mov_b32 m0, s68
	v_lshl_add_u64 v[214:215], s[30:31], 0, v[198:199]
	global_load_lds_dwordx4 v[212:213], off
	s_add_i32 m0, s68, 0x2000
	v_lshl_add_u64 v[216:217], s[44:45], 0, v[194:195]
	global_load_lds_dwordx4 v[214:215], off
	s_mov_b32 m0, s52
	v_lshl_add_u64 v[218:219], s[44:45], 0, v[196:197]
	global_load_lds_dwordx4 v[216:217], off
	s_mov_b32 m0, s53
	s_nop 0
	global_load_lds_dwordx4 v[218:219], off
	s_waitcnt vmcnt(8)
	s_waitcnt lgkmcnt(0)
	s_barrier
; #define PG8_STAGE(bufoff, gbase, voff) do { _Pragma("unroll") for (int _i = 0; _i < 2; ++_i) \
;         __builtin_amdgcn_global_load_lds((const unsigned*)((const char*)(gbase) + (voff)[_i]), (PG8_LAS unsigned*)(lds + (bufoff) + ldsw + _i * 8192), 16, 0, 0); } while (0)
; #define PG8_LDA(dst, b, h) do { _Pragma("unroll") for (int m = 0; m < 4; ++m) _Pragma("unroll") for (int k = 0; k < 2; ++k) dst[m][k] = *(const PG8_LAS bf16x8*)(lds + PG8_SA(b, h) + aoff + m * 2048 + k * 1024); } while (0)
; #define PG8_LDB(dst, b, h) do { _Pragma("unroll") for (int n = 0; n < 2; ++n) _Pragma("unroll") for (int k = 0; k < 2; ++k) dst[n][k] = *(const PG8_LAS bf16x8*)(lds + PG8_SB(b, h) + boff + n * 2048 + k * 1024); } while (0)
; #define PG8_MMA(ai, bj, At, Bt) do { __builtin_amdgcn_s_setprio(1); _Pragma("unroll") for (int m = 0; m < 4; ++m) _Pragma("unroll") for (int n = 0; n < 2; ++n) _Pragma("unroll") for (int k = 0; k < 2; ++k) \
;         acc[ai][bj][m][n] = __builtin_amdgcn_mfma_f32_16x16x32_bf16(Bt[n][k], At[m][k], acc[ai][bj][m][n], 0, 0, 0); __builtin_amdgcn_s_setprio(0); } while (0)
; #define PG8_WAIT_V(n) asm volatile("s_waitcnt vmcnt(" #n ")" ::: "memory")
; #define PG8_WAIT_L(n) asm volatile("s_waitcnt lgkmcnt(" #n ")" ::: "memory")
; #define PG8_BAR __builtin_amdgcn_s_barrier()
; #define PG8_SCHED __builtin_amdgcn_sched_barrier(0)
; template <class Epi, class Sched, bool ALIGN_EPI = false, bool SP2 = false>
; __device__ __forceinline__ void gemm_phase(PG8_LAS unsigned char* lds, const Gemm g, const Sched& S, const Epi& E, const int wv) {
;     ...
;             PG8_WAIT_V(8); PG8_WAIT_L(0); PG8_BAR; PG8_MMA(1, 0, At, B0); PG8_MMA(1, 1, At, B1); PG8_BAR; PG8_SCHED;
;             PG8_LDB(B0, 1, 0); PG8_LDB(B1, 1, 1); PG8_SCHED; PG8_LDA(At, 1, 0); PG8_STAGE(PG8_SA(0, 1), a2 + hstepA, voffA);
;             PG8_WAIT_V(8); PG8_WAIT_L(0); PG8_BAR; PG8_MMA(0, 0, At, B0); PG8_MMA(0, 1, At, B1); PG8_BAR; PG8_SCHED;
	s_waitcnt lgkmcnt(0)
	v_mfma_f32_16x16x32_bf16 v[62:65], v[114:117], v[162:165], v[62:65]
	v_mfma_f32_16x16x32_bf16 v[58:61], v[138:141], v[162:165], v[58:61]
	v_mfma_f32_16x16x32_bf16 v[46:49], v[114:117], v[170:173], v[46:49]
	v_mfma_f32_16x16x32_bf16 v[42:45], v[138:141], v[170:173], v[42:45]
	v_mfma_f32_16x16x32_bf16 v[30:33], v[114:117], v[178:181], v[30:33]
	v_mfma_f32_16x16x32_bf16 v[26:29], v[138:141], v[178:181], v[26:29]
	v_mfma_f32_16x16x32_bf16 v[14:17], v[114:117], v[204:207], v[14:17]
	v_mfma_f32_16x16x32_bf16 v[10:13], v[138:141], v[204:207], v[10:13]
	v_mfma_f32_16x16x32_bf16 v[62:65], v[126:129], v[166:169], v[62:65]
	v_mfma_f32_16x16x32_bf16 v[58:61], v[142:145], v[166:169], v[58:61]
	v_mfma_f32_16x16x32_bf16 v[46:49], v[126:129], v[174:177], v[46:49]
	v_mfma_f32_16x16x32_bf16 v[42:45], v[142:145], v[174:177], v[42:45]
	v_mfma_f32_16x16x32_bf16 v[30:33], v[126:129], v[182:185], v[30:33]
	v_mfma_f32_16x16x32_bf16 v[26:29], v[142:145], v[182:185], v[26:29]
	v_mfma_f32_16x16x32_bf16 v[14:17], v[126:129], v[208:211], v[14:17]
	v_mfma_f32_16x16x32_bf16 v[10:13], v[142:145], v[208:211], v[10:13]
	v_mfma_f32_16x16x32_bf16 v[54:57], v[146:149], v[162:165], v[54:57]
	v_mfma_f32_16x16x32_bf16 v[50:53], v[154:157], v[162:165], v[50:53]
	v_mfma_f32_16x16x32_bf16 v[38:41], v[146:149], v[170:173], v[38:41]
	v_mfma_f32_16x16x32_bf16 v[34:37], v[154:157], v[170:173], v[34:37]
	v_mfma_f32_16x16x32_bf16 v[22:25], v[146:149], v[178:181], v[22:25]
	v_mfma_f32_16x16x32_bf16 v[18:21], v[154:157], v[178:181], v[18:21]
	v_mfma_f32_16x16x32_bf16 v[6:9], v[146:149], v[204:207], v[6:9]
	v_mfma_f32_16x16x32_bf16 v[2:5], v[154:157], v[204:207], v[2:5]
	v_mfma_f32_16x16x32_bf16 v[54:57], v[150:153], v[166:169], v[54:57]
	v_mfma_f32_16x16x32_bf16 v[50:53], v[158:161], v[166:169], v[50:53]
	v_mfma_f32_16x16x32_bf16 v[38:41], v[150:153], v[174:177], v[38:41]
	v_mfma_f32_16x16x32_bf16 v[34:37], v[158:161], v[174:177], v[34:37]
	v_mfma_f32_16x16x32_bf16 v[22:25], v[150:153], v[182:185], v[22:25]
	v_mfma_f32_16x16x32_bf16 v[18:21], v[158:161], v[182:185], v[18:21]
	v_mfma_f32_16x16x32_bf16 v[6:9], v[150:153], v[208:211], v[6:9]
	v_mfma_f32_16x16x32_bf16 v[2:5], v[158:161], v[208:211], v[2:5]
	s_barrier
	s_add_i32 s68, 0, 0x18000
	s_add_i32 s69, 0, 0x1c000
	v_add_u32_e32 v142, s68, v230
	v_add_u32_e32 v158, s69, v230
	ds_read_b128 v[114:117], v142
	ds_read_b128 v[126:129], v142 offset:1024
	ds_read_b128 v[138:141], v142 offset:2048
	ds_read_b128 v[142:145], v142 offset:3072
	ds_read_b128 v[146:149], v158
	ds_read_b128 v[150:153], v158 offset:1024
	ds_read_b128 v[154:157], v158 offset:2048
	ds_read_b128 v[158:161], v158 offset:3072
	s_add_u32 s30, s44, 0x180000
	s_addc_u32 s31, s45, 0
	s_mov_b32 m0, s54
	ds_read_b128 v[162:165], v235 offset:32768
	ds_read_b128 v[166:169], v235 offset:33792
	ds_read_b128 v[170:173], v235 offset:34816
	ds_read_b128 v[174:177], v235 offset:35840
	ds_read_b128 v[178:181], v235 offset:36864
	ds_read_b128 v[182:185], v235 offset:37888
	ds_read_b128 v[204:207], v235 offset:38912
	ds_read_b128 v[208:211], v235 offset:39936
	global_load_lds_dwordx4 v194, s[30:31]
	s_mov_b32 m0, s55
	s_nop 0
	global_load_lds_dwordx4 v196, s[30:31]
	s_waitcnt vmcnt(8)
	s_waitcnt lgkmcnt(0)
	s_barrier
	s_waitcnt lgkmcnt(0)
	v_mfma_f32_16x16x32_bf16 v[134:137], v[114:117], v[162:165], v[134:137]
	v_mfma_f32_16x16x32_bf16 v[130:133], v[138:141], v[162:165], v[130:133]
	v_mfma_f32_16x16x32_bf16 v[110:113], v[114:117], v[170:173], v[110:113]
	v_mfma_f32_16x16x32_bf16 v[106:109], v[138:141], v[170:173], v[106:109]
	v_mfma_f32_16x16x32_bf16 v[94:97], v[114:117], v[178:181], v[94:97]
	v_mfma_f32_16x16x32_bf16 v[90:93], v[138:141], v[178:181], v[90:93]
	v_mfma_f32_16x16x32_bf16 v[78:81], v[114:117], v[204:207], v[78:81]
	v_mfma_f32_16x16x32_bf16 v[74:77], v[138:141], v[204:207], v[74:77]
	v_mfma_f32_16x16x32_bf16 v[134:137], v[126:129], v[166:169], v[134:137]
	v_mfma_f32_16x16x32_bf16 v[130:133], v[142:145], v[166:169], v[130:133]
	v_mfma_f32_16x16x32_bf16 v[110:113], v[126:129], v[174:177], v[110:113]
	v_mfma_f32_16x16x32_bf16 v[106:109], v[142:145], v[174:177], v[106:109]
	v_mfma_f32_16x16x32_bf16 v[94:97], v[126:129], v[182:185], v[94:97]
	v_mfma_f32_16x16x32_bf16 v[90:93], v[142:145], v[182:185], v[90:93]
	v_mfma_f32_16x16x32_bf16 v[78:81], v[126:129], v[208:211], v[78:81]
	v_mfma_f32_16x16x32_bf16 v[74:77], v[142:145], v[208:211], v[74:77]
	v_mfma_f32_16x16x32_bf16 v[122:125], v[146:149], v[162:165], v[122:125]
	v_mfma_f32_16x16x32_bf16 v[118:121], v[154:157], v[162:165], v[118:121]
	v_mfma_f32_16x16x32_bf16 v[102:105], v[146:149], v[170:173], v[102:105]
	v_mfma_f32_16x16x32_bf16 v[98:101], v[154:157], v[170:173], v[98:101]
	v_mfma_f32_16x16x32_bf16 v[86:89], v[146:149], v[178:181], v[86:89]
	v_mfma_f32_16x16x32_bf16 v[82:85], v[154:157], v[178:181], v[82:85]
	v_mfma_f32_16x16x32_bf16 v[70:73], v[146:149], v[204:207], v[70:73]
	v_mfma_f32_16x16x32_bf16 v[66:69], v[154:157], v[204:207], v[66:69]
	v_mfma_f32_16x16x32_bf16 v[122:125], v[150:153], v[166:169], v[122:125]
	v_mfma_f32_16x16x32_bf16 v[118:121], v[158:161], v[166:169], v[118:121]
	v_mfma_f32_16x16x32_bf16 v[102:105], v[150:153], v[174:177], v[102:105]
	v_mfma_f32_16x16x32_bf16 v[98:101], v[158:161], v[174:177], v[98:101]
	v_mfma_f32_16x16x32_bf16 v[86:89], v[150:153], v[182:185], v[86:89]
	v_mfma_f32_16x16x32_bf16 v[82:85], v[158:161], v[182:185], v[82:85]
	v_mfma_f32_16x16x32_bf16 v[70:73], v[150:153], v[208:211], v[70:73]
	v_mfma_f32_16x16x32_bf16 v[66:69], v[158:161], v[208:211], v[66:69]
	s_barrier
; #define PG8_STAGE(bufoff, gbase, voff) do { _Pragma("unroll") for (int _i = 0; _i < 2; ++_i) \
;         __builtin_amdgcn_global_load_lds((const unsigned*)((const char*)(gbase) + (voff)[_i]), (PG8_LAS unsigned*)(lds + (bufoff) + ldsw + _i * 8192), 16, 0, 0); } while (0)
; #define PG8_LDA(dst, b, h) do { _Pragma("unroll") for (int m = 0; m < 4; ++m) _Pragma("unroll") for (int k = 0; k < 2; ++k) dst[m][k] = *(const PG8_LAS bf16x8*)(lds + PG8_SA(b, h) + aoff + m * 2048 + k * 1024); } while (0)
; #define PG8_MMA(ai, bj, At, Bt) do { __builtin_amdgcn_s_setprio(1); _Pragma("unroll") for (int m = 0; m < 4; ++m) _Pragma("unroll") for (int n = 0; n < 2; ++n) _Pragma("unroll") for (int k = 0; k < 2; ++k) \
;         acc[ai][bj][m][n] = __builtin_amdgcn_mfma_f32_16x16x32_bf16(Bt[n][k], At[m][k], acc[ai][bj][m][n], 0, 0, 0); __builtin_amdgcn_s_setprio(0); } while (0)
; #define PG8_WAIT_V(n) asm volatile("s_waitcnt vmcnt(" #n ")" ::: "memory")
; #define PG8_WAIT_L(n) asm volatile("s_waitcnt lgkmcnt(" #n ")" ::: "memory")
; #define PG8_BAR __builtin_amdgcn_s_barrier()
; #define PG8_SCHED __builtin_amdgcn_sched_barrier(0)
; template <class Epi, class Sched, bool ALIGN_EPI = false, bool SP2 = false>
; __device__ __forceinline__ void gemm_phase(PG8_LAS unsigned char* lds, const Gemm g, const Sched& S, const Epi& E, const int wv) {
;     ...
;             PG8_LDA(At, 1, 1); PG8_STAGE(PG8_SB(1, 0), b3, voffB); PG8_STAGE(PG8_SB(1, 1), b3 + hstepB, voffB); PG8_STAGE(PG8_SA(1, 0), a3, voffA);
;             PG8_WAIT_V(8); PG8_WAIT_L(0); PG8_BAR; PG8_MMA(1, 0, At, B0); PG8_MMA(1, 1, At, B1); PG8_BAR; PG8_SCHED;
	s_add_i32 s30, s68, s47
	s_add_i32 m0, s30, 0xffffff80
	ds_read_b128 v[162:165], v235 offset:49152
	ds_read_b128 v[166:169], v235 offset:50176
	ds_read_b128 v[170:173], v235 offset:51200
	ds_read_b128 v[174:177], v235 offset:52224
	ds_read_b128 v[178:181], v235 offset:53248
	ds_read_b128 v[182:185], v235 offset:54272
	ds_read_b128 v[204:207], v235 offset:55296
	ds_read_b128 v[208:211], v235 offset:56320
	global_load_lds_dwordx4 v[190:191], off offset:128
	s_add_i32 m0, s30, 0x1f80
	s_add_i32 s30, s69, s47
	global_load_lds_dwordx4 v[192:193], off offset:128
	s_add_i32 m0, s30, 0xffffff80
	s_nop 0
	global_load_lds_dwordx4 v[212:213], off offset:128
	s_add_i32 m0, s30, 0x1f80
	s_nop 0
	global_load_lds_dwordx4 v[214:215], off offset:128
	s_add_i32 m0, s57, 0xffffff80
	s_nop 0
	global_load_lds_dwordx4 v[216:217], off offset:128
	s_add_i32 m0, s58, 0xffffff80
	s_nop 0
	global_load_lds_dwordx4 v[218:219], off offset:128
	s_waitcnt vmcnt(8)
	s_waitcnt lgkmcnt(0)
	s_barrier
	s_waitcnt lgkmcnt(0)
	v_mfma_f32_16x16x32_bf16 v[62:65], v[114:117], v[162:165], v[62:65]
	v_mfma_f32_16x16x32_bf16 v[58:61], v[138:141], v[162:165], v[58:61]
	v_mfma_f32_16x16x32_bf16 v[46:49], v[114:117], v[170:173], v[46:49]
	v_mfma_f32_16x16x32_bf16 v[42:45], v[138:141], v[170:173], v[42:45]
	v_mfma_f32_16x16x32_bf16 v[30:33], v[114:117], v[178:181], v[30:33]
	v_mfma_f32_16x16x32_bf16 v[26:29], v[138:141], v[178:181], v[26:29]
	v_mfma_f32_16x16x32_bf16 v[14:17], v[114:117], v[204:207], v[14:17]
	v_mfma_f32_16x16x32_bf16 v[10:13], v[138:141], v[204:207], v[10:13]
	v_mfma_f32_16x16x32_bf16 v[62:65], v[126:129], v[166:169], v[62:65]
	v_mfma_f32_16x16x32_bf16 v[58:61], v[142:145], v[166:169], v[58:61]
	v_mfma_f32_16x16x32_bf16 v[46:49], v[126:129], v[174:177], v[46:49]
	v_mfma_f32_16x16x32_bf16 v[42:45], v[142:145], v[174:177], v[42:45]
	v_mfma_f32_16x16x32_bf16 v[30:33], v[126:129], v[182:185], v[30:33]
	v_mfma_f32_16x16x32_bf16 v[26:29], v[142:145], v[182:185], v[26:29]
	v_mfma_f32_16x16x32_bf16 v[14:17], v[126:129], v[208:211], v[14:17]
	v_mfma_f32_16x16x32_bf16 v[10:13], v[142:145], v[208:211], v[10:13]
	v_mfma_f32_16x16x32_bf16 v[54:57], v[146:149], v[162:165], v[54:57]
	v_mfma_f32_16x16x32_bf16 v[50:53], v[154:157], v[162:165], v[50:53]
	v_mfma_f32_16x16x32_bf16 v[38:41], v[146:149], v[170:173], v[38:41]
	v_mfma_f32_16x16x32_bf16 v[34:37], v[154:157], v[170:173], v[34:37]
	v_mfma_f32_16x16x32_bf16 v[22:25], v[146:149], v[178:181], v[22:25]
	v_mfma_f32_16x16x32_bf16 v[18:21], v[154:157], v[178:181], v[18:21]
	v_mfma_f32_16x16x32_bf16 v[6:9], v[146:149], v[204:207], v[6:9]
	v_mfma_f32_16x16x32_bf16 v[2:5], v[154:157], v[204:207], v[2:5]
	v_mfma_f32_16x16x32_bf16 v[54:57], v[150:153], v[166:169], v[54:57]
	v_mfma_f32_16x16x32_bf16 v[50:53], v[158:161], v[166:169], v[50:53]
	v_mfma_f32_16x16x32_bf16 v[38:41], v[150:153], v[174:177], v[38:41]
	v_mfma_f32_16x16x32_bf16 v[34:37], v[158:161], v[174:177], v[34:37]
	v_mfma_f32_16x16x32_bf16 v[22:25], v[150:153], v[182:185], v[22:25]
	v_mfma_f32_16x16x32_bf16 v[18:21], v[158:161], v[182:185], v[18:21]
	v_mfma_f32_16x16x32_bf16 v[6:9], v[150:153], v[208:211], v[6:9]
	v_mfma_f32_16x16x32_bf16 v[2:5], v[158:161], v[208:211], v[2:5]
	s_barrier
	s_add_u32 s65, s65, 0x100
	s_addc_u32 s66, s66, 0
	s_cmp_ge_i32 s67, s56
	s_mov_b64 s[30:31], s[34:35]
	s_mov_b32 s44, s67
	s_cbranch_scc0 .LBB0_990
	s_movk_i32 s68, 0x4000
	s_movk_i32 s69, 0x6000
	s_mov_b32 s70, 0x18000
	s_mov_b32 s71, 0x3f317217
	v_readlane_b32 s67, v255, 30
	s_and_b64 vcc, exec, s[28:29]
	s_cbranch_vccz .LBB0_966

; #define PG8_STAGE(bufoff, gbase, voff) do { _Pragma("unroll") for (int _i = 0; _i < 2; ++_i) \
;         __builtin_amdgcn_global_load_lds((const unsigned*)((const char*)(gbase) + (voff)[_i]), (PG8_LAS unsigned*)(lds + (bufoff) + ldsw + _i * 8192), 16, 0, 0); } while (0)
; #define PG8_LDA(dst, b, h) do { _Pragma("unroll") for (int m = 0; m < 4; ++m) _Pragma("unroll") for (int k = 0; k < 2; ++k) dst[m][k] = *(const PG8_LAS bf16x8*)(lds + PG8_SA(b, h) + aoff + m * 2048 + k * 1024); } while (0)
; #define PG8_LDB(dst, b, h) do { _Pragma("unroll") for (int n = 0; n < 2; ++n) _Pragma("unroll") for (int k = 0; k < 2; ++k) dst[n][k] = *(const PG8_LAS bf16x8*)(lds + PG8_SB(b, h) + boff + n * 2048 + k * 1024); } while (0)
; #define PG8_MMA(ai, bj, At, Bt) do { __builtin_amdgcn_s_setprio(1); _Pragma("unroll") for (int m = 0; m < 4; ++m) _Pragma("unroll") for (int n = 0; n < 2; ++n) _Pragma("unroll") for (int k = 0; k < 2; ++k) \
;         acc[ai][bj][m][n] = __builtin_amdgcn_mfma_f32_16x16x32_bf16(Bt[n][k], At[m][k], acc[ai][bj][m][n], 0, 0, 0); __builtin_amdgcn_s_setprio(0); } while (0)
; #define PG8_WAIT_V(n) asm volatile("s_waitcnt vmcnt(" #n ")" ::: "memory")
; #define PG8_BAR __builtin_amdgcn_s_barrier()
; template <class Epi, class Sched, bool ALIGN_EPI = false, bool SP2 = false>
; __device__ __forceinline__ void gemm_phase(PG8_LAS unsigned char* lds, const Gemm g, const Sched& S, const Epi& E, const int wv) {
;     ...
;         for (int t = 0; t < nt; t += 2) {
;             const bool last = (t == nt - 2);
;             const char* a1 = cA + (size_t)(t + 1) * kstep;
;             const char* a2 = last ? nA : cA + (size_t)(t + 2) * kstep; const char* b2 = last ? nB : cB + (size_t)(t + 2) * kstep;
;             const char* a3 = a2 + kstep; const char* b3 = b2 + kstep;
;             if (last && has_next) S.a_ready(nxt);
;             if constexpr (SP2) {
;             PG8_LDB(B0, 0, 0); PG8_LDB(B1, 0, 1); PG8_SCHED; PG8_LDA(At, 0, 0); PG8_STAGE(PG8_SA(1, 1), a1 + hstepA, voffA);
;             PG8_WAIT_V(8); PG8_WAIT_L(0); PG8_BAR; PG8_MMA(0, 0, At, B0); PG8_MMA(0, 1, At, B1); PG8_BAR; PG8_SCHED;
;             PG8_LDA(At, 0, 1); PG8_STAGE(PG8_SB(0, 0), b2, voffB); PG8_STAGE(PG8_SB(0, 1), b2 + hstepB, voffB); PG8_STAGE(PG8_SA(0, 0), a2, voffA);
;             PG8_WAIT_V(8); PG8_WAIT_L(0); PG8_BAR; PG8_MMA(1, 0, At, B0); PG8_MMA(1, 1, At, B1); PG8_BAR; PG8_SCHED;
.LBB0_1074:
	s_add_i32 s63, s30, 2
	s_add_u32 s64, s28, 0xfff80080
	s_addc_u32 s31, s29, -1
	s_add_i32 s66, 0, 0x10000
	s_cmp_eq_u32 s57, s30
	s_cselect_b32 s31, s17, s31
	s_cselect_b32 s30, s40, s64
	v_add_u32_e32 v0, s66, v157
	s_cselect_b32 s65, s19, s62
	s_cselect_b32 s64, s18, s41
	s_add_i32 s67, 0, 0x14000
	ds_read_b128 v[164:167], v0
	ds_read_b128 v[168:171], v0 offset:1024
	ds_read_b128 v[172:175], v0 offset:2048
	ds_read_b128 v[176:179], v0 offset:3072
	v_add_u32_e32 v0, s67, v157
	ds_read_b128 v[180:183], v0
	ds_read_b128 v[194:197], v0 offset:1024
	ds_read_b128 v[198:201], v0 offset:2048
	ds_read_b128 v[202:205], v0 offset:3072
	s_add_i32 m0, s47, 0xc000
	ds_read_b128 v[206:209], v163
	ds_read_b128 v[210:213], v163 offset:1024
	ds_read_b128 v[214:217], v163 offset:2048
	ds_read_b128 v[228:231], v163 offset:3072
	ds_read_b128 v[232:235], v163 offset:4096
	ds_read_b128 v[236:239], v163 offset:5120
	ds_read_b128 v[240:243], v163 offset:6144
	ds_read_b128 v[244:247], v163 offset:7168
	global_load_lds_dwordx4 v146, s[28:29]
	s_add_i32 m0, s47, 0xe000
	s_nop 0
	global_load_lds_dwordx4 v148, s[28:29]
	s_waitcnt vmcnt(8)
	s_waitcnt lgkmcnt(0)
	s_barrier
	s_waitcnt lgkmcnt(0)
	v_mfma_f32_16x16x32_bf16 v[130:133], v[164:167], v[206:209], v[130:133]
	v_mfma_f32_16x16x32_bf16 v[126:129], v[172:175], v[206:209], v[126:129]
	v_mfma_f32_16x16x32_bf16 v[114:117], v[164:167], v[214:217], v[114:117]
	v_mfma_f32_16x16x32_bf16 v[110:113], v[172:175], v[214:217], v[110:113]
	v_mfma_f32_16x16x32_bf16 v[98:101], v[164:167], v[232:235], v[98:101]
	v_mfma_f32_16x16x32_bf16 v[94:97], v[172:175], v[232:235], v[94:97]
	v_mfma_f32_16x16x32_bf16 v[82:85], v[164:167], v[240:243], v[82:85]
	v_mfma_f32_16x16x32_bf16 v[78:81], v[172:175], v[240:243], v[78:81]
	v_mfma_f32_16x16x32_bf16 v[130:133], v[168:171], v[210:213], v[130:133]
	v_mfma_f32_16x16x32_bf16 v[126:129], v[176:179], v[210:213], v[126:129]
	v_mfma_f32_16x16x32_bf16 v[114:117], v[168:171], v[228:231], v[114:117]
	v_mfma_f32_16x16x32_bf16 v[110:113], v[176:179], v[228:231], v[110:113]
	v_mfma_f32_16x16x32_bf16 v[98:101], v[168:171], v[236:239], v[98:101]
	v_mfma_f32_16x16x32_bf16 v[94:97], v[176:179], v[236:239], v[94:97]
	v_mfma_f32_16x16x32_bf16 v[82:85], v[168:171], v[244:247], v[82:85]
	v_mfma_f32_16x16x32_bf16 v[78:81], v[176:179], v[244:247], v[78:81]
	v_mfma_f32_16x16x32_bf16 v[122:125], v[180:183], v[206:209], v[122:125]
	v_mfma_f32_16x16x32_bf16 v[118:121], v[198:201], v[206:209], v[118:121]
	v_mfma_f32_16x16x32_bf16 v[106:109], v[180:183], v[214:217], v[106:109]
	v_mfma_f32_16x16x32_bf16 v[102:105], v[198:201], v[214:217], v[102:105]
	v_mfma_f32_16x16x32_bf16 v[90:93], v[180:183], v[232:235], v[90:93]
	v_mfma_f32_16x16x32_bf16 v[86:89], v[198:201], v[232:235], v[86:89]
	v_mfma_f32_16x16x32_bf16 v[74:77], v[180:183], v[240:243], v[74:77]
	v_mfma_f32_16x16x32_bf16 v[70:73], v[198:201], v[240:243], v[70:73]
	v_mfma_f32_16x16x32_bf16 v[122:125], v[194:197], v[210:213], v[122:125]
	v_mfma_f32_16x16x32_bf16 v[118:121], v[202:205], v[210:213], v[118:121]
	v_mfma_f32_16x16x32_bf16 v[106:109], v[194:197], v[228:231], v[106:109]
	v_mfma_f32_16x16x32_bf16 v[102:105], v[202:205], v[228:231], v[102:105]
	v_mfma_f32_16x16x32_bf16 v[90:93], v[194:197], v[236:239], v[90:93]
	v_mfma_f32_16x16x32_bf16 v[86:89], v[202:205], v[236:239], v[86:89]
	v_mfma_f32_16x16x32_bf16 v[74:77], v[194:197], v[244:247], v[74:77]
	v_mfma_f32_16x16x32_bf16 v[70:73], v[202:205], v[244:247], v[70:73]
	s_barrier
	s_add_i32 s66, s66, s45
	v_lshl_add_u64 v[150:151], s[64:65], 0, v[138:139]
	s_mov_b32 m0, s66
	ds_read_b128 v[206:209], v163 offset:16384
	ds_read_b128 v[210:213], v163 offset:17408
	ds_read_b128 v[214:217], v163 offset:18432
	ds_read_b128 v[228:231], v163 offset:19456
	ds_read_b128 v[232:235], v163 offset:20480
	ds_read_b128 v[236:239], v163 offset:21504
	ds_read_b128 v[240:243], v163 offset:22528
	ds_read_b128 v[244:247], v163 offset:23552
	global_load_lds_dwordx4 v[150:151], off
	s_add_i32 m0, s66, 0x2000
	v_lshl_add_u64 v[184:185], s[64:65], 0, v[134:135]
	s_add_u32 s64, s64, s0
	s_addc_u32 s65, s65, s1
	s_add_i32 s66, s67, s45
	global_load_lds_dwordx4 v[184:185], off
	v_lshl_add_u64 v[190:191], s[64:65], 0, v[138:139]
	s_mov_b32 m0, s66
	v_lshl_add_u64 v[192:193], s[64:65], 0, v[134:135]
	global_load_lds_dwordx4 v[190:191], off
	s_add_i32 m0, s66, 0x2000
	v_lshl_add_u64 v[218:219], s[30:31], 0, v[140:141]
	global_load_lds_dwordx4 v[192:193], off
	s_mov_b32 m0, s47
	v_lshl_add_u64 v[248:249], s[30:31], 0, v[136:137]
	global_load_lds_dwordx4 v[218:219], off
	s_mov_b32 m0, s48
	s_nop 0
	global_load_lds_dwordx4 v[248:249], off
	s_waitcnt vmcnt(8)
	s_waitcnt lgkmcnt(0)
	s_barrier
; #define PG8_STAGE(bufoff, gbase, voff) do { _Pragma("unroll") for (int _i = 0; _i < 2; ++_i) \
;         __builtin_amdgcn_global_load_lds((const unsigned*)((const char*)(gbase) + (voff)[_i]), (PG8_LAS unsigned*)(lds + (bufoff) + ldsw + _i * 8192), 16, 0, 0); } while (0)
; #define PG8_LDA(dst, b, h) do { _Pragma("unroll") for (int m = 0; m < 4; ++m) _Pragma("unroll") for (int k = 0; k < 2; ++k) dst[m][k] = *(const PG8_LAS bf16x8*)(lds + PG8_SA(b, h) + aoff + m * 2048 + k * 1024); } while (0)
; #define PG8_LDB(dst, b, h) do { _Pragma("unroll") for (int n = 0; n < 2; ++n) _Pragma("unroll") for (int k = 0; k < 2; ++k) dst[n][k] = *(const PG8_LAS bf16x8*)(lds + PG8_SB(b, h) + boff + n * 2048 + k * 1024); } while (0)
; #define PG8_MMA(ai, bj, At, Bt) do { __builtin_amdgcn_s_setprio(1); _Pragma("unroll") for (int m = 0; m < 4; ++m) _Pragma("unroll") for (int n = 0; n < 2; ++n) _Pragma("unroll") for (int k = 0; k < 2; ++k) \
;         acc[ai][bj][m][n] = __builtin_amdgcn_mfma_f32_16x16x32_bf16(Bt[n][k], At[m][k], acc[ai][bj][m][n], 0, 0, 0); __builtin_amdgcn_s_setprio(0); } while (0)
; #define PG8_WAIT_V(n) asm volatile("s_waitcnt vmcnt(" #n ")" ::: "memory")
; #define PG8_WAIT_L(n) asm volatile("s_waitcnt lgkmcnt(" #n ")" ::: "memory")
; #define PG8_BAR __builtin_amdgcn_s_barrier()
; #define PG8_SCHED __builtin_amdgcn_sched_barrier(0)
; template <class Epi, class Sched, bool ALIGN_EPI = false, bool SP2 = false>
; __device__ __forceinline__ void gemm_phase(PG8_LAS unsigned char* lds, const Gemm g, const Sched& S, const Epi& E, const int wv) {
;     ...
;             PG8_WAIT_V(8); PG8_WAIT_L(0); PG8_BAR; PG8_MMA(1, 0, At, B0); PG8_MMA(1, 1, At, B1); PG8_BAR; PG8_SCHED;
;             PG8_LDB(B0, 1, 0); PG8_LDB(B1, 1, 1); PG8_SCHED; PG8_LDA(At, 1, 0); PG8_STAGE(PG8_SA(0, 1), a2 + hstepA, voffA);
;             PG8_WAIT_V(8); PG8_WAIT_L(0); PG8_BAR; PG8_MMA(0, 0, At, B0); PG8_MMA(0, 1, At, B1); PG8_BAR; PG8_SCHED;
	s_waitcnt lgkmcnt(0)
	v_mfma_f32_16x16x32_bf16 v[66:69], v[164:167], v[206:209], v[66:69]
	v_mfma_f32_16x16x32_bf16 v[62:65], v[172:175], v[206:209], v[62:65]
	v_mfma_f32_16x16x32_bf16 v[50:53], v[164:167], v[214:217], v[50:53]
	v_mfma_f32_16x16x32_bf16 v[46:49], v[172:175], v[214:217], v[46:49]
	v_mfma_f32_16x16x32_bf16 v[34:37], v[164:167], v[232:235], v[34:37]
	v_mfma_f32_16x16x32_bf16 v[30:33], v[172:175], v[232:235], v[30:33]
	v_mfma_f32_16x16x32_bf16 v[18:21], v[164:167], v[240:243], v[18:21]
	v_mfma_f32_16x16x32_bf16 v[14:17], v[172:175], v[240:243], v[14:17]
	v_mfma_f32_16x16x32_bf16 v[66:69], v[168:171], v[210:213], v[66:69]
	v_mfma_f32_16x16x32_bf16 v[62:65], v[176:179], v[210:213], v[62:65]
	v_mfma_f32_16x16x32_bf16 v[50:53], v[168:171], v[228:231], v[50:53]
	v_mfma_f32_16x16x32_bf16 v[46:49], v[176:179], v[228:231], v[46:49]
	v_mfma_f32_16x16x32_bf16 v[34:37], v[168:171], v[236:239], v[34:37]
	v_mfma_f32_16x16x32_bf16 v[30:33], v[176:179], v[236:239], v[30:33]
	v_mfma_f32_16x16x32_bf16 v[18:21], v[168:171], v[244:247], v[18:21]
	v_mfma_f32_16x16x32_bf16 v[14:17], v[176:179], v[244:247], v[14:17]
	v_mfma_f32_16x16x32_bf16 v[58:61], v[180:183], v[206:209], v[58:61]
	v_mfma_f32_16x16x32_bf16 v[54:57], v[198:201], v[206:209], v[54:57]
	v_mfma_f32_16x16x32_bf16 v[42:45], v[180:183], v[214:217], v[42:45]
	v_mfma_f32_16x16x32_bf16 v[38:41], v[198:201], v[214:217], v[38:41]
	v_mfma_f32_16x16x32_bf16 v[26:29], v[180:183], v[232:235], v[26:29]
	v_mfma_f32_16x16x32_bf16 v[22:25], v[198:201], v[232:235], v[22:25]
	v_mfma_f32_16x16x32_bf16 v[10:13], v[180:183], v[240:243], v[10:13]
	v_mfma_f32_16x16x32_bf16 v[6:9], v[198:201], v[240:243], v[6:9]
	v_mfma_f32_16x16x32_bf16 v[58:61], v[194:197], v[210:213], v[58:61]
	v_mfma_f32_16x16x32_bf16 v[54:57], v[202:205], v[210:213], v[54:57]
	v_mfma_f32_16x16x32_bf16 v[42:45], v[194:197], v[228:231], v[42:45]
	v_mfma_f32_16x16x32_bf16 v[38:41], v[202:205], v[228:231], v[38:41]
	v_mfma_f32_16x16x32_bf16 v[26:29], v[194:197], v[236:239], v[26:29]
	v_mfma_f32_16x16x32_bf16 v[22:25], v[202:205], v[236:239], v[22:25]
	v_mfma_f32_16x16x32_bf16 v[10:13], v[194:197], v[244:247], v[10:13]
	v_mfma_f32_16x16x32_bf16 v[6:9], v[202:205], v[244:247], v[6:9]
	s_barrier
	s_add_i32 s64, 0, 0x18000
	v_add_u32_e32 v0, s64, v157
	s_add_i32 s65, 0, 0x1c000
	ds_read_b128 v[164:167], v0
	ds_read_b128 v[168:171], v0 offset:1024
	ds_read_b128 v[172:175], v0 offset:2048
	ds_read_b128 v[176:179], v0 offset:3072
	v_add_u32_e32 v0, s65, v157
	ds_read_b128 v[180:183], v0
	ds_read_b128 v[194:197], v0 offset:1024
	ds_read_b128 v[198:201], v0 offset:2048
	ds_read_b128 v[202:205], v0 offset:3072
	s_add_u32 s30, s30, 0x80000
	s_addc_u32 s31, s31, 0
	s_mov_b32 m0, s49
	ds_read_b128 v[206:209], v163 offset:32768
	ds_read_b128 v[210:213], v163 offset:33792
	ds_read_b128 v[214:217], v163 offset:34816
	ds_read_b128 v[228:231], v163 offset:35840
	ds_read_b128 v[232:235], v163 offset:36864
	ds_read_b128 v[236:239], v163 offset:37888
	ds_read_b128 v[240:243], v163 offset:38912
	ds_read_b128 v[244:247], v163 offset:39936
	global_load_lds_dwordx4 v140, s[30:31]
	s_mov_b32 m0, s50
	s_nop 0
	global_load_lds_dwordx4 v136, s[30:31]
	s_waitcnt vmcnt(8)
	s_waitcnt lgkmcnt(0)
	s_barrier
	s_waitcnt lgkmcnt(0)
	v_mfma_f32_16x16x32_bf16 v[130:133], v[164:167], v[206:209], v[130:133]
	v_mfma_f32_16x16x32_bf16 v[126:129], v[172:175], v[206:209], v[126:129]
	v_mfma_f32_16x16x32_bf16 v[114:117], v[164:167], v[214:217], v[114:117]
	v_mfma_f32_16x16x32_bf16 v[110:113], v[172:175], v[214:217], v[110:113]
	v_mfma_f32_16x16x32_bf16 v[98:101], v[164:167], v[232:235], v[98:101]
	v_mfma_f32_16x16x32_bf16 v[94:97], v[172:175], v[232:235], v[94:97]
	v_mfma_f32_16x16x32_bf16 v[82:85], v[164:167], v[240:243], v[82:85]
	v_mfma_f32_16x16x32_bf16 v[78:81], v[172:175], v[240:243], v[78:81]
	v_mfma_f32_16x16x32_bf16 v[130:133], v[168:171], v[210:213], v[130:133]
	v_mfma_f32_16x16x32_bf16 v[126:129], v[176:179], v[210:213], v[126:129]
	v_mfma_f32_16x16x32_bf16 v[114:117], v[168:171], v[228:231], v[114:117]
	v_mfma_f32_16x16x32_bf16 v[110:113], v[176:179], v[228:231], v[110:113]
	v_mfma_f32_16x16x32_bf16 v[98:101], v[168:171], v[236:239], v[98:101]
	v_mfma_f32_16x16x32_bf16 v[94:97], v[176:179], v[236:239], v[94:97]
	v_mfma_f32_16x16x32_bf16 v[82:85], v[168:171], v[244:247], v[82:85]
	v_mfma_f32_16x16x32_bf16 v[78:81], v[176:179], v[244:247], v[78:81]
	v_mfma_f32_16x16x32_bf16 v[122:125], v[180:183], v[206:209], v[122:125]
	v_mfma_f32_16x16x32_bf16 v[118:121], v[198:201], v[206:209], v[118:121]
	v_mfma_f32_16x16x32_bf16 v[106:109], v[180:183], v[214:217], v[106:109]
	v_mfma_f32_16x16x32_bf16 v[102:105], v[198:201], v[214:217], v[102:105]
	v_mfma_f32_16x16x32_bf16 v[90:93], v[180:183], v[232:235], v[90:93]
	v_mfma_f32_16x16x32_bf16 v[86:89], v[198:201], v[232:235], v[86:89]
	v_mfma_f32_16x16x32_bf16 v[74:77], v[180:183], v[240:243], v[74:77]
	v_mfma_f32_16x16x32_bf16 v[70:73], v[198:201], v[240:243], v[70:73]
	v_mfma_f32_16x16x32_bf16 v[122:125], v[194:197], v[210:213], v[122:125]
	v_mfma_f32_16x16x32_bf16 v[118:121], v[202:205], v[210:213], v[118:121]
	v_mfma_f32_16x16x32_bf16 v[106:109], v[194:197], v[228:231], v[106:109]
	v_mfma_f32_16x16x32_bf16 v[102:105], v[202:205], v[228:231], v[102:105]
	v_mfma_f32_16x16x32_bf16 v[90:93], v[194:197], v[236:239], v[90:93]
	v_mfma_f32_16x16x32_bf16 v[86:89], v[202:205], v[236:239], v[86:89]
	v_mfma_f32_16x16x32_bf16 v[74:77], v[194:197], v[244:247], v[74:77]
	v_mfma_f32_16x16x32_bf16 v[70:73], v[202:205], v[244:247], v[70:73]
	s_barrier
; #define PG8_STAGE(bufoff, gbase, voff) do { _Pragma("unroll") for (int _i = 0; _i < 2; ++_i) \
;         __builtin_amdgcn_global_load_lds((const unsigned*)((const char*)(gbase) + (voff)[_i]), (PG8_LAS unsigned*)(lds + (bufoff) + ldsw + _i * 8192), 16, 0, 0); } while (0)
; #define PG8_LDA(dst, b, h) do { _Pragma("unroll") for (int m = 0; m < 4; ++m) _Pragma("unroll") for (int k = 0; k < 2; ++k) dst[m][k] = *(const PG8_LAS bf16x8*)(lds + PG8_SA(b, h) + aoff + m * 2048 + k * 1024); } while (0)
; #define PG8_MMA(ai, bj, At, Bt) do { __builtin_amdgcn_s_setprio(1); _Pragma("unroll") for (int m = 0; m < 4; ++m) _Pragma("unroll") for (int n = 0; n < 2; ++n) _Pragma("unroll") for (int k = 0; k < 2; ++k) \
;         acc[ai][bj][m][n] = __builtin_amdgcn_mfma_f32_16x16x32_bf16(Bt[n][k], At[m][k], acc[ai][bj][m][n], 0, 0, 0); __builtin_amdgcn_s_setprio(0); } while (0)
; #define PG8_WAIT_V(n) asm volatile("s_waitcnt vmcnt(" #n ")" ::: "memory")
; #define PG8_WAIT_L(n) asm volatile("s_waitcnt lgkmcnt(" #n ")" ::: "memory")
; #define PG8_BAR __builtin_amdgcn_s_barrier()
; #define PG8_SCHED __builtin_amdgcn_sched_barrier(0)
; template <class Epi, class Sched, bool ALIGN_EPI = false, bool SP2 = false>
; __device__ __forceinline__ void gemm_phase(PG8_LAS unsigned char* lds, const Gemm g, const Sched& S, const Epi& E, const int wv) {
;     ...
;             PG8_LDA(At, 1, 1); PG8_STAGE(PG8_SB(1, 0), b3, voffB); PG8_STAGE(PG8_SB(1, 1), b3 + hstepB, voffB); PG8_STAGE(PG8_SA(1, 0), a3, voffA);
;             PG8_WAIT_V(8); PG8_WAIT_L(0); PG8_BAR; PG8_MMA(1, 0, At, B0); PG8_MMA(1, 1, At, B1); PG8_BAR; PG8_SCHED;
	s_add_i32 s30, s64, s45
	s_add_i32 m0, s30, 0xffffff80
	ds_read_b128 v[206:209], v163 offset:49152
	ds_read_b128 v[210:213], v163 offset:50176
	ds_read_b128 v[214:217], v163 offset:51200
	ds_read_b128 v[228:231], v163 offset:52224
	ds_read_b128 v[232:235], v163 offset:53248
	ds_read_b128 v[236:239], v163 offset:54272
	ds_read_b128 v[240:243], v163 offset:55296
	ds_read_b128 v[244:247], v163 offset:56320
	global_load_lds_dwordx4 v[150:151], off offset:128
	s_add_i32 m0, s30, 0x1f80
	s_add_i32 s30, s65, s45
	global_load_lds_dwordx4 v[184:185], off offset:128
	s_add_i32 m0, s30, 0xffffff80
	s_nop 0
	global_load_lds_dwordx4 v[190:191], off offset:128
	s_add_i32 m0, s30, 0x1f80
	s_nop 0
	global_load_lds_dwordx4 v[192:193], off offset:128
	s_add_i32 m0, s53, 0xffffff80
	s_nop 0
	global_load_lds_dwordx4 v[218:219], off offset:128
	s_add_i32 m0, s54, 0xffffff80
	s_nop 0
	global_load_lds_dwordx4 v[248:249], off offset:128
	s_waitcnt vmcnt(8)
	s_waitcnt lgkmcnt(0)
	s_barrier
	s_waitcnt lgkmcnt(0)
	v_mfma_f32_16x16x32_bf16 v[66:69], v[164:167], v[206:209], v[66:69]
	v_mfma_f32_16x16x32_bf16 v[62:65], v[172:175], v[206:209], v[62:65]
	v_mfma_f32_16x16x32_bf16 v[50:53], v[164:167], v[214:217], v[50:53]
	v_mfma_f32_16x16x32_bf16 v[46:49], v[172:175], v[214:217], v[46:49]
	v_mfma_f32_16x16x32_bf16 v[34:37], v[164:167], v[232:235], v[34:37]
	v_mfma_f32_16x16x32_bf16 v[30:33], v[172:175], v[232:235], v[30:33]
	v_mfma_f32_16x16x32_bf16 v[18:21], v[164:167], v[240:243], v[18:21]
	v_mfma_f32_16x16x32_bf16 v[14:17], v[172:175], v[240:243], v[14:17]
	v_mfma_f32_16x16x32_bf16 v[66:69], v[168:171], v[210:213], v[66:69]
	v_mfma_f32_16x16x32_bf16 v[62:65], v[176:179], v[210:213], v[62:65]
	v_mfma_f32_16x16x32_bf16 v[50:53], v[168:171], v[228:231], v[50:53]
	v_mfma_f32_16x16x32_bf16 v[46:49], v[176:179], v[228:231], v[46:49]
	v_mfma_f32_16x16x32_bf16 v[34:37], v[168:171], v[236:239], v[34:37]
	v_mfma_f32_16x16x32_bf16 v[30:33], v[176:179], v[236:239], v[30:33]
	v_mfma_f32_16x16x32_bf16 v[18:21], v[168:171], v[244:247], v[18:21]
	v_mfma_f32_16x16x32_bf16 v[14:17], v[176:179], v[244:247], v[14:17]
	v_mfma_f32_16x16x32_bf16 v[58:61], v[180:183], v[206:209], v[58:61]
	v_mfma_f32_16x16x32_bf16 v[54:57], v[198:201], v[206:209], v[54:57]
	v_mfma_f32_16x16x32_bf16 v[42:45], v[180:183], v[214:217], v[42:45]
	v_mfma_f32_16x16x32_bf16 v[38:41], v[198:201], v[214:217], v[38:41]
	v_mfma_f32_16x16x32_bf16 v[26:29], v[180:183], v[232:235], v[26:29]
	v_mfma_f32_16x16x32_bf16 v[22:25], v[198:201], v[232:235], v[22:25]
	v_mfma_f32_16x16x32_bf16 v[10:13], v[180:183], v[240:243], v[10:13]
	v_mfma_f32_16x16x32_bf16 v[6:9], v[198:201], v[240:243], v[6:9]
	v_mfma_f32_16x16x32_bf16 v[58:61], v[194:197], v[210:213], v[58:61]
	v_mfma_f32_16x16x32_bf16 v[54:57], v[202:205], v[210:213], v[54:57]
	v_mfma_f32_16x16x32_bf16 v[42:45], v[194:197], v[228:231], v[42:45]
	v_mfma_f32_16x16x32_bf16 v[38:41], v[202:205], v[228:231], v[38:41]
	v_mfma_f32_16x16x32_bf16 v[26:29], v[194:197], v[236:239], v[26:29]
	v_mfma_f32_16x16x32_bf16 v[22:25], v[202:205], v[236:239], v[22:25]
	v_mfma_f32_16x16x32_bf16 v[10:13], v[194:197], v[244:247], v[10:13]
	v_mfma_f32_16x16x32_bf16 v[6:9], v[202:205], v[244:247], v[6:9]
	s_barrier
	s_add_u32 s28, s28, 0x100
	s_addc_u32 s29, s29, 0
	s_add_u32 s41, s41, 0x100
	s_addc_u32 s62, s62, 0
	s_cmp_ge_i32 s63, s55
	s_mov_b32 s30, s63
	s_cbranch_scc0 .LBB0_1074
	v_readlane_b32 s67, v255, 30

; #define PG8_STAGE(bufoff, gbase, voff) do { _Pragma("unroll") for (int _i = 0; _i < 2; ++_i) \
;         __builtin_amdgcn_global_load_lds((const unsigned*)((const char*)(gbase) + (voff)[_i]), (PG8_LAS unsigned*)(lds + (bufoff) + ldsw + _i * 8192), 16, 0, 0); } while (0)
; #define PG8_LDA(dst, b, h) do { _Pragma("unroll") for (int m = 0; m < 4; ++m) _Pragma("unroll") for (int k = 0; k < 2; ++k) dst[m][k] = *(const PG8_LAS bf16x8*)(lds + PG8_SA(b, h) + aoff + m * 2048 + k * 1024); } while (0)
; #define PG8_LDB(dst, b, h) do { _Pragma("unroll") for (int n = 0; n < 2; ++n) _Pragma("unroll") for (int k = 0; k < 2; ++k) dst[n][k] = *(const PG8_LAS bf16x8*)(lds + PG8_SB(b, h) + boff + n * 2048 + k * 1024); } while (0)
; #define PG8_MMA(ai, bj, At, Bt) do { __builtin_amdgcn_s_setprio(1); _Pragma("unroll") for (int m = 0; m < 4; ++m) _Pragma("unroll") for (int n = 0; n < 2; ++n) _Pragma("unroll") for (int k = 0; k < 2; ++k) \
;         acc[ai][bj][m][n] = __builtin_amdgcn_mfma_f32_16x16x32_bf16(Bt[n][k], At[m][k], acc[ai][bj][m][n], 0, 0, 0); __builtin_amdgcn_s_setprio(0); } while (0)
; #define PG8_WAIT_V(n) asm volatile("s_waitcnt vmcnt(" #n ")" ::: "memory")
; #define PG8_BAR __builtin_amdgcn_s_barrier()
; template <class Epi, class Sched, bool ALIGN_EPI = false, bool SP2 = false>
; __device__ __forceinline__ void gemm_phase(PG8_LAS unsigned char* lds, const Gemm g, const Sched& S, const Epi& E, const int wv) {
;     ...
;         for (int t = 0; t < nt; t += 2) {
;             const bool last = (t == nt - 2);
;             const char* a1 = cA + (size_t)(t + 1) * kstep;
;             const char* a2 = last ? nA : cA + (size_t)(t + 2) * kstep; const char* b2 = last ? nB : cB + (size_t)(t + 2) * kstep;
;             const char* a3 = a2 + kstep; const char* b3 = b2 + kstep;
;             if (last && has_next) S.a_ready(nxt);
;             if constexpr (SP2) {
;             PG8_LDB(B0, 0, 0); PG8_LDB(B1, 0, 1); PG8_SCHED; PG8_LDA(At, 0, 0); PG8_STAGE(PG8_SA(1, 1), a1 + hstepA, voffA);
;             PG8_WAIT_V(8); PG8_WAIT_L(0); PG8_BAR; PG8_MMA(0, 0, At, B0); PG8_MMA(0, 1, At, B1); PG8_BAR; PG8_SCHED;
;             PG8_LDA(At, 0, 1); PG8_STAGE(PG8_SB(0, 0), b2, voffB); PG8_STAGE(PG8_SB(0, 1), b2 + hstepB, voffB); PG8_STAGE(PG8_SA(0, 0), a2, voffA);
;             PG8_WAIT_V(8); PG8_WAIT_L(0); PG8_BAR; PG8_MMA(1, 0, At, B0); PG8_MMA(1, 1, At, B1); PG8_BAR; PG8_SCHED;
.LBB0_1385:
	s_add_i32 s70, s52, 2
	s_add_u32 s71, s44, 0xfffc0080
	s_addc_u32 s53, s45, -1
	s_add_i32 s74, 0, 0x10000
	s_cmp_eq_u32 s65, s52
	s_cselect_b32 s53, s13, s53
	s_cselect_b32 s52, s19, s71
	s_cselect_b32 s73, s15, s55
	s_cselect_b32 s72, s14, s54
	s_add_i32 s71, 0, 0x14000
	v_add_u32_e32 v142, s74, v230
	v_add_u32_e32 v158, s71, v230
	ds_read_b128 v[114:117], v142
	ds_read_b128 v[126:129], v142 offset:1024
	ds_read_b128 v[138:141], v142 offset:2048
	ds_read_b128 v[142:145], v142 offset:3072
	ds_read_b128 v[146:149], v158
	ds_read_b128 v[150:153], v158 offset:1024
	ds_read_b128 v[154:157], v158 offset:2048
	ds_read_b128 v[158:161], v158 offset:3072
	s_add_i32 m0, s51, 0xc000
	ds_read_b128 v[162:165], v235
	ds_read_b128 v[166:169], v235 offset:1024
	ds_read_b128 v[170:173], v235 offset:2048
	ds_read_b128 v[174:177], v235 offset:3072
	ds_read_b128 v[178:181], v235 offset:4096
	ds_read_b128 v[182:185], v235 offset:5120
	ds_read_b128 v[204:207], v235 offset:6144
	ds_read_b128 v[208:211], v235 offset:7168
	global_load_lds_dwordx4 v200, s[44:45]
	s_add_i32 m0, s51, 0xe000
	s_nop 0
	global_load_lds_dwordx4 v202, s[44:45]
	s_waitcnt vmcnt(8)
	s_waitcnt lgkmcnt(0)
	s_barrier
	s_waitcnt lgkmcnt(0)
	v_mfma_f32_16x16x32_bf16 v[134:137], v[114:117], v[162:165], v[134:137]
	v_mfma_f32_16x16x32_bf16 v[130:133], v[138:141], v[162:165], v[130:133]
	v_mfma_f32_16x16x32_bf16 v[110:113], v[114:117], v[170:173], v[110:113]
	v_mfma_f32_16x16x32_bf16 v[106:109], v[138:141], v[170:173], v[106:109]
	v_mfma_f32_16x16x32_bf16 v[94:97], v[114:117], v[178:181], v[94:97]
	v_mfma_f32_16x16x32_bf16 v[90:93], v[138:141], v[178:181], v[90:93]
	v_mfma_f32_16x16x32_bf16 v[78:81], v[114:117], v[204:207], v[78:81]
	v_mfma_f32_16x16x32_bf16 v[74:77], v[138:141], v[204:207], v[74:77]
	v_mfma_f32_16x16x32_bf16 v[134:137], v[126:129], v[166:169], v[134:137]
	v_mfma_f32_16x16x32_bf16 v[130:133], v[142:145], v[166:169], v[130:133]
	v_mfma_f32_16x16x32_bf16 v[110:113], v[126:129], v[174:177], v[110:113]
	v_mfma_f32_16x16x32_bf16 v[106:109], v[142:145], v[174:177], v[106:109]
	v_mfma_f32_16x16x32_bf16 v[94:97], v[126:129], v[182:185], v[94:97]
	v_mfma_f32_16x16x32_bf16 v[90:93], v[142:145], v[182:185], v[90:93]
	v_mfma_f32_16x16x32_bf16 v[78:81], v[126:129], v[208:211], v[78:81]
	v_mfma_f32_16x16x32_bf16 v[74:77], v[142:145], v[208:211], v[74:77]
	v_mfma_f32_16x16x32_bf16 v[122:125], v[146:149], v[162:165], v[122:125]
	v_mfma_f32_16x16x32_bf16 v[118:121], v[154:157], v[162:165], v[118:121]
	v_mfma_f32_16x16x32_bf16 v[102:105], v[146:149], v[170:173], v[102:105]
	v_mfma_f32_16x16x32_bf16 v[98:101], v[154:157], v[170:173], v[98:101]
	v_mfma_f32_16x16x32_bf16 v[86:89], v[146:149], v[178:181], v[86:89]
	v_mfma_f32_16x16x32_bf16 v[82:85], v[154:157], v[178:181], v[82:85]
	v_mfma_f32_16x16x32_bf16 v[70:73], v[146:149], v[204:207], v[70:73]
	v_mfma_f32_16x16x32_bf16 v[66:69], v[154:157], v[204:207], v[66:69]
	v_mfma_f32_16x16x32_bf16 v[122:125], v[150:153], v[166:169], v[122:125]
	v_mfma_f32_16x16x32_bf16 v[118:121], v[158:161], v[166:169], v[118:121]
	v_mfma_f32_16x16x32_bf16 v[102:105], v[150:153], v[174:177], v[102:105]
	v_mfma_f32_16x16x32_bf16 v[98:101], v[158:161], v[174:177], v[98:101]
	v_mfma_f32_16x16x32_bf16 v[86:89], v[150:153], v[182:185], v[86:89]
	v_mfma_f32_16x16x32_bf16 v[82:85], v[158:161], v[182:185], v[82:85]
	v_mfma_f32_16x16x32_bf16 v[70:73], v[150:153], v[208:211], v[70:73]
	v_mfma_f32_16x16x32_bf16 v[66:69], v[158:161], v[208:211], v[66:69]
	s_barrier
	s_add_i32 s74, s74, s3
	v_lshl_add_u64 v[190:191], s[72:73], 0, v[0:1]
	s_mov_b32 m0, s74
	ds_read_b128 v[162:165], v235 offset:16384
	ds_read_b128 v[166:169], v235 offset:17408
	ds_read_b128 v[170:173], v235 offset:18432
	ds_read_b128 v[174:177], v235 offset:19456
	ds_read_b128 v[178:181], v235 offset:20480
	ds_read_b128 v[182:185], v235 offset:21504
	ds_read_b128 v[204:207], v235 offset:22528
	ds_read_b128 v[208:211], v235 offset:23552
	global_load_lds_dwordx4 v[190:191], off
	s_add_i32 m0, s74, 0x2000
	v_lshl_add_u64 v[192:193], s[72:73], 0, v[198:199]
	s_add_u32 s72, s72, s24
	s_addc_u32 s73, s73, s25
	s_add_i32 s71, s71, s3
	global_load_lds_dwordx4 v[192:193], off
	v_lshl_add_u64 v[212:213], s[72:73], 0, v[0:1]
	s_mov_b32 m0, s71
	v_lshl_add_u64 v[214:215], s[72:73], 0, v[198:199]
	global_load_lds_dwordx4 v[212:213], off
	s_add_i32 m0, s71, 0x2000
	v_lshl_add_u64 v[216:217], s[52:53], 0, v[194:195]
	global_load_lds_dwordx4 v[214:215], off
	s_mov_b32 m0, s51
	v_lshl_add_u64 v[218:219], s[52:53], 0, v[196:197]
	global_load_lds_dwordx4 v[216:217], off
	s_mov_b32 m0, s59
	s_nop 0
	global_load_lds_dwordx4 v[218:219], off
	s_waitcnt vmcnt(8)
	s_waitcnt lgkmcnt(0)
	s_barrier
; #define PG8_STAGE(bufoff, gbase, voff) do { _Pragma("unroll") for (int _i = 0; _i < 2; ++_i) \
;         __builtin_amdgcn_global_load_lds((const unsigned*)((const char*)(gbase) + (voff)[_i]), (PG8_LAS unsigned*)(lds + (bufoff) + ldsw + _i * 8192), 16, 0, 0); } while (0)
; #define PG8_LDA(dst, b, h) do { _Pragma("unroll") for (int m = 0; m < 4; ++m) _Pragma("unroll") for (int k = 0; k < 2; ++k) dst[m][k] = *(const PG8_LAS bf16x8*)(lds + PG8_SA(b, h) + aoff + m * 2048 + k * 1024); } while (0)
; #define PG8_LDB(dst, b, h) do { _Pragma("unroll") for (int n = 0; n < 2; ++n) _Pragma("unroll") for (int k = 0; k < 2; ++k) dst[n][k] = *(const PG8_LAS bf16x8*)(lds + PG8_SB(b, h) + boff + n * 2048 + k * 1024); } while (0)
; #define PG8_MMA(ai, bj, At, Bt) do { __builtin_amdgcn_s_setprio(1); _Pragma("unroll") for (int m = 0; m < 4; ++m) _Pragma("unroll") for (int n = 0; n < 2; ++n) _Pragma("unroll") for (int k = 0; k < 2; ++k) \
;         acc[ai][bj][m][n] = __builtin_amdgcn_mfma_f32_16x16x32_bf16(Bt[n][k], At[m][k], acc[ai][bj][m][n], 0, 0, 0); __builtin_amdgcn_s_setprio(0); } while (0)
; #define PG8_WAIT_V(n) asm volatile("s_waitcnt vmcnt(" #n ")" ::: "memory")
; #define PG8_WAIT_L(n) asm volatile("s_waitcnt lgkmcnt(" #n ")" ::: "memory")
; #define PG8_BAR __builtin_amdgcn_s_barrier()
; #define PG8_SCHED __builtin_amdgcn_sched_barrier(0)
; template <class Epi, class Sched, bool ALIGN_EPI = false, bool SP2 = false>
; __device__ __forceinline__ void gemm_phase(PG8_LAS unsigned char* lds, const Gemm g, const Sched& S, const Epi& E, const int wv) {
;     ...
;             PG8_WAIT_V(8); PG8_WAIT_L(0); PG8_BAR; PG8_MMA(1, 0, At, B0); PG8_MMA(1, 1, At, B1); PG8_BAR; PG8_SCHED;
;             PG8_LDB(B0, 1, 0); PG8_LDB(B1, 1, 1); PG8_SCHED; PG8_LDA(At, 1, 0); PG8_STAGE(PG8_SA(0, 1), a2 + hstepA, voffA);
;             PG8_WAIT_V(8); PG8_WAIT_L(0); PG8_BAR; PG8_MMA(0, 0, At, B0); PG8_MMA(0, 1, At, B1); PG8_BAR; PG8_SCHED;
	s_waitcnt lgkmcnt(0)
	v_mfma_f32_16x16x32_bf16 v[62:65], v[114:117], v[162:165], v[62:65]
	v_mfma_f32_16x16x32_bf16 v[58:61], v[138:141], v[162:165], v[58:61]
	v_mfma_f32_16x16x32_bf16 v[46:49], v[114:117], v[170:173], v[46:49]
	v_mfma_f32_16x16x32_bf16 v[42:45], v[138:141], v[170:173], v[42:45]
	v_mfma_f32_16x16x32_bf16 v[30:33], v[114:117], v[178:181], v[30:33]
	v_mfma_f32_16x16x32_bf16 v[26:29], v[138:141], v[178:181], v[26:29]
	v_mfma_f32_16x16x32_bf16 v[14:17], v[114:117], v[204:207], v[14:17]
	v_mfma_f32_16x16x32_bf16 v[10:13], v[138:141], v[204:207], v[10:13]
	v_mfma_f32_16x16x32_bf16 v[62:65], v[126:129], v[166:169], v[62:65]
	v_mfma_f32_16x16x32_bf16 v[58:61], v[142:145], v[166:169], v[58:61]
	v_mfma_f32_16x16x32_bf16 v[46:49], v[126:129], v[174:177], v[46:49]
	v_mfma_f32_16x16x32_bf16 v[42:45], v[142:145], v[174:177], v[42:45]
	v_mfma_f32_16x16x32_bf16 v[30:33], v[126:129], v[182:185], v[30:33]
	v_mfma_f32_16x16x32_bf16 v[26:29], v[142:145], v[182:185], v[26:29]
	v_mfma_f32_16x16x32_bf16 v[14:17], v[126:129], v[208:211], v[14:17]
	v_mfma_f32_16x16x32_bf16 v[10:13], v[142:145], v[208:211], v[10:13]
	v_mfma_f32_16x16x32_bf16 v[54:57], v[146:149], v[162:165], v[54:57]
	v_mfma_f32_16x16x32_bf16 v[50:53], v[154:157], v[162:165], v[50:53]
	v_mfma_f32_16x16x32_bf16 v[38:41], v[146:149], v[170:173], v[38:41]
	v_mfma_f32_16x16x32_bf16 v[34:37], v[154:157], v[170:173], v[34:37]
	v_mfma_f32_16x16x32_bf16 v[22:25], v[146:149], v[178:181], v[22:25]
	v_mfma_f32_16x16x32_bf16 v[18:21], v[154:157], v[178:181], v[18:21]
	v_mfma_f32_16x16x32_bf16 v[6:9], v[146:149], v[204:207], v[6:9]
	v_mfma_f32_16x16x32_bf16 v[2:5], v[154:157], v[204:207], v[2:5]
	v_mfma_f32_16x16x32_bf16 v[54:57], v[150:153], v[166:169], v[54:57]
	v_mfma_f32_16x16x32_bf16 v[50:53], v[158:161], v[166:169], v[50:53]
	v_mfma_f32_16x16x32_bf16 v[38:41], v[150:153], v[174:177], v[38:41]
	v_mfma_f32_16x16x32_bf16 v[34:37], v[158:161], v[174:177], v[34:37]
	v_mfma_f32_16x16x32_bf16 v[22:25], v[150:153], v[182:185], v[22:25]
	v_mfma_f32_16x16x32_bf16 v[18:21], v[158:161], v[182:185], v[18:21]
	v_mfma_f32_16x16x32_bf16 v[6:9], v[150:153], v[208:211], v[6:9]
	v_mfma_f32_16x16x32_bf16 v[2:5], v[158:161], v[208:211], v[2:5]
	s_barrier
	s_add_i32 s71, 0, 0x18000
	s_add_i32 s72, 0, 0x1c000
	v_add_u32_e32 v142, s71, v230
	v_add_u32_e32 v158, s72, v230
	ds_read_b128 v[114:117], v142
	ds_read_b128 v[126:129], v142 offset:1024
	ds_read_b128 v[138:141], v142 offset:2048
	ds_read_b128 v[142:145], v142 offset:3072
	ds_read_b128 v[146:149], v158
	ds_read_b128 v[150:153], v158 offset:1024
	ds_read_b128 v[154:157], v158 offset:2048
	ds_read_b128 v[158:161], v158 offset:3072
	s_add_u32 s52, s52, 0x40000
	s_addc_u32 s53, s53, 0
	s_mov_b32 m0, s60
	ds_read_b128 v[162:165], v235 offset:32768
	ds_read_b128 v[166:169], v235 offset:33792
	ds_read_b128 v[170:173], v235 offset:34816
	ds_read_b128 v[174:177], v235 offset:35840
	ds_read_b128 v[178:181], v235 offset:36864
	ds_read_b128 v[182:185], v235 offset:37888
	ds_read_b128 v[204:207], v235 offset:38912
	ds_read_b128 v[208:211], v235 offset:39936
	global_load_lds_dwordx4 v194, s[52:53]
	s_mov_b32 m0, s61
	s_nop 0
	global_load_lds_dwordx4 v196, s[52:53]
	s_waitcnt vmcnt(8)
	s_waitcnt lgkmcnt(0)
	s_barrier
	s_waitcnt lgkmcnt(0)
	v_mfma_f32_16x16x32_bf16 v[134:137], v[114:117], v[162:165], v[134:137]
	v_mfma_f32_16x16x32_bf16 v[130:133], v[138:141], v[162:165], v[130:133]
	v_mfma_f32_16x16x32_bf16 v[110:113], v[114:117], v[170:173], v[110:113]
	v_mfma_f32_16x16x32_bf16 v[106:109], v[138:141], v[170:173], v[106:109]
	v_mfma_f32_16x16x32_bf16 v[94:97], v[114:117], v[178:181], v[94:97]
	v_mfma_f32_16x16x32_bf16 v[90:93], v[138:141], v[178:181], v[90:93]
	v_mfma_f32_16x16x32_bf16 v[78:81], v[114:117], v[204:207], v[78:81]
	v_mfma_f32_16x16x32_bf16 v[74:77], v[138:141], v[204:207], v[74:77]
	v_mfma_f32_16x16x32_bf16 v[134:137], v[126:129], v[166:169], v[134:137]
	v_mfma_f32_16x16x32_bf16 v[130:133], v[142:145], v[166:169], v[130:133]
	v_mfma_f32_16x16x32_bf16 v[110:113], v[126:129], v[174:177], v[110:113]
	v_mfma_f32_16x16x32_bf16 v[106:109], v[142:145], v[174:177], v[106:109]
	v_mfma_f32_16x16x32_bf16 v[94:97], v[126:129], v[182:185], v[94:97]
	v_mfma_f32_16x16x32_bf16 v[90:93], v[142:145], v[182:185], v[90:93]
	v_mfma_f32_16x16x32_bf16 v[78:81], v[126:129], v[208:211], v[78:81]
	v_mfma_f32_16x16x32_bf16 v[74:77], v[142:145], v[208:211], v[74:77]
	v_mfma_f32_16x16x32_bf16 v[122:125], v[146:149], v[162:165], v[122:125]
	v_mfma_f32_16x16x32_bf16 v[118:121], v[154:157], v[162:165], v[118:121]
	v_mfma_f32_16x16x32_bf16 v[102:105], v[146:149], v[170:173], v[102:105]
	v_mfma_f32_16x16x32_bf16 v[98:101], v[154:157], v[170:173], v[98:101]
	v_mfma_f32_16x16x32_bf16 v[86:89], v[146:149], v[178:181], v[86:89]
	v_mfma_f32_16x16x32_bf16 v[82:85], v[154:157], v[178:181], v[82:85]
	v_mfma_f32_16x16x32_bf16 v[70:73], v[146:149], v[204:207], v[70:73]
	v_mfma_f32_16x16x32_bf16 v[66:69], v[154:157], v[204:207], v[66:69]
	v_mfma_f32_16x16x32_bf16 v[122:125], v[150:153], v[166:169], v[122:125]
	v_mfma_f32_16x16x32_bf16 v[118:121], v[158:161], v[166:169], v[118:121]
	v_mfma_f32_16x16x32_bf16 v[102:105], v[150:153], v[174:177], v[102:105]
	v_mfma_f32_16x16x32_bf16 v[98:101], v[158:161], v[174:177], v[98:101]
	v_mfma_f32_16x16x32_bf16 v[86:89], v[150:153], v[182:185], v[86:89]
	v_mfma_f32_16x16x32_bf16 v[82:85], v[158:161], v[182:185], v[82:85]
	v_mfma_f32_16x16x32_bf16 v[70:73], v[150:153], v[208:211], v[70:73]
	v_mfma_f32_16x16x32_bf16 v[66:69], v[158:161], v[208:211], v[66:69]
	s_barrier
; #define PG8_STAGE(bufoff, gbase, voff) do { _Pragma("unroll") for (int _i = 0; _i < 2; ++_i) \
;         __builtin_amdgcn_global_load_lds((const unsigned*)((const char*)(gbase) + (voff)[_i]), (PG8_LAS unsigned*)(lds + (bufoff) + ldsw + _i * 8192), 16, 0, 0); } while (0)
; #define PG8_LDA(dst, b, h) do { _Pragma("unroll") for (int m = 0; m < 4; ++m) _Pragma("unroll") for (int k = 0; k < 2; ++k) dst[m][k] = *(const PG8_LAS bf16x8*)(lds + PG8_SA(b, h) + aoff + m * 2048 + k * 1024); } while (0)
; #define PG8_MMA(ai, bj, At, Bt) do { __builtin_amdgcn_s_setprio(1); _Pragma("unroll") for (int m = 0; m < 4; ++m) _Pragma("unroll") for (int n = 0; n < 2; ++n) _Pragma("unroll") for (int k = 0; k < 2; ++k) \
;         acc[ai][bj][m][n] = __builtin_amdgcn_mfma_f32_16x16x32_bf16(Bt[n][k], At[m][k], acc[ai][bj][m][n], 0, 0, 0); __builtin_amdgcn_s_setprio(0); } while (0)
; #define PG8_WAIT_V(n) asm volatile("s_waitcnt vmcnt(" #n ")" ::: "memory")
; #define PG8_WAIT_L(n) asm volatile("s_waitcnt lgkmcnt(" #n ")" ::: "memory")
; #define PG8_BAR __builtin_amdgcn_s_barrier()
; #define PG8_SCHED __builtin_amdgcn_sched_barrier(0)
; template <class Epi, class Sched, bool ALIGN_EPI = false, bool SP2 = false>
; __device__ __forceinline__ void gemm_phase(PG8_LAS unsigned char* lds, const Gemm g, const Sched& S, const Epi& E, const int wv) {
;     ...
;             PG8_LDA(At, 1, 1); PG8_STAGE(PG8_SB(1, 0), b3, voffB); PG8_STAGE(PG8_SB(1, 1), b3 + hstepB, voffB); PG8_STAGE(PG8_SA(1, 0), a3, voffA);
;             PG8_WAIT_V(8); PG8_WAIT_L(0); PG8_BAR; PG8_MMA(1, 0, At, B0); PG8_MMA(1, 1, At, B1); PG8_BAR; PG8_SCHED;
	s_add_i32 s52, s71, s3
	s_add_i32 m0, s52, 0xffffff80
	ds_read_b128 v[162:165], v235 offset:49152
	ds_read_b128 v[166:169], v235 offset:50176
	ds_read_b128 v[170:173], v235 offset:51200
	ds_read_b128 v[174:177], v235 offset:52224
	ds_read_b128 v[178:181], v235 offset:53248
	ds_read_b128 v[182:185], v235 offset:54272
	ds_read_b128 v[204:207], v235 offset:55296
	ds_read_b128 v[208:211], v235 offset:56320
	global_load_lds_dwordx4 v[190:191], off offset:128
	s_add_i32 m0, s52, 0x1f80
	s_add_i32 s52, s72, s3
	global_load_lds_dwordx4 v[192:193], off offset:128
	s_add_i32 m0, s52, 0xffffff80
	s_nop 0
	global_load_lds_dwordx4 v[212:213], off offset:128
	s_add_i32 m0, s52, 0x1f80
	s_nop 0
	global_load_lds_dwordx4 v[214:215], off offset:128
	s_add_i32 m0, s63, 0xffffff80
	s_nop 0
	global_load_lds_dwordx4 v[216:217], off offset:128
	s_add_i32 m0, s64, 0xffffff80
	s_nop 0
	global_load_lds_dwordx4 v[218:219], off offset:128
	s_waitcnt vmcnt(8)
	s_waitcnt lgkmcnt(0)
	s_barrier
	s_waitcnt lgkmcnt(0)
	v_mfma_f32_16x16x32_bf16 v[62:65], v[114:117], v[162:165], v[62:65]
	v_mfma_f32_16x16x32_bf16 v[58:61], v[138:141], v[162:165], v[58:61]
	v_mfma_f32_16x16x32_bf16 v[46:49], v[114:117], v[170:173], v[46:49]
	v_mfma_f32_16x16x32_bf16 v[42:45], v[138:141], v[170:173], v[42:45]
	v_mfma_f32_16x16x32_bf16 v[30:33], v[114:117], v[178:181], v[30:33]
	v_mfma_f32_16x16x32_bf16 v[26:29], v[138:141], v[178:181], v[26:29]
	v_mfma_f32_16x16x32_bf16 v[14:17], v[114:117], v[204:207], v[14:17]
	v_mfma_f32_16x16x32_bf16 v[10:13], v[138:141], v[204:207], v[10:13]
	v_mfma_f32_16x16x32_bf16 v[62:65], v[126:129], v[166:169], v[62:65]
	v_mfma_f32_16x16x32_bf16 v[58:61], v[142:145], v[166:169], v[58:61]
	v_mfma_f32_16x16x32_bf16 v[46:49], v[126:129], v[174:177], v[46:49]
	v_mfma_f32_16x16x32_bf16 v[42:45], v[142:145], v[174:177], v[42:45]
	v_mfma_f32_16x16x32_bf16 v[30:33], v[126:129], v[182:185], v[30:33]
	v_mfma_f32_16x16x32_bf16 v[26:29], v[142:145], v[182:185], v[26:29]
	v_mfma_f32_16x16x32_bf16 v[14:17], v[126:129], v[208:211], v[14:17]
	v_mfma_f32_16x16x32_bf16 v[10:13], v[142:145], v[208:211], v[10:13]
	v_mfma_f32_16x16x32_bf16 v[54:57], v[146:149], v[162:165], v[54:57]
	v_mfma_f32_16x16x32_bf16 v[50:53], v[154:157], v[162:165], v[50:53]
	v_mfma_f32_16x16x32_bf16 v[38:41], v[146:149], v[170:173], v[38:41]
	v_mfma_f32_16x16x32_bf16 v[34:37], v[154:157], v[170:173], v[34:37]
	v_mfma_f32_16x16x32_bf16 v[22:25], v[146:149], v[178:181], v[22:25]
	v_mfma_f32_16x16x32_bf16 v[18:21], v[154:157], v[178:181], v[18:21]
	v_mfma_f32_16x16x32_bf16 v[6:9], v[146:149], v[204:207], v[6:9]
	v_mfma_f32_16x16x32_bf16 v[2:5], v[154:157], v[204:207], v[2:5]
	v_mfma_f32_16x16x32_bf16 v[54:57], v[150:153], v[166:169], v[54:57]
	v_mfma_f32_16x16x32_bf16 v[50:53], v[158:161], v[166:169], v[50:53]
	v_mfma_f32_16x16x32_bf16 v[38:41], v[150:153], v[174:177], v[38:41]
	v_mfma_f32_16x16x32_bf16 v[34:37], v[158:161], v[174:177], v[34:37]
	v_mfma_f32_16x16x32_bf16 v[22:25], v[150:153], v[182:185], v[22:25]
	v_mfma_f32_16x16x32_bf16 v[18:21], v[158:161], v[182:185], v[18:21]
	v_mfma_f32_16x16x32_bf16 v[6:9], v[150:153], v[208:211], v[6:9]
	v_mfma_f32_16x16x32_bf16 v[2:5], v[158:161], v[208:211], v[2:5]
	s_barrier
	s_add_u32 s44, s44, 0x100
	s_addc_u32 s45, s45, 0
	s_add_u32 s54, s54, 0x100
	s_addc_u32 s55, s55, 0
	s_cmp_ge_i32 s70, s62
	s_mov_b32 s52, s70
	s_cbranch_scc0 .LBB0_1385
	s_mov_b32 s72, 0x10000
	s_mov_b32 s73, 0x12000
	s_mov_b32 s74, 0x14000
	s_mov_b32 s70, 0x18000
	s_mov_b32 s71, 0x3f317217
	s_and_b64 vcc, exec, s[46:47]
	s_cbranch_vccz .LBB0_1361

; #define PG8_STAGE(bufoff, gbase, voff) do { _Pragma("unroll") for (int _i = 0; _i < 2; ++_i) \
;         __builtin_amdgcn_global_load_lds((const unsigned*)((const char*)(gbase) + (voff)[_i]), (PG8_LAS unsigned*)(lds + (bufoff) + ldsw + _i * 8192), 16, 0, 0); } while (0)
; #define PG8_LDA(dst, b, h) do { _Pragma("unroll") for (int m = 0; m < 4; ++m) _Pragma("unroll") for (int k = 0; k < 2; ++k) dst[m][k] = *(const PG8_LAS bf16x8*)(lds + PG8_SA(b, h) + aoff + m * 2048 + k * 1024); } while (0)
; #define PG8_LDB(dst, b, h) do { _Pragma("unroll") for (int n = 0; n < 2; ++n) _Pragma("unroll") for (int k = 0; k < 2; ++k) dst[n][k] = *(const PG8_LAS bf16x8*)(lds + PG8_SB(b, h) + boff + n * 2048 + k * 1024); } while (0)
; #define PG8_MMA(ai, bj, At, Bt) do { __builtin_amdgcn_s_setprio(1); _Pragma("unroll") for (int m = 0; m < 4; ++m) _Pragma("unroll") for (int n = 0; n < 2; ++n) _Pragma("unroll") for (int k = 0; k < 2; ++k) \
;         acc[ai][bj][m][n] = __builtin_amdgcn_mfma_f32_16x16x32_bf16(Bt[n][k], At[m][k], acc[ai][bj][m][n], 0, 0, 0); __builtin_amdgcn_s_setprio(0); } while (0)
; #define PG8_WAIT_V(n) asm volatile("s_waitcnt vmcnt(" #n ")" ::: "memory")
; #define PG8_BAR __builtin_amdgcn_s_barrier()
; template <class Epi, class Sched, bool ALIGN_EPI = false, bool SP2 = false>
; __device__ __forceinline__ void gemm_phase(PG8_LAS unsigned char* lds, const Gemm g, const Sched& S, const Epi& E, const int wv) {
;     ...
;         for (int t = 0; t < nt; t += 2) {
;             const bool last = (t == nt - 2);
;             const char* a1 = cA + (size_t)(t + 1) * kstep;
;             const char* a2 = last ? nA : cA + (size_t)(t + 2) * kstep; const char* b2 = last ? nB : cB + (size_t)(t + 2) * kstep;
;             const char* a3 = a2 + kstep; const char* b3 = b2 + kstep;
;             if (last && has_next) S.a_ready(nxt);
;             if constexpr (SP2) {
;             PG8_LDB(B0, 0, 0); PG8_LDB(B1, 0, 1); PG8_SCHED; PG8_LDA(At, 0, 0); PG8_STAGE(PG8_SA(1, 1), a1 + hstepA, voffA);
;             PG8_WAIT_V(8); PG8_WAIT_L(0); PG8_BAR; PG8_MMA(0, 0, At, B0); PG8_MMA(0, 1, At, B1); PG8_BAR; PG8_SCHED;
;             PG8_LDA(At, 0, 1); PG8_STAGE(PG8_SB(0, 0), b2, voffB); PG8_STAGE(PG8_SB(0, 1), b2 + hstepB, voffB); PG8_STAGE(PG8_SA(0, 0), a2, voffA);
;             PG8_WAIT_V(8); PG8_WAIT_L(0); PG8_BAR; PG8_MMA(1, 0, At, B0); PG8_MMA(1, 1, At, B1); PG8_BAR; PG8_SCHED;
.LBB0_1495:
	s_add_i32 s52, s46, 2
	s_add_u32 s14, s48, 0x100
	s_addc_u32 s15, s49, 0
	s_add_i32 s53, 0, 0x10000
	s_cmp_eq_u32 s72, s46
	s_cselect_b32 s47, s11, s15
	s_cselect_b32 s46, s13, s14
	s_cselect_b32 s77, s87, s51
	s_cselect_b32 s76, s86, s35
	s_add_i32 s78, 0, 0x14000
	v_add_u32_e32 v150, s53, v208
	v_add_u32_e32 v166, s78, v208
	ds_read_b128 v[138:141], v150
	ds_read_b128 v[142:145], v150 offset:1024
	ds_read_b128 v[146:149], v150 offset:2048
	ds_read_b128 v[150:153], v150 offset:3072
	ds_read_b128 v[154:157], v166
	ds_read_b128 v[158:161], v166 offset:1024
	ds_read_b128 v[162:165], v166 offset:2048
	ds_read_b128 v[166:169], v166 offset:3072
	v_lshl_add_u64 v[190:191], s[48:49], 0, v[182:183]
	s_add_i32 m0, s64, 0xc000
	ds_read_b128 v[194:197], v211
	ds_read_b128 v[198:201], v211 offset:1024
	ds_read_b128 v[202:205], v211 offset:2048
	ds_read_b128 v[214:217], v211 offset:3072
	ds_read_b128 v[228:231], v211 offset:4096
	ds_read_b128 v[232:235], v211 offset:5120
	ds_read_b128 v[236:239], v211 offset:6144
	ds_read_b128 v[240:243], v211 offset:7168
	global_load_lds_dwordx4 v[190:191], off
	v_lshl_add_u64 v[190:191], s[48:49], 0, v[184:185]
	s_add_i32 m0, s64, 0xe000
	s_nop 0
	global_load_lds_dwordx4 v[190:191], off
	s_waitcnt vmcnt(8)
	s_waitcnt lgkmcnt(0)
	s_barrier
	s_waitcnt lgkmcnt(0)
	v_mfma_f32_16x16x32_bf16 v[118:121], v[138:141], v[194:197], v[118:121]
	v_mfma_f32_16x16x32_bf16 v[46:49], v[146:149], v[194:197], v[46:49]
	v_mfma_f32_16x16x32_bf16 v[110:113], v[138:141], v[202:205], v[110:113]
	v_mfma_f32_16x16x32_bf16 v[38:41], v[146:149], v[202:205], v[38:41]
	v_mfma_f32_16x16x32_bf16 v[134:137], v[138:141], v[228:231], v[134:137]
	v_mfma_f32_16x16x32_bf16 v[62:65], v[146:149], v[228:231], v[62:65]
	v_mfma_f32_16x16x32_bf16 v[130:133], v[138:141], v[236:239], v[130:133]
	v_mfma_f32_16x16x32_bf16 v[58:61], v[146:149], v[236:239], v[58:61]
	v_mfma_f32_16x16x32_bf16 v[118:121], v[142:145], v[198:201], v[118:121]
	v_mfma_f32_16x16x32_bf16 v[46:49], v[150:153], v[198:201], v[46:49]
	v_mfma_f32_16x16x32_bf16 v[110:113], v[142:145], v[214:217], v[110:113]
	v_mfma_f32_16x16x32_bf16 v[38:41], v[150:153], v[214:217], v[38:41]
	v_mfma_f32_16x16x32_bf16 v[134:137], v[142:145], v[232:235], v[134:137]
	v_mfma_f32_16x16x32_bf16 v[62:65], v[150:153], v[232:235], v[62:65]
	v_mfma_f32_16x16x32_bf16 v[130:133], v[142:145], v[240:243], v[130:133]
	v_mfma_f32_16x16x32_bf16 v[58:61], v[150:153], v[240:243], v[58:61]
	v_mfma_f32_16x16x32_bf16 v[114:117], v[154:157], v[194:197], v[114:117]
	v_mfma_f32_16x16x32_bf16 v[42:45], v[162:165], v[194:197], v[42:45]
	v_mfma_f32_16x16x32_bf16 v[106:109], v[154:157], v[202:205], v[106:109]
	v_mfma_f32_16x16x32_bf16 v[34:37], v[162:165], v[202:205], v[34:37]
	v_mfma_f32_16x16x32_bf16 v[126:129], v[154:157], v[228:231], v[126:129]
	v_mfma_f32_16x16x32_bf16 v[54:57], v[162:165], v[228:231], v[54:57]
	v_mfma_f32_16x16x32_bf16 v[122:125], v[154:157], v[236:239], v[122:125]
	v_mfma_f32_16x16x32_bf16 v[50:53], v[162:165], v[236:239], v[50:53]
	v_mfma_f32_16x16x32_bf16 v[114:117], v[158:161], v[198:201], v[114:117]
	v_mfma_f32_16x16x32_bf16 v[42:45], v[166:169], v[198:201], v[42:45]
	v_mfma_f32_16x16x32_bf16 v[106:109], v[158:161], v[214:217], v[106:109]
	v_mfma_f32_16x16x32_bf16 v[34:37], v[166:169], v[214:217], v[34:37]
	v_mfma_f32_16x16x32_bf16 v[126:129], v[158:161], v[232:235], v[126:129]
	v_mfma_f32_16x16x32_bf16 v[54:57], v[166:169], v[232:235], v[54:57]
	v_mfma_f32_16x16x32_bf16 v[122:125], v[158:161], v[240:243], v[122:125]
	v_mfma_f32_16x16x32_bf16 v[50:53], v[166:169], v[240:243], v[50:53]
	s_barrier
	s_add_i32 s48, s53, s63
	v_lshl_add_u64 v[190:191], s[76:77], 0, v[0:1]
	s_mov_b32 m0, s48
	ds_read_b128 v[194:197], v211 offset:16384
	ds_read_b128 v[198:201], v211 offset:17408
	ds_read_b128 v[202:205], v211 offset:18432
	ds_read_b128 v[214:217], v211 offset:19456
	ds_read_b128 v[228:231], v211 offset:20480
	ds_read_b128 v[232:235], v211 offset:21504
	ds_read_b128 v[236:239], v211 offset:22528
	ds_read_b128 v[240:243], v211 offset:23552
	global_load_lds_dwordx4 v[190:191], off
	s_add_i32 m0, s48, 0x2000
	s_add_u32 s48, s76, s16
	v_lshl_add_u64 v[192:193], s[76:77], 0, v[174:175]
	s_addc_u32 s49, s77, s17
	s_add_i32 s53, s78, s63
	global_load_lds_dwordx4 v[192:193], off
	v_lshl_add_u64 v[218:219], s[48:49], 0, v[0:1]
	s_mov_b32 m0, s53
	v_lshl_add_u64 v[244:245], s[48:49], 0, v[174:175]
	global_load_lds_dwordx4 v[218:219], off
	s_add_i32 m0, s53, 0x2000
	v_lshl_add_u64 v[246:247], s[46:47], 0, v[170:171]
	global_load_lds_dwordx4 v[244:245], off
	s_mov_b32 m0, s64
	v_lshl_add_u64 v[248:249], s[46:47], 0, v[172:173]
	global_load_lds_dwordx4 v[246:247], off
	s_mov_b32 m0, s65
	s_nop 0
	global_load_lds_dwordx4 v[248:249], off
	s_waitcnt vmcnt(8)
	s_waitcnt lgkmcnt(0)
	s_barrier
; #define PG8_STAGE(bufoff, gbase, voff) do { _Pragma("unroll") for (int _i = 0; _i < 2; ++_i) \
;         __builtin_amdgcn_global_load_lds((const unsigned*)((const char*)(gbase) + (voff)[_i]), (PG8_LAS unsigned*)(lds + (bufoff) + ldsw + _i * 8192), 16, 0, 0); } while (0)
; #define PG8_LDA(dst, b, h) do { _Pragma("unroll") for (int m = 0; m < 4; ++m) _Pragma("unroll") for (int k = 0; k < 2; ++k) dst[m][k] = *(const PG8_LAS bf16x8*)(lds + PG8_SA(b, h) + aoff + m * 2048 + k * 1024); } while (0)
; #define PG8_LDB(dst, b, h) do { _Pragma("unroll") for (int n = 0; n < 2; ++n) _Pragma("unroll") for (int k = 0; k < 2; ++k) dst[n][k] = *(const PG8_LAS bf16x8*)(lds + PG8_SB(b, h) + boff + n * 2048 + k * 1024); } while (0)
; #define PG8_MMA(ai, bj, At, Bt) do { __builtin_amdgcn_s_setprio(1); _Pragma("unroll") for (int m = 0; m < 4; ++m) _Pragma("unroll") for (int n = 0; n < 2; ++n) _Pragma("unroll") for (int k = 0; k < 2; ++k) \
;         acc[ai][bj][m][n] = __builtin_amdgcn_mfma_f32_16x16x32_bf16(Bt[n][k], At[m][k], acc[ai][bj][m][n], 0, 0, 0); __builtin_amdgcn_s_setprio(0); } while (0)
; #define PG8_WAIT_V(n) asm volatile("s_waitcnt vmcnt(" #n ")" ::: "memory")
; #define PG8_WAIT_L(n) asm volatile("s_waitcnt lgkmcnt(" #n ")" ::: "memory")
; #define PG8_BAR __builtin_amdgcn_s_barrier()
; #define PG8_SCHED __builtin_amdgcn_sched_barrier(0)
; template <class Epi, class Sched, bool ALIGN_EPI = false, bool SP2 = false>
; __device__ __forceinline__ void gemm_phase(PG8_LAS unsigned char* lds, const Gemm g, const Sched& S, const Epi& E, const int wv) {
;     ...
;             PG8_WAIT_V(8); PG8_WAIT_L(0); PG8_BAR; PG8_MMA(1, 0, At, B0); PG8_MMA(1, 1, At, B1); PG8_BAR; PG8_SCHED;
;             PG8_LDB(B0, 1, 0); PG8_LDB(B1, 1, 1); PG8_SCHED; PG8_LDA(At, 1, 0); PG8_STAGE(PG8_SA(0, 1), a2 + hstepA, voffA);
;             PG8_WAIT_V(8); PG8_WAIT_L(0); PG8_BAR; PG8_MMA(0, 0, At, B0); PG8_MMA(0, 1, At, B1); PG8_BAR; PG8_SCHED;
	s_waitcnt lgkmcnt(0)
	v_mfma_f32_16x16x32_bf16 v[86:89], v[138:141], v[194:197], v[86:89]
	v_mfma_f32_16x16x32_bf16 v[14:17], v[146:149], v[194:197], v[14:17]
	v_mfma_f32_16x16x32_bf16 v[70:73], v[138:141], v[202:205], v[70:73]
	v_mfma_f32_16x16x32_bf16 v[6:9], v[146:149], v[202:205], v[6:9]
	v_mfma_f32_16x16x32_bf16 v[102:105], v[138:141], v[228:231], v[102:105]
	v_mfma_f32_16x16x32_bf16 v[30:33], v[146:149], v[228:231], v[30:33]
	v_mfma_f32_16x16x32_bf16 v[98:101], v[138:141], v[236:239], v[98:101]
	v_mfma_f32_16x16x32_bf16 v[26:29], v[146:149], v[236:239], v[26:29]
	v_mfma_f32_16x16x32_bf16 v[86:89], v[142:145], v[198:201], v[86:89]
	v_mfma_f32_16x16x32_bf16 v[14:17], v[150:153], v[198:201], v[14:17]
	v_mfma_f32_16x16x32_bf16 v[70:73], v[142:145], v[214:217], v[70:73]
	v_mfma_f32_16x16x32_bf16 v[6:9], v[150:153], v[214:217], v[6:9]
	v_mfma_f32_16x16x32_bf16 v[102:105], v[142:145], v[232:235], v[102:105]
	v_mfma_f32_16x16x32_bf16 v[30:33], v[150:153], v[232:235], v[30:33]
	v_mfma_f32_16x16x32_bf16 v[98:101], v[142:145], v[240:243], v[98:101]
	v_mfma_f32_16x16x32_bf16 v[26:29], v[150:153], v[240:243], v[26:29]
	v_mfma_f32_16x16x32_bf16 v[82:85], v[154:157], v[194:197], v[82:85]
	v_mfma_f32_16x16x32_bf16 v[10:13], v[162:165], v[194:197], v[10:13]
	v_mfma_f32_16x16x32_bf16 v[66:69], v[154:157], v[202:205], v[66:69]
	v_mfma_f32_16x16x32_bf16 v[2:5], v[162:165], v[202:205], v[2:5]
	v_mfma_f32_16x16x32_bf16 v[94:97], v[154:157], v[228:231], v[94:97]
	v_mfma_f32_16x16x32_bf16 v[22:25], v[162:165], v[228:231], v[22:25]
	v_mfma_f32_16x16x32_bf16 v[90:93], v[154:157], v[236:239], v[90:93]
	v_mfma_f32_16x16x32_bf16 v[18:21], v[162:165], v[236:239], v[18:21]
	v_mfma_f32_16x16x32_bf16 v[82:85], v[158:161], v[198:201], v[82:85]
	v_mfma_f32_16x16x32_bf16 v[10:13], v[166:169], v[198:201], v[10:13]
	v_mfma_f32_16x16x32_bf16 v[66:69], v[158:161], v[214:217], v[66:69]
	v_mfma_f32_16x16x32_bf16 v[2:5], v[166:169], v[214:217], v[2:5]
	v_mfma_f32_16x16x32_bf16 v[94:97], v[158:161], v[232:235], v[94:97]
	v_mfma_f32_16x16x32_bf16 v[22:25], v[166:169], v[232:235], v[22:25]
	v_mfma_f32_16x16x32_bf16 v[90:93], v[158:161], v[240:243], v[90:93]
	v_mfma_f32_16x16x32_bf16 v[18:21], v[166:169], v[240:243], v[18:21]
	s_barrier
	s_add_i32 s48, 0, 0x18000
	s_add_i32 s49, 0, 0x1c000
	v_add_u32_e32 v150, s48, v208
	v_add_u32_e32 v166, s49, v208
	ds_read_b128 v[138:141], v150
	ds_read_b128 v[142:145], v150 offset:1024
	ds_read_b128 v[146:149], v150 offset:2048
	ds_read_b128 v[150:153], v150 offset:3072
	ds_read_b128 v[154:157], v166
	ds_read_b128 v[158:161], v166 offset:1024
	ds_read_b128 v[162:165], v166 offset:2048
	ds_read_b128 v[166:169], v166 offset:3072
	s_add_u32 s46, s46, 0x80000
	s_addc_u32 s47, s47, 0
	s_mov_b32 m0, s66
	ds_read_b128 v[194:197], v211 offset:32768
	ds_read_b128 v[198:201], v211 offset:33792
	ds_read_b128 v[202:205], v211 offset:34816
	ds_read_b128 v[214:217], v211 offset:35840
	ds_read_b128 v[228:231], v211 offset:36864
	ds_read_b128 v[232:235], v211 offset:37888
	ds_read_b128 v[236:239], v211 offset:38912
	ds_read_b128 v[240:243], v211 offset:39936
	global_load_lds_dwordx4 v170, s[46:47]
	s_mov_b32 m0, s67
	s_nop 0
	global_load_lds_dwordx4 v172, s[46:47]
	s_waitcnt vmcnt(8)
	s_waitcnt lgkmcnt(0)
	s_barrier
	s_waitcnt lgkmcnt(0)
	v_mfma_f32_16x16x32_bf16 v[118:121], v[138:141], v[194:197], v[118:121]
	v_mfma_f32_16x16x32_bf16 v[46:49], v[146:149], v[194:197], v[46:49]
	v_mfma_f32_16x16x32_bf16 v[110:113], v[138:141], v[202:205], v[110:113]
	v_mfma_f32_16x16x32_bf16 v[38:41], v[146:149], v[202:205], v[38:41]
	v_mfma_f32_16x16x32_bf16 v[134:137], v[138:141], v[228:231], v[134:137]
	v_mfma_f32_16x16x32_bf16 v[62:65], v[146:149], v[228:231], v[62:65]
	v_mfma_f32_16x16x32_bf16 v[130:133], v[138:141], v[236:239], v[130:133]
	v_mfma_f32_16x16x32_bf16 v[58:61], v[146:149], v[236:239], v[58:61]
	v_mfma_f32_16x16x32_bf16 v[118:121], v[142:145], v[198:201], v[118:121]
	v_mfma_f32_16x16x32_bf16 v[46:49], v[150:153], v[198:201], v[46:49]
	v_mfma_f32_16x16x32_bf16 v[110:113], v[142:145], v[214:217], v[110:113]
	v_mfma_f32_16x16x32_bf16 v[38:41], v[150:153], v[214:217], v[38:41]
	v_mfma_f32_16x16x32_bf16 v[134:137], v[142:145], v[232:235], v[134:137]
	v_mfma_f32_16x16x32_bf16 v[62:65], v[150:153], v[232:235], v[62:65]
	v_mfma_f32_16x16x32_bf16 v[130:133], v[142:145], v[240:243], v[130:133]
	v_mfma_f32_16x16x32_bf16 v[58:61], v[150:153], v[240:243], v[58:61]
	v_mfma_f32_16x16x32_bf16 v[114:117], v[154:157], v[194:197], v[114:117]
	v_mfma_f32_16x16x32_bf16 v[42:45], v[162:165], v[194:197], v[42:45]
	v_mfma_f32_16x16x32_bf16 v[106:109], v[154:157], v[202:205], v[106:109]
	v_mfma_f32_16x16x32_bf16 v[34:37], v[162:165], v[202:205], v[34:37]
	v_mfma_f32_16x16x32_bf16 v[126:129], v[154:157], v[228:231], v[126:129]
	v_mfma_f32_16x16x32_bf16 v[54:57], v[162:165], v[228:231], v[54:57]
	v_mfma_f32_16x16x32_bf16 v[122:125], v[154:157], v[236:239], v[122:125]
	v_mfma_f32_16x16x32_bf16 v[50:53], v[162:165], v[236:239], v[50:53]
	v_mfma_f32_16x16x32_bf16 v[114:117], v[158:161], v[198:201], v[114:117]
	v_mfma_f32_16x16x32_bf16 v[42:45], v[166:169], v[198:201], v[42:45]
	v_mfma_f32_16x16x32_bf16 v[106:109], v[158:161], v[214:217], v[106:109]
	v_mfma_f32_16x16x32_bf16 v[34:37], v[166:169], v[214:217], v[34:37]
	v_mfma_f32_16x16x32_bf16 v[126:129], v[158:161], v[232:235], v[126:129]
	v_mfma_f32_16x16x32_bf16 v[54:57], v[166:169], v[232:235], v[54:57]
	v_mfma_f32_16x16x32_bf16 v[122:125], v[158:161], v[240:243], v[122:125]
	v_mfma_f32_16x16x32_bf16 v[50:53], v[166:169], v[240:243], v[50:53]
	s_barrier
; #define PG8_STAGE(bufoff, gbase, voff) do { _Pragma("unroll") for (int _i = 0; _i < 2; ++_i) \
;         __builtin_amdgcn_global_load_lds((const unsigned*)((const char*)(gbase) + (voff)[_i]), (PG8_LAS unsigned*)(lds + (bufoff) + ldsw + _i * 8192), 16, 0, 0); } while (0)
; #define PG8_LDA(dst, b, h) do { _Pragma("unroll") for (int m = 0; m < 4; ++m) _Pragma("unroll") for (int k = 0; k < 2; ++k) dst[m][k] = *(const PG8_LAS bf16x8*)(lds + PG8_SA(b, h) + aoff + m * 2048 + k * 1024); } while (0)
; #define PG8_MMA(ai, bj, At, Bt) do { __builtin_amdgcn_s_setprio(1); _Pragma("unroll") for (int m = 0; m < 4; ++m) _Pragma("unroll") for (int n = 0; n < 2; ++n) _Pragma("unroll") for (int k = 0; k < 2; ++k) \
;         acc[ai][bj][m][n] = __builtin_amdgcn_mfma_f32_16x16x32_bf16(Bt[n][k], At[m][k], acc[ai][bj][m][n], 0, 0, 0); __builtin_amdgcn_s_setprio(0); } while (0)
; #define PG8_WAIT_V(n) asm volatile("s_waitcnt vmcnt(" #n ")" ::: "memory")
; #define PG8_WAIT_L(n) asm volatile("s_waitcnt lgkmcnt(" #n ")" ::: "memory")
; #define PG8_BAR __builtin_amdgcn_s_barrier()
; #define PG8_SCHED __builtin_amdgcn_sched_barrier(0)
; template <class Epi, class Sched, bool ALIGN_EPI = false, bool SP2 = false>
; __device__ __forceinline__ void gemm_phase(PG8_LAS unsigned char* lds, const Gemm g, const Sched& S, const Epi& E, const int wv) {
;     ...
;             PG8_LDA(At, 1, 1); PG8_STAGE(PG8_SB(1, 0), b3, voffB); PG8_STAGE(PG8_SB(1, 1), b3 + hstepB, voffB); PG8_STAGE(PG8_SA(1, 0), a3, voffA);
;             PG8_WAIT_V(8); PG8_WAIT_L(0); PG8_BAR; PG8_MMA(1, 0, At, B0); PG8_MMA(1, 1, At, B1); PG8_BAR; PG8_SCHED;
	s_add_i32 s46, s48, s63
	s_add_i32 m0, s46, 0xffffff80
	ds_read_b128 v[194:197], v211 offset:49152
	ds_read_b128 v[198:201], v211 offset:50176
	ds_read_b128 v[202:205], v211 offset:51200
	ds_read_b128 v[214:217], v211 offset:52224
	ds_read_b128 v[228:231], v211 offset:53248
	ds_read_b128 v[232:235], v211 offset:54272
	ds_read_b128 v[236:239], v211 offset:55296
	ds_read_b128 v[240:243], v211 offset:56320
	global_load_lds_dwordx4 v[190:191], off offset:128
	s_add_i32 m0, s46, 0x1f80
	s_add_i32 s46, s49, s63
	global_load_lds_dwordx4 v[192:193], off offset:128
	s_add_i32 m0, s46, 0xffffff80
	s_nop 0
	global_load_lds_dwordx4 v[218:219], off offset:128
	s_add_i32 m0, s46, 0x1f80
	s_nop 0
	global_load_lds_dwordx4 v[244:245], off offset:128
	s_add_i32 m0, s70, 0xffffff80
	s_nop 0
	global_load_lds_dwordx4 v[246:247], off offset:128
	s_add_i32 m0, s71, 0xffffff80
	s_nop 0
	global_load_lds_dwordx4 v[248:249], off offset:128
	s_waitcnt vmcnt(8)
	s_waitcnt lgkmcnt(0)
	s_barrier
	s_waitcnt lgkmcnt(0)
	v_mfma_f32_16x16x32_bf16 v[86:89], v[138:141], v[194:197], v[86:89]
	v_mfma_f32_16x16x32_bf16 v[14:17], v[146:149], v[194:197], v[14:17]
	v_mfma_f32_16x16x32_bf16 v[70:73], v[138:141], v[202:205], v[70:73]
	v_mfma_f32_16x16x32_bf16 v[6:9], v[146:149], v[202:205], v[6:9]
	v_mfma_f32_16x16x32_bf16 v[102:105], v[138:141], v[228:231], v[102:105]
	v_mfma_f32_16x16x32_bf16 v[30:33], v[146:149], v[228:231], v[30:33]
	v_mfma_f32_16x16x32_bf16 v[98:101], v[138:141], v[236:239], v[98:101]
	v_mfma_f32_16x16x32_bf16 v[26:29], v[146:149], v[236:239], v[26:29]
	v_mfma_f32_16x16x32_bf16 v[86:89], v[142:145], v[198:201], v[86:89]
	v_mfma_f32_16x16x32_bf16 v[14:17], v[150:153], v[198:201], v[14:17]
	v_mfma_f32_16x16x32_bf16 v[70:73], v[142:145], v[214:217], v[70:73]
	v_mfma_f32_16x16x32_bf16 v[6:9], v[150:153], v[214:217], v[6:9]
	v_mfma_f32_16x16x32_bf16 v[102:105], v[142:145], v[232:235], v[102:105]
	v_mfma_f32_16x16x32_bf16 v[30:33], v[150:153], v[232:235], v[30:33]
	v_mfma_f32_16x16x32_bf16 v[98:101], v[142:145], v[240:243], v[98:101]
	v_mfma_f32_16x16x32_bf16 v[26:29], v[150:153], v[240:243], v[26:29]
	v_mfma_f32_16x16x32_bf16 v[82:85], v[154:157], v[194:197], v[82:85]
	v_mfma_f32_16x16x32_bf16 v[10:13], v[162:165], v[194:197], v[10:13]
	v_mfma_f32_16x16x32_bf16 v[66:69], v[154:157], v[202:205], v[66:69]
	v_mfma_f32_16x16x32_bf16 v[2:5], v[162:165], v[202:205], v[2:5]
	v_mfma_f32_16x16x32_bf16 v[94:97], v[154:157], v[228:231], v[94:97]
	v_mfma_f32_16x16x32_bf16 v[22:25], v[162:165], v[228:231], v[22:25]
	v_mfma_f32_16x16x32_bf16 v[90:93], v[154:157], v[236:239], v[90:93]
	v_mfma_f32_16x16x32_bf16 v[18:21], v[162:165], v[236:239], v[18:21]
	v_mfma_f32_16x16x32_bf16 v[82:85], v[158:161], v[198:201], v[82:85]
	v_mfma_f32_16x16x32_bf16 v[10:13], v[166:169], v[198:201], v[10:13]
	v_mfma_f32_16x16x32_bf16 v[66:69], v[158:161], v[214:217], v[66:69]
	v_mfma_f32_16x16x32_bf16 v[2:5], v[166:169], v[214:217], v[2:5]
	v_mfma_f32_16x16x32_bf16 v[94:97], v[158:161], v[232:235], v[94:97]
	v_mfma_f32_16x16x32_bf16 v[22:25], v[166:169], v[232:235], v[22:25]
	v_mfma_f32_16x16x32_bf16 v[90:93], v[158:161], v[240:243], v[90:93]
	v_mfma_f32_16x16x32_bf16 v[18:21], v[166:169], v[240:243], v[18:21]
	s_barrier
	s_add_u32 s35, s35, 0x100
	s_addc_u32 s51, s51, 0
	s_cmp_ge_i32 s52, s68
	s_mov_b64 s[48:49], s[14:15]
	s_mov_b32 s46, s52
	s_cbranch_scc0 .LBB0_1495
	s_movk_i32 s78, 0x7ff
	s_movk_i32 s76, 0x3000
	s_and_b64 vcc, exec, s[30:31]
	s_cbranch_vccz .LBB0_1470

; #define PG8_STAGE(bufoff, gbase, voff) do { _Pragma("unroll") for (int _i = 0; _i < 2; ++_i) \
;         __builtin_amdgcn_global_load_lds((const unsigned*)((const char*)(gbase) + (voff)[_i]), (PG8_LAS unsigned*)(lds + (bufoff) + ldsw + _i * 8192), 16, 0, 0); } while (0)
; #define PG8_LDA(dst, b, h) do { _Pragma("unroll") for (int m = 0; m < 4; ++m) _Pragma("unroll") for (int k = 0; k < 2; ++k) dst[m][k] = *(const PG8_LAS bf16x8*)(lds + PG8_SA(b, h) + aoff + m * 2048 + k * 1024); } while (0)
; #define PG8_LDB(dst, b, h) do { _Pragma("unroll") for (int n = 0; n < 2; ++n) _Pragma("unroll") for (int k = 0; k < 2; ++k) dst[n][k] = *(const PG8_LAS bf16x8*)(lds + PG8_SB(b, h) + boff + n * 2048 + k * 1024); } while (0)
; #define PG8_MMA(ai, bj, At, Bt) do { __builtin_amdgcn_s_setprio(1); _Pragma("unroll") for (int m = 0; m < 4; ++m) _Pragma("unroll") for (int n = 0; n < 2; ++n) _Pragma("unroll") for (int k = 0; k < 2; ++k) \
;         acc[ai][bj][m][n] = __builtin_amdgcn_mfma_f32_16x16x32_bf16(Bt[n][k], At[m][k], acc[ai][bj][m][n], 0, 0, 0); __builtin_amdgcn_s_setprio(0); } while (0)
; #define PG8_WAIT_V(n) asm volatile("s_waitcnt vmcnt(" #n ")" ::: "memory")
; #define PG8_BAR __builtin_amdgcn_s_barrier()
; template <class Epi, class Sched, bool ALIGN_EPI = false, bool SP2 = false>
; __device__ __forceinline__ void gemm_phase(PG8_LAS unsigned char* lds, const Gemm g, const Sched& S, const Epi& E, const int wv) {
;     ...
;         for (int t = 0; t < nt; t += 2) {
;             const bool last = (t == nt - 2);
;             const char* a1 = cA + (size_t)(t + 1) * kstep;
;             const char* a2 = last ? nA : cA + (size_t)(t + 2) * kstep; const char* b2 = last ? nB : cB + (size_t)(t + 2) * kstep;
;             const char* a3 = a2 + kstep; const char* b3 = b2 + kstep;
;             if (last && has_next) S.a_ready(nxt);
;             if constexpr (SP2) {
;             PG8_LDB(B0, 0, 0); PG8_LDB(B1, 0, 1); PG8_SCHED; PG8_LDA(At, 0, 0); PG8_STAGE(PG8_SA(1, 1), a1 + hstepA, voffA);
;             PG8_WAIT_V(8); PG8_WAIT_L(0); PG8_BAR; PG8_MMA(0, 0, At, B0); PG8_MMA(0, 1, At, B1); PG8_BAR; PG8_SCHED;
;             PG8_LDA(At, 0, 1); PG8_STAGE(PG8_SB(0, 0), b2, voffB); PG8_STAGE(PG8_SB(0, 1), b2 + hstepB, voffB); PG8_STAGE(PG8_SA(0, 0), a2, voffA);
;             PG8_WAIT_V(8); PG8_WAIT_L(0); PG8_BAR; PG8_MMA(1, 0, At, B0); PG8_MMA(1, 1, At, B1); PG8_BAR; PG8_SCHED;
.LBB0_1676:
	s_add_i32 s67, s44, 2
	s_add_u32 s34, s30, 0x100
	s_addc_u32 s35, s31, 0
	s_add_i32 s70, 0, 0x10000
	s_cmp_eq_u32 s59, s44
	s_cselect_b32 s45, s13, s35
	s_cselect_b32 s44, s12, s34
	s_cselect_b32 s69, s15, s66
	s_cselect_b32 s68, s14, s65
	s_add_i32 s71, 0, 0x14000
	v_add_u32_e32 v142, s70, v230
	v_add_u32_e32 v158, s71, v230
	ds_read_b128 v[114:117], v142
	ds_read_b128 v[126:129], v142 offset:1024
	ds_read_b128 v[138:141], v142 offset:2048
	ds_read_b128 v[142:145], v142 offset:3072
	ds_read_b128 v[146:149], v158
	ds_read_b128 v[150:153], v158 offset:1024
	ds_read_b128 v[154:157], v158 offset:2048
	ds_read_b128 v[158:161], v158 offset:3072
	v_lshl_add_u64 v[190:191], s[30:31], 0, v[200:201]
	s_add_i32 m0, s52, 0xc000
	ds_read_b128 v[162:165], v235
	ds_read_b128 v[166:169], v235 offset:1024
	ds_read_b128 v[170:173], v235 offset:2048
	ds_read_b128 v[174:177], v235 offset:3072
	ds_read_b128 v[178:181], v235 offset:4096
	ds_read_b128 v[182:185], v235 offset:5120
	ds_read_b128 v[204:207], v235 offset:6144
	ds_read_b128 v[208:211], v235 offset:7168
	global_load_lds_dwordx4 v[190:191], off
	v_lshl_add_u64 v[190:191], s[30:31], 0, v[202:203]
	s_add_i32 m0, s52, 0xe000
	s_nop 0
	global_load_lds_dwordx4 v[190:191], off
	s_waitcnt vmcnt(8)
	s_waitcnt lgkmcnt(0)
	s_barrier
	s_waitcnt lgkmcnt(0)
	v_mfma_f32_16x16x32_bf16 v[134:137], v[114:117], v[162:165], v[134:137]
	v_mfma_f32_16x16x32_bf16 v[130:133], v[138:141], v[162:165], v[130:133]
	v_mfma_f32_16x16x32_bf16 v[110:113], v[114:117], v[170:173], v[110:113]
	v_mfma_f32_16x16x32_bf16 v[106:109], v[138:141], v[170:173], v[106:109]
	v_mfma_f32_16x16x32_bf16 v[94:97], v[114:117], v[178:181], v[94:97]
	v_mfma_f32_16x16x32_bf16 v[90:93], v[138:141], v[178:181], v[90:93]
	v_mfma_f32_16x16x32_bf16 v[78:81], v[114:117], v[204:207], v[78:81]
	v_mfma_f32_16x16x32_bf16 v[74:77], v[138:141], v[204:207], v[74:77]
	v_mfma_f32_16x16x32_bf16 v[134:137], v[126:129], v[166:169], v[134:137]
	v_mfma_f32_16x16x32_bf16 v[130:133], v[142:145], v[166:169], v[130:133]
	v_mfma_f32_16x16x32_bf16 v[110:113], v[126:129], v[174:177], v[110:113]
	v_mfma_f32_16x16x32_bf16 v[106:109], v[142:145], v[174:177], v[106:109]
	v_mfma_f32_16x16x32_bf16 v[94:97], v[126:129], v[182:185], v[94:97]
	v_mfma_f32_16x16x32_bf16 v[90:93], v[142:145], v[182:185], v[90:93]
	v_mfma_f32_16x16x32_bf16 v[78:81], v[126:129], v[208:211], v[78:81]
	v_mfma_f32_16x16x32_bf16 v[74:77], v[142:145], v[208:211], v[74:77]
	v_mfma_f32_16x16x32_bf16 v[122:125], v[146:149], v[162:165], v[122:125]
	v_mfma_f32_16x16x32_bf16 v[118:121], v[154:157], v[162:165], v[118:121]
	v_mfma_f32_16x16x32_bf16 v[102:105], v[146:149], v[170:173], v[102:105]
	v_mfma_f32_16x16x32_bf16 v[98:101], v[154:157], v[170:173], v[98:101]
	v_mfma_f32_16x16x32_bf16 v[86:89], v[146:149], v[178:181], v[86:89]
	v_mfma_f32_16x16x32_bf16 v[82:85], v[154:157], v[178:181], v[82:85]
	v_mfma_f32_16x16x32_bf16 v[70:73], v[146:149], v[204:207], v[70:73]
	v_mfma_f32_16x16x32_bf16 v[66:69], v[154:157], v[204:207], v[66:69]
	v_mfma_f32_16x16x32_bf16 v[122:125], v[150:153], v[166:169], v[122:125]
	v_mfma_f32_16x16x32_bf16 v[118:121], v[158:161], v[166:169], v[118:121]
	v_mfma_f32_16x16x32_bf16 v[102:105], v[150:153], v[174:177], v[102:105]
	v_mfma_f32_16x16x32_bf16 v[98:101], v[158:161], v[174:177], v[98:101]
	v_mfma_f32_16x16x32_bf16 v[86:89], v[150:153], v[182:185], v[86:89]
	v_mfma_f32_16x16x32_bf16 v[82:85], v[158:161], v[182:185], v[82:85]
	v_mfma_f32_16x16x32_bf16 v[70:73], v[150:153], v[208:211], v[70:73]
	v_mfma_f32_16x16x32_bf16 v[66:69], v[158:161], v[208:211], v[66:69]
	s_barrier
	s_add_i32 s30, s70, s47
	v_lshl_add_u64 v[190:191], s[68:69], 0, v[0:1]
	s_mov_b32 m0, s30
	ds_read_b128 v[162:165], v235 offset:16384
	ds_read_b128 v[166:169], v235 offset:17408
	ds_read_b128 v[170:173], v235 offset:18432
	ds_read_b128 v[174:177], v235 offset:19456
	ds_read_b128 v[178:181], v235 offset:20480
	ds_read_b128 v[182:185], v235 offset:21504
	ds_read_b128 v[204:207], v235 offset:22528
	ds_read_b128 v[208:211], v235 offset:23552
	global_load_lds_dwordx4 v[190:191], off
	s_add_i32 m0, s30, 0x2000
	s_add_u32 s30, s68, s2
	v_lshl_add_u64 v[192:193], s[68:69], 0, v[198:199]
	s_addc_u32 s31, s69, s3
	s_add_i32 s68, s71, s47
	global_load_lds_dwordx4 v[192:193], off
	v_lshl_add_u64 v[212:213], s[30:31], 0, v[0:1]
	s_mov_b32 m0, s68
	v_lshl_add_u64 v[214:215], s[30:31], 0, v[198:199]
	global_load_lds_dwordx4 v[212:213], off
	s_add_i32 m0, s68, 0x2000
	v_lshl_add_u64 v[216:217], s[44:45], 0, v[194:195]
	global_load_lds_dwordx4 v[214:215], off
	s_mov_b32 m0, s52
	v_lshl_add_u64 v[218:219], s[44:45], 0, v[196:197]
	global_load_lds_dwordx4 v[216:217], off
	s_mov_b32 m0, s53
	s_nop 0
	global_load_lds_dwordx4 v[218:219], off
	s_waitcnt vmcnt(8)
	s_waitcnt lgkmcnt(0)
	s_barrier
; #define PG8_STAGE(bufoff, gbase, voff) do { _Pragma("unroll") for (int _i = 0; _i < 2; ++_i) \
;         __builtin_amdgcn_global_load_lds((const unsigned*)((const char*)(gbase) + (voff)[_i]), (PG8_LAS unsigned*)(lds + (bufoff) + ldsw + _i * 8192), 16, 0, 0); } while (0)
; #define PG8_LDA(dst, b, h) do { _Pragma("unroll") for (int m = 0; m < 4; ++m) _Pragma("unroll") for (int k = 0; k < 2; ++k) dst[m][k] = *(const PG8_LAS bf16x8*)(lds + PG8_SA(b, h) + aoff + m * 2048 + k * 1024); } while (0)
; #define PG8_LDB(dst, b, h) do { _Pragma("unroll") for (int n = 0; n < 2; ++n) _Pragma("unroll") for (int k = 0; k < 2; ++k) dst[n][k] = *(const PG8_LAS bf16x8*)(lds + PG8_SB(b, h) + boff + n * 2048 + k * 1024); } while (0)
; #define PG8_MMA(ai, bj, At, Bt) do { __builtin_amdgcn_s_setprio(1); _Pragma("unroll") for (int m = 0; m < 4; ++m) _Pragma("unroll") for (int n = 0; n < 2; ++n) _Pragma("unroll") for (int k = 0; k < 2; ++k) \
;         acc[ai][bj][m][n] = __builtin_amdgcn_mfma_f32_16x16x32_bf16(Bt[n][k], At[m][k], acc[ai][bj][m][n], 0, 0, 0); __builtin_amdgcn_s_setprio(0); } while (0)
; #define PG8_WAIT_V(n) asm volatile("s_waitcnt vmcnt(" #n ")" ::: "memory")
; #define PG8_WAIT_L(n) asm volatile("s_waitcnt lgkmcnt(" #n ")" ::: "memory")
; #define PG8_BAR __builtin_amdgcn_s_barrier()
; #define PG8_SCHED __builtin_amdgcn_sched_barrier(0)
; template <class Epi, class Sched, bool ALIGN_EPI = false, bool SP2 = false>
; __device__ __forceinline__ void gemm_phase(PG8_LAS unsigned char* lds, const Gemm g, const Sched& S, const Epi& E, const int wv) {
;     ...
;             PG8_WAIT_V(8); PG8_WAIT_L(0); PG8_BAR; PG8_MMA(1, 0, At, B0); PG8_MMA(1, 1, At, B1); PG8_BAR; PG8_SCHED;
;             PG8_LDB(B0, 1, 0); PG8_LDB(B1, 1, 1); PG8_SCHED; PG8_LDA(At, 1, 0); PG8_STAGE(PG8_SA(0, 1), a2 + hstepA, voffA);
;             PG8_WAIT_V(8); PG8_WAIT_L(0); PG8_BAR; PG8_MMA(0, 0, At, B0); PG8_MMA(0, 1, At, B1); PG8_BAR; PG8_SCHED;
	s_waitcnt lgkmcnt(0)
	v_mfma_f32_16x16x32_bf16 v[62:65], v[114:117], v[162:165], v[62:65]
	v_mfma_f32_16x16x32_bf16 v[58:61], v[138:141], v[162:165], v[58:61]
	v_mfma_f32_16x16x32_bf16 v[46:49], v[114:117], v[170:173], v[46:49]
	v_mfma_f32_16x16x32_bf16 v[42:45], v[138:141], v[170:173], v[42:45]
	v_mfma_f32_16x16x32_bf16 v[30:33], v[114:117], v[178:181], v[30:33]
	v_mfma_f32_16x16x32_bf16 v[26:29], v[138:141], v[178:181], v[26:29]
	v_mfma_f32_16x16x32_bf16 v[14:17], v[114:117], v[204:207], v[14:17]
	v_mfma_f32_16x16x32_bf16 v[10:13], v[138:141], v[204:207], v[10:13]
	v_mfma_f32_16x16x32_bf16 v[62:65], v[126:129], v[166:169], v[62:65]
	v_mfma_f32_16x16x32_bf16 v[58:61], v[142:145], v[166:169], v[58:61]
	v_mfma_f32_16x16x32_bf16 v[46:49], v[126:129], v[174:177], v[46:49]
	v_mfma_f32_16x16x32_bf16 v[42:45], v[142:145], v[174:177], v[42:45]
	v_mfma_f32_16x16x32_bf16 v[30:33], v[126:129], v[182:185], v[30:33]
	v_mfma_f32_16x16x32_bf16 v[26:29], v[142:145], v[182:185], v[26:29]
	v_mfma_f32_16x16x32_bf16 v[14:17], v[126:129], v[208:211], v[14:17]
	v_mfma_f32_16x16x32_bf16 v[10:13], v[142:145], v[208:211], v[10:13]
	v_mfma_f32_16x16x32_bf16 v[54:57], v[146:149], v[162:165], v[54:57]
	v_mfma_f32_16x16x32_bf16 v[50:53], v[154:157], v[162:165], v[50:53]
	v_mfma_f32_16x16x32_bf16 v[38:41], v[146:149], v[170:173], v[38:41]
	v_mfma_f32_16x16x32_bf16 v[34:37], v[154:157], v[170:173], v[34:37]
	v_mfma_f32_16x16x32_bf16 v[22:25], v[146:149], v[178:181], v[22:25]
	v_mfma_f32_16x16x32_bf16 v[18:21], v[154:157], v[178:181], v[18:21]
	v_mfma_f32_16x16x32_bf16 v[6:9], v[146:149], v[204:207], v[6:9]
	v_mfma_f32_16x16x32_bf16 v[2:5], v[154:157], v[204:207], v[2:5]
	v_mfma_f32_16x16x32_bf16 v[54:57], v[150:153], v[166:169], v[54:57]
	v_mfma_f32_16x16x32_bf16 v[50:53], v[158:161], v[166:169], v[50:53]
	v_mfma_f32_16x16x32_bf16 v[38:41], v[150:153], v[174:177], v[38:41]
	v_mfma_f32_16x16x32_bf16 v[34:37], v[158:161], v[174:177], v[34:37]
	v_mfma_f32_16x16x32_bf16 v[22:25], v[150:153], v[182:185], v[22:25]
	v_mfma_f32_16x16x32_bf16 v[18:21], v[158:161], v[182:185], v[18:21]
	v_mfma_f32_16x16x32_bf16 v[6:9], v[150:153], v[208:211], v[6:9]
	v_mfma_f32_16x16x32_bf16 v[2:5], v[158:161], v[208:211], v[2:5]
	s_barrier
	s_add_i32 s68, 0, 0x18000
	s_add_i32 s69, 0, 0x1c000
	v_add_u32_e32 v142, s68, v230
	v_add_u32_e32 v158, s69, v230
	ds_read_b128 v[114:117], v142
	ds_read_b128 v[126:129], v142 offset:1024
	ds_read_b128 v[138:141], v142 offset:2048
	ds_read_b128 v[142:145], v142 offset:3072
	ds_read_b128 v[146:149], v158
	ds_read_b128 v[150:153], v158 offset:1024
	ds_read_b128 v[154:157], v158 offset:2048
	ds_read_b128 v[158:161], v158 offset:3072
	s_add_u32 s30, s44, 0x180000
	s_addc_u32 s31, s45, 0
	s_mov_b32 m0, s54
	ds_read_b128 v[162:165], v235 offset:32768
	ds_read_b128 v[166:169], v235 offset:33792
	ds_read_b128 v[170:173], v235 offset:34816
	ds_read_b128 v[174:177], v235 offset:35840
	ds_read_b128 v[178:181], v235 offset:36864
	ds_read_b128 v[182:185], v235 offset:37888
	ds_read_b128 v[204:207], v235 offset:38912
	ds_read_b128 v[208:211], v235 offset:39936
	global_load_lds_dwordx4 v194, s[30:31]
	s_mov_b32 m0, s55
	s_nop 0
	global_load_lds_dwordx4 v196, s[30:31]
	s_waitcnt vmcnt(8)
	s_waitcnt lgkmcnt(0)
	s_barrier
	s_waitcnt lgkmcnt(0)
	v_mfma_f32_16x16x32_bf16 v[134:137], v[114:117], v[162:165], v[134:137]
	v_mfma_f32_16x16x32_bf16 v[130:133], v[138:141], v[162:165], v[130:133]
	v_mfma_f32_16x16x32_bf16 v[110:113], v[114:117], v[170:173], v[110:113]
	v_mfma_f32_16x16x32_bf16 v[106:109], v[138:141], v[170:173], v[106:109]
	v_mfma_f32_16x16x32_bf16 v[94:97], v[114:117], v[178:181], v[94:97]
	v_mfma_f32_16x16x32_bf16 v[90:93], v[138:141], v[178:181], v[90:93]
	v_mfma_f32_16x16x32_bf16 v[78:81], v[114:117], v[204:207], v[78:81]
	v_mfma_f32_16x16x32_bf16 v[74:77], v[138:141], v[204:207], v[74:77]
	v_mfma_f32_16x16x32_bf16 v[134:137], v[126:129], v[166:169], v[134:137]
	v_mfma_f32_16x16x32_bf16 v[130:133], v[142:145], v[166:169], v[130:133]
	v_mfma_f32_16x16x32_bf16 v[110:113], v[126:129], v[174:177], v[110:113]
	v_mfma_f32_16x16x32_bf16 v[106:109], v[142:145], v[174:177], v[106:109]
	v_mfma_f32_16x16x32_bf16 v[94:97], v[126:129], v[182:185], v[94:97]
	v_mfma_f32_16x16x32_bf16 v[90:93], v[142:145], v[182:185], v[90:93]
	v_mfma_f32_16x16x32_bf16 v[78:81], v[126:129], v[208:211], v[78:81]
	v_mfma_f32_16x16x32_bf16 v[74:77], v[142:145], v[208:211], v[74:77]
	v_mfma_f32_16x16x32_bf16 v[122:125], v[146:149], v[162:165], v[122:125]
	v_mfma_f32_16x16x32_bf16 v[118:121], v[154:157], v[162:165], v[118:121]
	v_mfma_f32_16x16x32_bf16 v[102:105], v[146:149], v[170:173], v[102:105]
	v_mfma_f32_16x16x32_bf16 v[98:101], v[154:157], v[170:173], v[98:101]
	v_mfma_f32_16x16x32_bf16 v[86:89], v[146:149], v[178:181], v[86:89]
	v_mfma_f32_16x16x32_bf16 v[82:85], v[154:157], v[178:181], v[82:85]
	v_mfma_f32_16x16x32_bf16 v[70:73], v[146:149], v[204:207], v[70:73]
	v_mfma_f32_16x16x32_bf16 v[66:69], v[154:157], v[204:207], v[66:69]
	v_mfma_f32_16x16x32_bf16 v[122:125], v[150:153], v[166:169], v[122:125]
	v_mfma_f32_16x16x32_bf16 v[118:121], v[158:161], v[166:169], v[118:121]
	v_mfma_f32_16x16x32_bf16 v[102:105], v[150:153], v[174:177], v[102:105]
	v_mfma_f32_16x16x32_bf16 v[98:101], v[158:161], v[174:177], v[98:101]
	v_mfma_f32_16x16x32_bf16 v[86:89], v[150:153], v[182:185], v[86:89]
	v_mfma_f32_16x16x32_bf16 v[82:85], v[158:161], v[182:185], v[82:85]
	v_mfma_f32_16x16x32_bf16 v[70:73], v[150:153], v[208:211], v[70:73]
	v_mfma_f32_16x16x32_bf16 v[66:69], v[158:161], v[208:211], v[66:69]
	s_barrier
; #define PG8_STAGE(bufoff, gbase, voff) do { _Pragma("unroll") for (int _i = 0; _i < 2; ++_i) \
;         __builtin_amdgcn_global_load_lds((const unsigned*)((const char*)(gbase) + (voff)[_i]), (PG8_LAS unsigned*)(lds + (bufoff) + ldsw + _i * 8192), 16, 0, 0); } while (0)
; #define PG8_LDA(dst, b, h) do { _Pragma("unroll") for (int m = 0; m < 4; ++m) _Pragma("unroll") for (int k = 0; k < 2; ++k) dst[m][k] = *(const PG8_LAS bf16x8*)(lds + PG8_SA(b, h) + aoff + m * 2048 + k * 1024); } while (0)
; #define PG8_MMA(ai, bj, At, Bt) do { __builtin_amdgcn_s_setprio(1); _Pragma("unroll") for (int m = 0; m < 4; ++m) _Pragma("unroll") for (int n = 0; n < 2; ++n) _Pragma("unroll") for (int k = 0; k < 2; ++k) \
;         acc[ai][bj][m][n] = __builtin_amdgcn_mfma_f32_16x16x32_bf16(Bt[n][k], At[m][k], acc[ai][bj][m][n], 0, 0, 0); __builtin_amdgcn_s_setprio(0); } while (0)
; #define PG8_WAIT_V(n) asm volatile("s_waitcnt vmcnt(" #n ")" ::: "memory")
; #define PG8_WAIT_L(n) asm volatile("s_waitcnt lgkmcnt(" #n ")" ::: "memory")
; #define PG8_BAR __builtin_amdgcn_s_barrier()
; #define PG8_SCHED __builtin_amdgcn_sched_barrier(0)
; template <class Epi, class Sched, bool ALIGN_EPI = false, bool SP2 = false>
; __device__ __forceinline__ void gemm_phase(PG8_LAS unsigned char* lds, const Gemm g, const Sched& S, const Epi& E, const int wv) {
;     ...
;             PG8_LDA(At, 1, 1); PG8_STAGE(PG8_SB(1, 0), b3, voffB); PG8_STAGE(PG8_SB(1, 1), b3 + hstepB, voffB); PG8_STAGE(PG8_SA(1, 0), a3, voffA);
;             PG8_WAIT_V(8); PG8_WAIT_L(0); PG8_BAR; PG8_MMA(1, 0, At, B0); PG8_MMA(1, 1, At, B1); PG8_BAR; PG8_SCHED;
	s_add_i32 s30, s68, s47
	s_add_i32 m0, s30, 0xffffff80
	ds_read_b128 v[162:165], v235 offset:49152
	ds_read_b128 v[166:169], v235 offset:50176
	ds_read_b128 v[170:173], v235 offset:51200
	ds_read_b128 v[174:177], v235 offset:52224
	ds_read_b128 v[178:181], v235 offset:53248
	ds_read_b128 v[182:185], v235 offset:54272
	ds_read_b128 v[204:207], v235 offset:55296
	ds_read_b128 v[208:211], v235 offset:56320
	global_load_lds_dwordx4 v[190:191], off offset:128
	s_add_i32 m0, s30, 0x1f80
	s_add_i32 s30, s69, s47
	global_load_lds_dwordx4 v[192:193], off offset:128
	s_add_i32 m0, s30, 0xffffff80
	s_nop 0
	global_load_lds_dwordx4 v[212:213], off offset:128
	s_add_i32 m0, s30, 0x1f80
	s_nop 0
	global_load_lds_dwordx4 v[214:215], off offset:128
	s_add_i32 m0, s57, 0xffffff80
	s_nop 0
	global_load_lds_dwordx4 v[216:217], off offset:128
	s_add_i32 m0, s58, 0xffffff80
	s_nop 0
	global_load_lds_dwordx4 v[218:219], off offset:128
	s_waitcnt vmcnt(8)
	s_waitcnt lgkmcnt(0)
	s_barrier
	s_waitcnt lgkmcnt(0)
	v_mfma_f32_16x16x32_bf16 v[62:65], v[114:117], v[162:165], v[62:65]
	v_mfma_f32_16x16x32_bf16 v[58:61], v[138:141], v[162:165], v[58:61]
	v_mfma_f32_16x16x32_bf16 v[46:49], v[114:117], v[170:173], v[46:49]
	v_mfma_f32_16x16x32_bf16 v[42:45], v[138:141], v[170:173], v[42:45]
	v_mfma_f32_16x16x32_bf16 v[30:33], v[114:117], v[178:181], v[30:33]
	v_mfma_f32_16x16x32_bf16 v[26:29], v[138:141], v[178:181], v[26:29]
	v_mfma_f32_16x16x32_bf16 v[14:17], v[114:117], v[204:207], v[14:17]
	v_mfma_f32_16x16x32_bf16 v[10:13], v[138:141], v[204:207], v[10:13]
	v_mfma_f32_16x16x32_bf16 v[62:65], v[126:129], v[166:169], v[62:65]
	v_mfma_f32_16x16x32_bf16 v[58:61], v[142:145], v[166:169], v[58:61]
	v_mfma_f32_16x16x32_bf16 v[46:49], v[126:129], v[174:177], v[46:49]
	v_mfma_f32_16x16x32_bf16 v[42:45], v[142:145], v[174:177], v[42:45]
	v_mfma_f32_16x16x32_bf16 v[30:33], v[126:129], v[182:185], v[30:33]
	v_mfma_f32_16x16x32_bf16 v[26:29], v[142:145], v[182:185], v[26:29]
	v_mfma_f32_16x16x32_bf16 v[14:17], v[126:129], v[208:211], v[14:17]
	v_mfma_f32_16x16x32_bf16 v[10:13], v[142:145], v[208:211], v[10:13]
	v_mfma_f32_16x16x32_bf16 v[54:57], v[146:149], v[162:165], v[54:57]
	v_mfma_f32_16x16x32_bf16 v[50:53], v[154:157], v[162:165], v[50:53]
	v_mfma_f32_16x16x32_bf16 v[38:41], v[146:149], v[170:173], v[38:41]
	v_mfma_f32_16x16x32_bf16 v[34:37], v[154:157], v[170:173], v[34:37]
	v_mfma_f32_16x16x32_bf16 v[22:25], v[146:149], v[178:181], v[22:25]
	v_mfma_f32_16x16x32_bf16 v[18:21], v[154:157], v[178:181], v[18:21]
	v_mfma_f32_16x16x32_bf16 v[6:9], v[146:149], v[204:207], v[6:9]
	v_mfma_f32_16x16x32_bf16 v[2:5], v[154:157], v[204:207], v[2:5]
	v_mfma_f32_16x16x32_bf16 v[54:57], v[150:153], v[166:169], v[54:57]
	v_mfma_f32_16x16x32_bf16 v[50:53], v[158:161], v[166:169], v[50:53]
	v_mfma_f32_16x16x32_bf16 v[38:41], v[150:153], v[174:177], v[38:41]
	v_mfma_f32_16x16x32_bf16 v[34:37], v[158:161], v[174:177], v[34:37]
	v_mfma_f32_16x16x32_bf16 v[22:25], v[150:153], v[182:185], v[22:25]
	v_mfma_f32_16x16x32_bf16 v[18:21], v[158:161], v[182:185], v[18:21]
	v_mfma_f32_16x16x32_bf16 v[6:9], v[150:153], v[208:211], v[6:9]
	v_mfma_f32_16x16x32_bf16 v[2:5], v[158:161], v[208:211], v[2:5]
	s_barrier
	s_add_u32 s65, s65, 0x100
	s_addc_u32 s66, s66, 0
	s_cmp_ge_i32 s67, s56
	s_mov_b64 s[30:31], s[34:35]
	s_mov_b32 s44, s67
	s_cbranch_scc0 .LBB0_1676
	s_movk_i32 s68, 0x4000
	s_movk_i32 s69, 0x6000
	s_mov_b32 s70, 0x18000
	s_mov_b32 s71, 0x3f317217
	s_and_b64 vcc, exec, s[28:29]
	s_cbranch_vccz .LBB0_1652
